# static priority raise for the cross-term (critical) waves inside the retention scan loops
# baseline (speedup 1.0000x reference)
; #define LAS __attribute__((address_space(3)))
; #define EX2(x) __builtin_amdgcn_exp2f(x)
; template <bool XW, int PASS, bool RMW> ...
;     ...
;     const float qd = pass == 0 ? EX2(lgf * (float)(icol + 1)) : EX2(lgb * (float)(128 - icol));
;     int pbuf = 0;
;     if (tids < 128) kdec[tids] = EX2(lg * (float)(PASS == 0 ? 127 - tids : tids));
;     __syncthreads();
;     bf16x8 qf[16], vr[2], kb0[8];
;     u32x2 ovn[8];
; #pragma unroll
;     for (int gq = 0; gq < 8; ++gq) { ovn[gq].x = 0u; ovn[gq].y = 0u; }
;     {
;       const int c0 = pass == 0 ? 0 : nc - 1, c1 = pass == 0 ? 1 : nc - 2;
;       if constexpr (XW) {
; #pragma unroll
;         for (int s = 0; s < 16; ++s) qf[s] = ldg16(qr, qoff0 + (unsigned)c0 * 262144u + 1024u * s);
;         if constexpr (PASS == 1 && RMW) {
; #pragma unroll
;           for (int gq = 0; gq < 8; ++gq) ovn[gq] = *(const u32x2*)((const char*)y + (yoff0 + (unsigned)c0 * 524288u + 64u * (gq >> 2) + 16u * (gq & 3)));
;         }
;       }
; #pragma unroll
;       for (int s = 0; s < 8; ++s) kb0[s] = ldg16(kT, kboff0 + (unsigned)c0 * 262144u + 1024u * s);
; #pragma unroll
;       for (int t = 0; t < 2; ++t) {
;         const int sv = 2 * dq + t;
;         const bf16x8 raw = ldg16(vT, vaoff0 + (unsigned)c0 * 524288u + 1024u * sv);
;         *(LAS bf16x8*)(vimg + et * 8192 + sv * 1024 + lane * 16) = scale_tab(raw, kdec + 16 * sv + 8 * h);
;         vr[t] = ldg16(vT, vaoff0 + (unsigned)c1 * 524288u + 1024u * sv);
;       }
;       lds_barrier();
.LBB0_96:
	s_or_b64 exec, exec, s[0:1]
	v_or_b32_e32 v0, s3, v224
	s_waitcnt lgkmcnt(0)
	s_barrier
	global_load_dwordx4 v[8:11], v0, s[16:17]
	v_readlane_b32 s0, v254, 15
	v_or_b32_e32 v0, 0x400, v226
	v_or_b32_e32 v1, 0x800, v226
	v_or_b32_e32 v2, 0xc00, v226
	v_or_b32_e32 v3, 0x1000, v226
	v_or_b32_e32 v4, 0x1400, v226
	v_or_b32_e32 v5, 0x1800, v226
	v_or_b32_e32 v6, 0x1c00, v226
	v_or_b32_e32 v7, 0x2000, v226
	v_or_b32_e32 v12, 0x2400, v226
	v_or_b32_e32 v13, 0x2800, v226
	v_or_b32_e32 v14, 0x2c00, v226
	v_or_b32_e32 v15, 0x3000, v226
	v_or_b32_e32 v16, 0x3400, v226
	v_or_b32_e32 v17, 0x3800, v226
	v_or_b32_e32 v18, 0x3c00, v226
	v_or_b32_e32 v19, 0x400, v223
	v_add_u32_e32 v228, s0, v197
	global_load_dwordx4 v[26:29], v226, s[92:93]
	global_load_dwordx4 v[84:87], v223, s[14:15]
	v_or_b32_e32 v20, 0x800, v223
	v_or_b32_e32 v21, 0xc00, v223
	v_or_b32_e32 v22, 0x1000, v223
	v_or_b32_e32 v23, 0x1400, v223
	v_or_b32_e32 v24, 0x1800, v223
	v_or_b32_e32 v25, 0x1c00, v223
	global_load_dwordx4 v[66:69], v0, s[92:93]
	global_load_dwordx4 v[70:73], v1, s[92:93]
	global_load_dwordx4 v[74:77], v2, s[92:93]
	global_load_dwordx4 v[78:81], v3, s[92:93]
	global_load_dwordx4 v[88:91], v4, s[92:93]
	global_load_dwordx4 v[92:95], v5, s[92:93]
	global_load_dwordx4 v[96:99], v6, s[92:93]
	global_load_dwordx4 v[100:103], v7, s[92:93]
	global_load_dwordx4 v[104:107], v12, s[92:93]
	global_load_dwordx4 v[108:111], v13, s[92:93]
	global_load_dwordx4 v[112:115], v14, s[92:93]
	global_load_dwordx4 v[116:119], v15, s[92:93]
	s_nop 0
	global_load_dwordx4 v[4:7], v16, s[92:93]
	global_load_dwordx4 v[0:3], v17, s[92:93]
	global_load_dwordx4 v[62:65], v18, s[92:93]
	global_load_dwordx4 v[144:147], v19, s[14:15]
	global_load_dwordx4 v[140:143], v20, s[14:15]
	global_load_dwordx4 v[136:139], v21, s[14:15]
	global_load_dwordx4 v[132:135], v22, s[14:15]
	global_load_dwordx4 v[58:61], v23, s[14:15]
	global_load_dwordx4 v[46:49], v24, s[14:15]
	global_load_dwordx4 v[42:45], v25, s[14:15]
	ds_read_b128 v[12:15], v228
	ds_read_b128 v[16:19], v228 offset:16
	v_or_b32_e32 v30, s33, v224
	v_add_u32_e32 v183, s3, v198
	v_readlane_b32 s0, v254, 16
	v_add_u32_e32 v182, s33, v198
	v_add_u32_e32 v82, 0x41400, v226
	v_add_u32_e32 v229, s0, v197
	v_add_u32_e32 v83, 0x41800, v226
	v_add_u32_e32 v148, 0x43400, v226
	v_add_u32_e32 v149, 0x43800, v226
	v_add_u32_e32 v150, 0x43c00, v226
	v_or_b32_e32 v151, 64, v227
	v_or_b32_e32 v152, 16, v227
	v_or_b32_e32 v153, 0x50, v227
	v_or_b32_e32 v154, 32, v227
	v_or_b32_e32 v155, 0x60, v227
	v_or_b32_e32 v156, 48, v227
	v_add_lshl_u32 v203, v221, s28, 12
	s_add_i32 s2, s30, s29
	v_add3_u32 v173, v220, v203, s2
	s_mov_b32 s0, 1
	s_movk_i32 s1, 0x4000
	s_mov_b32 s9, 1
	s_waitcnt vmcnt(24)
	v_lshlrev_b32_e32 v20, 16, v8
	v_and_b32_e32 v8, 0xffff0000, v8
	v_lshlrev_b32_e32 v21, 16, v9
	v_and_b32_e32 v9, 0xffff0000, v9
	v_lshlrev_b32_e32 v22, 16, v10
	v_and_b32_e32 v10, 0xffff0000, v10
	v_lshlrev_b32_e32 v23, 16, v11
	v_and_b32_e32 v11, 0xffff0000, v11
	s_waitcnt lgkmcnt(1)
	v_mul_f32_e32 v12, v12, v20
	v_mul_f32_e32 v8, v13, v8
	v_mul_f32_e32 v13, v14, v21
	v_mul_f32_e32 v9, v15, v9
	s_waitcnt lgkmcnt(0)
	v_mul_f32_e32 v14, v16, v22
	v_mul_f32_e32 v10, v17, v10
	v_mul_f32_e32 v15, v18, v23
	v_mul_f32_e32 v11, v19, v11
	v_cvt_pk_bf16_f32 v8, v12, v8
	v_cvt_pk_bf16_f32 v9, v13, v9
	v_cvt_pk_bf16_f32 v10, v14, v10
	v_cvt_pk_bf16_f32 v11, v15, v11
	global_load_dwordx4 v[12:15], v30, s[16:17]
	v_add_u32_e32 v16, 0x80000, v224
	v_or_b32_e32 v17, s3, v16
	ds_write_b128 v183, v[8:11]
	v_or_b32_e32 v20, s33, v16
	global_load_dwordx4 v[54:57], v17, s[16:17]
	ds_read_b128 v[8:11], v229
	ds_read_b128 v[16:19], v229 offset:16
	s_waitcnt vmcnt(1)
	v_lshlrev_b32_e32 v21, 16, v12
	v_and_b32_e32 v12, 0xffff0000, v12
	v_lshlrev_b32_e32 v22, 16, v13
	v_and_b32_e32 v13, 0xffff0000, v13
	v_lshlrev_b32_e32 v23, 16, v14
	v_and_b32_e32 v14, 0xffff0000, v14
	v_lshlrev_b32_e32 v24, 16, v15
	v_and_b32_e32 v15, 0xffff0000, v15
	s_waitcnt lgkmcnt(1)
	v_mul_f32_e32 v8, v8, v21
	v_mul_f32_e32 v9, v9, v12
	v_mul_f32_e32 v10, v10, v22
	v_mul_f32_e32 v11, v11, v13
	s_waitcnt lgkmcnt(0)
	v_mul_f32_e32 v12, v16, v23
	v_mul_f32_e32 v13, v17, v14
	v_mul_f32_e32 v14, v18, v24
	v_mul_f32_e32 v15, v19, v15
	v_cvt_pk_bf16_f32 v8, v8, v9
	v_cvt_pk_bf16_f32 v9, v10, v11
	v_cvt_pk_bf16_f32 v10, v12, v13
	v_cvt_pk_bf16_f32 v11, v14, v15
	ds_write_b128 v182, v[8:11]
	global_load_dwordx4 v[50:53], v20, s[16:17]
	s_waitcnt lgkmcnt(0)
	s_barrier
; #define LAS __attribute__((address_space(3)))
; #define MFMA32(a, b, c) __builtin_amdgcn_mfma_f32_32x32x16_bf16((a), (b), (c), 0, 0, 0)
; #define EX2(x) __builtin_amdgcn_exp2f(x)
; template <bool XW, int PASS, bool RMW> ...
;     ...
;     for (int i = 0; i < 16; ++i) { st0[i] = 0.f; st1[i] = 0.f; }
;     const float lg = pass == 0 ? lgf : lgb;
;     const float cd = EX2(lg * 128.0f);
;     const float qd = pass == 0 ? EX2(lgf * (float)(icol + 1)) : EX2(lgb * (float)(128 - icol));
;     ...
;     for (int cc = 0; cc < nc; ++cc) {
;       const int c = pass == 0 ? cc : nc - 1 - cc;
;       const int k1 = cc + 1 < nc ? cc + 1 : nc - 1, k2 = cc + 2 < nc ? cc + 2 : nc - 1;
;       const int cn = pass == 0 ? k1 : nc - 1 - k1, cnn = pass == 0 ? k2 : nc - 1 - k2;
;       if constexpr (XW) {
;         const unsigned yb = yoff0 + (unsigned)c * 524288u;
;         f32x16 yc0, yc1;
; #pragma unroll
;         for (int i = 0; i < 16; ++i) { yc0[i] = 0.f; yc1[i] = 0.f; }
;         const LAS bf16_t* sp = Sb + pbuf * SBE + r * 264 + 8 * h;
; #pragma unroll
;         for (int sb = 0; sb < 8; ++sb) {
;           bf16x8 a0[2], a1[2];
; #pragma unroll
;           for (int k = 0; k < 2; ++k) { a0[k] = *(const LAS bf16x8*)(sp + 16 * (2 * sb + k)); a1[k] = *(const LAS bf16x8*)(sp + 32 * 264 + 16 * (2 * sb + k)); }
; #pragma unroll
;           for (int k = 0; k < 2; ++k) { yc0 = MFMA32(a0[k], qf[2 * sb + k], yc0); yc1 = MFMA32(a1[k], qf[2 * sb + k], yc1); }
;         }
;         asm volatile("" : "+v"(yc0), "+v"(yc1) :: "memory");
	ds_read_b128 v[8:11], v217
	ds_read_b128 v[120:123], v217 offset:32
	s_waitcnt lgkmcnt(1)
	v_mfma_f32_32x32x16_bf16 v[10:25], v[8:11], v[26:29], 0
	ds_read_b128 v[30:33], v217 offset:16896
	ds_read_b128 v[124:127], v217 offset:16928
	v_add_u32_e32 v9, 0x40000, v226
	v_mul_f32_e32 v8, 0xc3000000, v169
	v_exp_f32_e32 v168, v8
	s_nop 0
	v_mov_b32_e32 v170, v168
	s_waitcnt lgkmcnt(1)
	v_mfma_f32_32x32x16_bf16 v[26:41], v[30:33], v[26:29], 0
	v_mov_b32_e32 v171, v168
	v_mfma_f32_32x32x16_bf16 v[10:25], v[120:123], v[66:69], v[10:25]
	s_waitcnt lgkmcnt(0)
	v_mfma_f32_32x32x16_bf16 v[26:41], v[124:127], v[66:69], v[26:41]
	ds_read_b128 v[66:69], v217 offset:64
	ds_read_b128 v[120:123], v217 offset:96
	s_waitcnt lgkmcnt(1)
	v_mfma_f32_32x32x16_bf16 v[10:25], v[66:69], v[70:73], v[10:25]
	ds_read_b128 v[66:69], v217 offset:16960
	ds_read_b128 v[124:127], v217 offset:16992
	s_waitcnt lgkmcnt(1)
	v_mfma_f32_32x32x16_bf16 v[26:41], v[66:69], v[70:73], v[26:41]
	ds_read_b128 v[66:69], v217 offset:128
	ds_read_b128 v[70:73], v217 offset:160
	v_mfma_f32_32x32x16_bf16 v[10:25], v[120:123], v[74:77], v[10:25]
	s_waitcnt lgkmcnt(2)
	v_mfma_f32_32x32x16_bf16 v[26:41], v[124:127], v[74:77], v[26:41]
	s_waitcnt lgkmcnt(1)
	v_mfma_f32_32x32x16_bf16 v[10:25], v[66:69], v[78:81], v[10:25]
	ds_read_b128 v[66:69], v217 offset:17024
	ds_read_b128 v[74:77], v217 offset:17056
	s_waitcnt lgkmcnt(1)
	v_mfma_f32_32x32x16_bf16 v[26:41], v[66:69], v[78:81], v[26:41]
	v_add_u32_e32 v78, 0x40400, v226
	v_add_u32_e32 v79, 0x40800, v226
	v_add_u32_e32 v80, 0x40c00, v226
	v_add_u32_e32 v81, 0x41000, v226
	v_mfma_f32_32x32x16_bf16 v[10:25], v[70:73], v[88:91], v[10:25]
	ds_read_b128 v[66:69], v217 offset:192
	ds_read_b128 v[70:73], v217 offset:224
	s_waitcnt lgkmcnt(2)
	v_mfma_f32_32x32x16_bf16 v[26:41], v[74:77], v[88:91], v[26:41]
	v_add_u32_e32 v88, 0x41c00, v226
	v_add_u32_e32 v89, 0x42000, v226
	v_add_u32_e32 v90, 0x42400, v226
	s_waitcnt lgkmcnt(1)
	v_mfma_f32_32x32x16_bf16 v[10:25], v[66:69], v[92:95], v[10:25]
	ds_read_b128 v[66:69], v217 offset:17088
	ds_read_b128 v[74:77], v217 offset:17120
	s_waitcnt lgkmcnt(1)
	v_mfma_f32_32x32x16_bf16 v[26:41], v[66:69], v[92:95], v[26:41]
	v_mfma_f32_32x32x16_bf16 v[10:25], v[70:73], v[96:99], v[10:25]
	ds_read_b128 v[66:69], v217 offset:256
	ds_read_b128 v[70:73], v217 offset:288
	s_waitcnt lgkmcnt(2)
	v_mfma_f32_32x32x16_bf16 v[26:41], v[74:77], v[96:99], v[26:41]
	s_waitcnt lgkmcnt(1)
	v_mfma_f32_32x32x16_bf16 v[10:25], v[66:69], v[100:103], v[10:25]
	ds_read_b128 v[66:69], v217 offset:17152
	ds_read_b128 v[74:77], v217 offset:17184
	s_waitcnt lgkmcnt(1)
	v_mfma_f32_32x32x16_bf16 v[26:41], v[66:69], v[100:103], v[26:41]
	v_mfma_f32_32x32x16_bf16 v[10:25], v[70:73], v[104:107], v[10:25]
	ds_read_b128 v[66:69], v217 offset:320
	ds_read_b128 v[70:73], v217 offset:352
	s_waitcnt lgkmcnt(2)
	v_mfma_f32_32x32x16_bf16 v[26:41], v[74:77], v[104:107], v[26:41]
	s_waitcnt lgkmcnt(1)
	v_mfma_f32_32x32x16_bf16 v[10:25], v[66:69], v[108:111], v[10:25]
	ds_read_b128 v[66:69], v217 offset:17216
	ds_read_b128 v[74:77], v217 offset:17248
	s_waitcnt lgkmcnt(1)
	v_mfma_f32_32x32x16_bf16 v[26:41], v[66:69], v[108:111], v[26:41]
	v_mfma_f32_32x32x16_bf16 v[10:25], v[70:73], v[112:115], v[10:25]
	ds_read_b128 v[66:69], v217 offset:384
	ds_read_b128 v[70:73], v217 offset:416
	s_waitcnt lgkmcnt(2)
	v_mfma_f32_32x32x16_bf16 v[26:41], v[74:77], v[112:115], v[26:41]
	s_waitcnt lgkmcnt(1)
	v_mfma_f32_32x32x16_bf16 v[10:25], v[66:69], v[116:119], v[10:25]
	ds_read_b128 v[66:69], v217 offset:17280
	ds_read_b128 v[74:77], v217 offset:17312
	s_waitcnt lgkmcnt(1)
	v_mfma_f32_32x32x16_bf16 v[26:41], v[66:69], v[116:119], v[26:41]
	ds_read_b128 v[66:69], v217 offset:448
	v_mfma_f32_32x32x16_bf16 v[10:25], v[70:73], v[4:7], v[10:25]
	s_waitcnt lgkmcnt(1)
	v_mfma_f32_32x32x16_bf16 v[26:41], v[74:77], v[4:7], v[26:41]
	ds_read_b128 v[4:7], v217 offset:17344
	ds_read_b128 v[70:73], v217 offset:480
	v_add_u32_e32 v74, 0x42800, v226
	v_add_u32_e32 v75, 0x42c00, v226
	v_add_u32_e32 v76, 0x43000, v226
	s_waitcnt lgkmcnt(2)
	v_mfma_f32_32x32x16_bf16 v[10:25], v[66:69], v[0:3], v[10:25]
	ds_read_b128 v[66:69], v217 offset:17376
	s_waitcnt lgkmcnt(2)
	v_mfma_f32_32x32x16_bf16 v[26:41], v[4:7], v[0:3], v[26:41]
	v_add_u32_e32 v0, 0, v190
	v_add_u32_e32 v231, 0x11400, v0
	v_add_u32_e32 v230, 0x13400, v0
	v_mul_f32_e32 v0, 0, v168
	v_mov_b32_e32 v1, v0
	v_mov_b32_e32 v2, v0
	v_mov_b32_e32 v3, v0
	s_waitcnt lgkmcnt(1)
	v_mfma_f32_32x32x16_bf16 v[10:25], v[70:73], v[62:65], v[10:25]
	v_mov_b32_e32 v4, v0
	v_mov_b32_e32 v5, v0
	v_mov_b32_e32 v6, v0
	v_mov_b32_e32 v7, v0
	v_mov_b32_e32 v8, v0
	s_waitcnt lgkmcnt(0)
; template <bool XW, int PASS, bool RMW> ...
;     ...
;     for (int cc = 0; cc < nc; ++cc) {
;       const int c = pass == 0 ? cc : nc - 1 - cc;
;       const int k1 = cc + 1 < nc ? cc + 1 : nc - 1, k2 = cc + 2 < nc ? cc + 2 : nc - 1;
;       const int cn = pass == 0 ? k1 : nc - 1 - k1, cnn = pass == 0 ? k2 : nc - 1 - k2;
;       if constexpr (XW) {
;         const unsigned yb = yoff0 + (unsigned)c * 524288u;
;         f32x16 yc0, yc1;
; #pragma unroll
;         for (int i = 0; i < 16; ++i) { yc0[i] = 0.f; yc1[i] = 0.f; }
;         const LAS bf16_t* sp = Sb + pbuf * SBE + r * 264 + 8 * h;
; #pragma unroll
;         for (int sb = 0; sb < 8; ++sb) {
;           bf16x8 a0[2], a1[2];
; #pragma unroll
;           for (int k = 0; k < 2; ++k) { a0[k] = *(const LAS bf16x8*)(sp + 16 * (2 * sb + k)); a1[k] = *(const LAS bf16x8*)(sp + 32 * 264 + 16 * (2 * sb + k)); }
; #pragma unroll
;           for (int k = 0; k < 2; ++k) { yc0 = MFMA32(a0[k], qf[2 * sb + k], yc0); yc1 = MFMA32(a1[k], qf[2 * sb + k], yc1); }
;         }
;         asm volatile("" : "+v"(yc0), "+v"(yc1) :: "memory");
; #pragma unroll
;         for (int s = 0; s < 16; ++s) qf[s] = ldg16(qr, qoff0 + (unsigned)cn * 262144u + 1024u * s);
;         const float qe = cc > 0 ? qd : 0.f;
; #pragma unroll
;         for (int gq = 0; gq < 4; ++gq) {
;           u32x2 a; a.x = cvt_pk_bf16(bf_lo(ovn[gq].x) + qe * yc0[4 * gq], bf_hi(ovn[gq].x) + qe * yc0[4 * gq + 1]); a.y = cvt_pk_bf16(bf_lo(ovn[gq].y) + qe * yc0[4 * gq + 2], bf_hi(ovn[gq].y) + qe * yc0[4 * gq + 3]);
;           *(u32x2*)((char*)y + (yb + 16u * gq)) = a;
;           u32x2 c2; c2.x = cvt_pk_bf16(bf_lo(ovn[4 + gq].x) + qe * yc1[4 * gq], bf_hi(ovn[4 + gq].x) + qe * yc1[4 * gq + 1]); c2.y = cvt_pk_bf16(bf_lo(ovn[4 + gq].y) + qe * yc1[4 * gq + 2], bf_hi(ovn[4 + gq].y) + qe * yc1[4 * gq + 3]);
;           *(u32x2*)((char*)y + (yb + 64u + 16u * gq)) = c2;
;         }
;         if constexpr (PASS == 1 && RMW) {
;           const unsigned ybn = yoff0 + (unsigned)cn * 524288u;
; #pragma unroll
;           for (int gq = 0; gq < 8; ++gq) ovn[gq] = *(const u32x2*)((const char*)y + (ybn + 64u * (gq >> 2) + 16u * (gq & 3)));
;         }
;       }
; #pragma unroll
;       for (int i = 0; i < 16; ++i) { st0[i] *= cd; st1[i] *= cd; }
; #pragma unroll
;       for (int sb = 0; sb < 2; ++sb) {
;         bf16x8 a0[4], a1[4];
; #pragma unroll
	v_mfma_f32_32x32x16_bf16 v[26:41], v[66:69], v[62:65], v[26:41]
	global_load_dwordx4 v[128:131], v9, s[92:93]
	global_load_dwordx4 v[124:127], v78, s[92:93]
	global_load_dwordx4 v[120:123], v79, s[92:93]
	global_load_dwordx4 v[116:119], v80, s[92:93]
	global_load_dwordx4 v[112:115], v81, s[92:93]
	global_load_dwordx4 v[108:111], v82, s[92:93]
	global_load_dwordx4 v[104:107], v83, s[92:93]
	global_load_dwordx4 v[100:103], v88, s[92:93]
	global_load_dwordx4 v[96:99], v89, s[92:93]
	global_load_dwordx4 v[92:95], v90, s[92:93]
	s_nop 0
	global_load_dwordx4 v[88:91], v74, s[92:93]
	global_load_dwordx4 v[80:83], v75, s[92:93]
	s_nop 0
	global_load_dwordx4 v[76:79], v76, s[92:93]
	s_nop 0
	global_load_dwordx4 v[72:75], v148, s[92:93]
	global_load_dwordx4 v[68:71], v149, s[92:93]
	global_load_dwordx4 v[64:67], v150, s[92:93]
	v_fma_f32 v9, v10, 0, 0
	v_fma_f32 v10, v11, 0, 0
	v_fma_f32 v11, v12, 0, 0
	v_fma_f32 v12, v13, 0, 0
	v_cvt_pk_bf16_f32 v10, v9, v10
	v_cvt_pk_bf16_f32 v11, v11, v12
	v_fma_f32 v13, v26, 0, 0
	v_fma_f32 v26, v27, 0, 0
	v_fma_f32 v27, v28, 0, 0
	v_fma_f32 v28, v29, 0, 0
	global_store_dwordx2 v227, v[10:11], s[18:19]
	v_cvt_pk_bf16_f32 v10, v13, v26
	v_cvt_pk_bf16_f32 v11, v27, v28
	v_fma_f32 v14, v14, 0, 0
	v_fma_f32 v15, v15, 0, 0
	v_fma_f32 v16, v16, 0, 0
	v_fma_f32 v17, v17, 0, 0
	global_store_dwordx2 v151, v[10:11], s[18:19]
	v_cvt_pk_bf16_f32 v10, v14, v15
	v_cvt_pk_bf16_f32 v11, v16, v17
	v_fma_f32 v29, v30, 0, 0
	v_fma_f32 v30, v31, 0, 0
	v_fma_f32 v31, v32, 0, 0
	v_fma_f32 v32, v33, 0, 0
	global_store_dwordx2 v152, v[10:11], s[18:19]
	v_cvt_pk_bf16_f32 v10, v29, v30
	v_cvt_pk_bf16_f32 v11, v31, v32
	v_fma_f32 v18, v18, 0, 0
	v_fma_f32 v19, v19, 0, 0
	v_fma_f32 v20, v20, 0, 0
	v_fma_f32 v21, v21, 0, 0
	global_store_dwordx2 v153, v[10:11], s[18:19]
	v_cvt_pk_bf16_f32 v10, v18, v19
	v_cvt_pk_bf16_f32 v11, v20, v21
	v_fma_f32 v33, v34, 0, 0
	v_fma_f32 v34, v35, 0, 0
	v_fma_f32 v35, v36, 0, 0
	v_fma_f32 v36, v37, 0, 0
	v_fma_f32 v41, v41, 0, 0
	global_store_dwordx2 v154, v[10:11], s[18:19]
	v_cvt_pk_bf16_f32 v10, v33, v34
	v_cvt_pk_bf16_f32 v11, v35, v36
	v_fma_f32 v22, v22, 0, 0
	v_fma_f32 v23, v23, 0, 0
	v_fma_f32 v24, v24, 0, 0
	v_fma_f32 v25, v25, 0, 0
	v_fma_f32 v37, v38, 0, 0
	v_fma_f32 v38, v39, 0, 0
	v_fma_f32 v39, v40, 0, 0
	global_store_dwordx2 v155, v[10:11], s[18:19]
	v_cvt_pk_bf16_f32 v10, v22, v23
	v_cvt_pk_bf16_f32 v11, v24, v25
	global_store_dwordx2 v156, v[10:11], s[18:19]
	v_cvt_pk_bf16_f32 v40, v37, v38
	v_cvt_pk_bf16_f32 v41, v39, v41
	ds_read_b128 v[32:35], v231
	ds_read_b128 v[36:39], v231 offset:1024
	v_mov_b32_e32 v9, v0
	v_mov_b32_e32 v10, v0
	v_mov_b32_e32 v11, v0
	v_mov_b32_e32 v12, v0
	v_mov_b32_e32 v13, v0
	v_mov_b32_e32 v14, v0
	v_mov_b32_e32 v15, v0
	v_add_u32_e32 v62, 0x40800, v223
	v_add_u32_e32 v63, 0x40c00, v223
	s_waitcnt lgkmcnt(1)
	v_mfma_f32_32x32x16_bf16 v[16:31], v[32:35], v[84:87], v[0:15]
	ds_read_b128 v[32:35], v230
	ds_read_b128 v[148:151], v230 offset:1024
	s_waitcnt lgkmcnt(1)
	v_mfma_f32_32x32x16_bf16 v[0:15], v[32:35], v[84:87], v[0:15]
	v_mfma_f32_32x32x16_bf16 v[16:31], v[36:39], v[144:147], v[16:31]
	ds_read_b128 v[32:35], v231 offset:2048
	ds_read_b128 v[36:39], v231 offset:3072
	s_waitcnt lgkmcnt(2)
	v_mfma_f32_32x32x16_bf16 v[0:15], v[148:151], v[144:147], v[0:15]
	s_waitcnt vmcnt(24)
	v_lshlrev_b32_e32 v150, 16, v54
	v_and_b32_e32 v54, 0xffff0000, v54
	v_lshlrev_b32_e32 v151, 16, v55
	v_and_b32_e32 v55, 0xffff0000, v55
	s_waitcnt lgkmcnt(1)
	v_mfma_f32_32x32x16_bf16 v[16:31], v[32:35], v[140:143], v[16:31]
	ds_read_b128 v[32:35], v230 offset:2048
	ds_read_b128 v[84:87], v230 offset:3072
	s_waitcnt lgkmcnt(1)
	v_mfma_f32_32x32x16_bf16 v[0:15], v[32:35], v[140:143], v[0:15]
	v_or_b32_e32 v32, 0x70, v227
	global_store_dwordx2 v32, v[40:41], s[18:19]
	v_add_u32_e32 v40, 0x40000, v223
	v_add_u32_e32 v41, 0x40400, v223
	v_mfma_f32_32x32x16_bf16 v[16:31], v[36:39], v[136:139], v[16:31]
	s_waitcnt lgkmcnt(0)
	v_mfma_f32_32x32x16_bf16 v[0:15], v[84:87], v[136:139], v[0:15]
	ds_read_b128 v[32:35], v231 offset:4096
	ds_read_b128 v[36:39], v231 offset:5120
	s_waitcnt lgkmcnt(1)
	v_mfma_f32_32x32x16_bf16 v[16:31], v[32:35], v[132:135], v[16:31]
	ds_read_b128 v[32:35], v230 offset:4096
	ds_read_b128 v[84:87], v230 offset:5120
	s_waitcnt lgkmcnt(1)
	v_mfma_f32_32x32x16_bf16 v[0:15], v[32:35], v[132:135], v[0:15]
	ds_read_b128 v[32:35], v231 offset:6144
	v_add_u32_e32 v132, 0x100000, v224
	v_or_b32_e32 v148, s3, v132
	v_or_b32_e32 v149, s33, v132
	v_mfma_f32_32x32x16_bf16 v[16:31], v[36:39], v[58:61], v[16:31]
	s_waitcnt lgkmcnt(1)
	v_mfma_f32_32x32x16_bf16 v[0:15], v[84:87], v[58:61], v[0:15]
	ds_read_b128 v[36:39], v230 offset:6144
	ds_read_b128 v[58:61], v231 offset:7168
	v_add_u32_e32 v84, 0x41000, v223
	v_add_u32_e32 v85, 0x41400, v223
	v_add_u32_e32 v86, 0x41800, v223
	v_add_u32_e32 v87, 0x41c00, v223
	s_waitcnt lgkmcnt(2)
	v_mfma_f32_32x32x16_bf16 v[16:31], v[32:35], v[46:49], v[16:31]
	ds_read_b128 v[32:35], v230 offset:7168
	global_load_dwordx4 v[164:167], v40, s[14:15]
	global_load_dwordx4 v[160:163], v41, s[14:15]
	global_load_dwordx4 v[156:159], v62, s[14:15]
	global_load_dwordx4 v[140:143], v63, s[14:15]
	s_waitcnt vmcnt(28)
	v_lshlrev_b32_e32 v40, 16, v53
	v_and_b32_e32 v41, 0xffff0000, v53
	s_waitcnt lgkmcnt(2)
	v_mfma_f32_32x32x16_bf16 v[0:15], v[36:39], v[46:49], v[0:15]
	v_lshlrev_b32_e32 v46, 16, v56
	v_and_b32_e32 v47, 0xffff0000, v56
	v_lshlrev_b32_e32 v48, 16, v57
	v_and_b32_e32 v49, 0xffff0000, v57
	v_lshlrev_b32_e32 v56, 16, v50
	v_and_b32_e32 v50, 0xffff0000, v50
	v_lshlrev_b32_e32 v57, 16, v51
	s_waitcnt lgkmcnt(1)
; template <bool XW, int PASS, bool RMW> ...
;     ...
;         const LAS bf16_t* sp = Sb + pbuf * SBE + r * 264 + 8 * h;
; #pragma unroll
;         for (int sb = 0; sb < 8; ++sb) {
;           bf16x8 a0[2], a1[2];
; #pragma unroll
;           for (int k = 0; k < 2; ++k) { a0[k] = *(const LAS bf16x8*)(sp + 16 * (2 * sb + k)); a1[k] = *(const LAS bf16x8*)(sp + 32 * 264 + 16 * (2 * sb + k)); }
; #pragma unroll
;           for (int k = 0; k < 2; ++k) { yc0 = MFMA32(a0[k], qf[2 * sb + k], yc0); yc1 = MFMA32(a1[k], qf[2 * sb + k], yc1); }
;         }
;         asm volatile("" : "+v"(yc0), "+v"(yc1) :: "memory");
; #pragma unroll
;         for (int s = 0; s < 16; ++s) qf[s] = ldg16(qr, qoff0 + (unsigned)cn * 262144u + 1024u * s);
;         const float qe = cc > 0 ? qd : 0.f;
; #pragma unroll
;         for (int gq = 0; gq < 4; ++gq) {
;           u32x2 a; a.x = cvt_pk_bf16(bf_lo(ovn[gq].x) + qe * yc0[4 * gq], bf_hi(ovn[gq].x) + qe * yc0[4 * gq + 1]); a.y = cvt_pk_bf16(bf_lo(ovn[gq].y) + qe * yc0[4 * gq + 2], bf_hi(ovn[gq].y) + qe * yc0[4 * gq + 3]);
;           *(u32x2*)((char*)y + (yb + 16u * gq)) = a;
;     ...
;         for (int k = 0; k < 4; ++k) { a0[k] = *(const LAS bf16x8*)(vimg + (cc & 1) * 16384 + (4 * sb + k) * 1024 + lane * 16); a1[k] = *(const LAS bf16x8*)(vimg + (cc & 1) * 16384 + 8192 + (4 * sb + k) * 1024 + lane * 16); }
; #pragma unroll
;         for (int k = 0; k < 4; ++k) { st0 = MFMA32(a0[k], kb0[4 * sb + k], st0); st1 = MFMA32(a1[k], kb0[4 * sb + k], st1); }
;         asm volatile("" : "+v"(st0), "+v"(st1) :: "memory");
; #pragma unroll
;         for (int k = 0; k < 4; ++k) kb0[4 * sb + k] = ldg16(kT, kboff0 + (unsigned)cn * 262144u + 1024u * (4 * sb + k));
;       }
; #pragma unroll
;       for (int t = 0; t < 2; ++t) {
;         const int sv = 2 * dq + t;
;         *(LAS bf16x8*)(vimg + ((cc + 1) & 1) * 16384 + et * 8192 + sv * 1024 + lane * 16) = scale_tab(vr[t], kdec + 16 * sv + 8 * h);
;         vr[t] = ldg16(vT, vaoff0 + (unsigned)cnn * 524288u + 1024u * sv);
;       }
;       LAS bf16_t* sw = Sb + (pbuf ^ 1) * SBE + (4 * h) * 264 + 32 * w + r;
; #pragma unroll
;       for (int i = 0; i < 16; ++i) {
;         const int eo = ((i & 3) + 8 * (i >> 2)) * 264;
;         const unsigned pkw = cvt_pk_bf16(st0[i], st1[i]);
;         sw[eo] = (bf16_t)(pkw & 0xffffu);
;         sw[eo + 32 * 264] = (bf16_t)(pkw >> 16);
;       }
;       lds_barrier();
	v_mfma_f32_32x32x16_bf16 v[16:31], v[58:61], v[42:45], v[16:31]
	v_and_b32_e32 v51, 0xffff0000, v51
	v_lshlrev_b32_e32 v58, 16, v52
	v_and_b32_e32 v52, 0xffff0000, v52
	s_waitcnt lgkmcnt(0)
	v_mfma_f32_32x32x16_bf16 v[0:15], v[32:35], v[42:45], v[0:15]
	ds_read_b128 v[32:35], v228
	global_load_dwordx4 v[144:147], v84, s[14:15]
	global_load_dwordx4 v[136:139], v85, s[14:15]
	global_load_dwordx4 v[132:135], v86, s[14:15]
	s_nop 0
	global_load_dwordx4 v[84:87], v87, s[14:15]
	ds_read_b128 v[36:39], v228 offset:16
	s_waitcnt lgkmcnt(1)
	v_mul_f32_e32 v32, v32, v150
	v_mul_f32_e32 v33, v33, v54
	v_mul_f32_e32 v34, v34, v151
	v_mul_f32_e32 v35, v35, v55
	s_waitcnt lgkmcnt(0)
	v_mul_f32_e32 v36, v36, v46
	v_mul_f32_e32 v37, v37, v47
	v_mul_f32_e32 v38, v38, v48
	v_mul_f32_e32 v39, v39, v49
	v_cvt_pk_bf16_f32 v32, v32, v33
	v_cvt_pk_bf16_f32 v33, v34, v35
	v_cvt_pk_bf16_f32 v34, v36, v37
	v_cvt_pk_bf16_f32 v35, v38, v39
	ds_write_b128 v183, v[32:35] offset:16384
	ds_read_b128 v[32:35], v229
	ds_read_b128 v[36:39], v229 offset:16
	global_load_dwordx4 v[152:155], v148, s[16:17]
	s_waitcnt lgkmcnt(1)
	v_mul_f32_e32 v32, v32, v56
	v_mul_f32_e32 v33, v33, v50
	v_mul_f32_e32 v34, v34, v57
	v_mul_f32_e32 v35, v35, v51
	s_waitcnt lgkmcnt(0)
	v_mul_f32_e32 v36, v36, v58
	v_mul_f32_e32 v37, v37, v52
	v_mul_f32_e32 v38, v38, v40
	v_mul_f32_e32 v39, v39, v41
	v_cvt_pk_bf16_f32 v32, v32, v33
	v_cvt_pk_bf16_f32 v33, v34, v35
	v_cvt_pk_bf16_f32 v34, v36, v37
	v_cvt_pk_bf16_f32 v35, v38, v39
	global_load_dwordx4 v[148:151], v149, s[16:17]
	ds_write_b128 v182, v[32:35] offset:16384
	v_cvt_pk_bf16_f32 v32, v16, v0
	ds_write_b16 v199, v32 offset:33792
	ds_write_b16_d16_hi v199, v32 offset:50688
	v_cvt_pk_bf16_f32 v32, v17, v1
	ds_write_b16 v199, v32 offset:34320
	ds_write_b16_d16_hi v199, v32 offset:51216
	v_cvt_pk_bf16_f32 v32, v18, v2
	ds_write_b16 v199, v32 offset:34848
	ds_write_b16_d16_hi v199, v32 offset:51744
	v_cvt_pk_bf16_f32 v32, v19, v3
	ds_write_b16 v199, v32 offset:35376
	ds_write_b16_d16_hi v199, v32 offset:52272
	v_cvt_pk_bf16_f32 v32, v20, v4
	ds_write_b16 v199, v32 offset:38016
	ds_write_b16_d16_hi v199, v32 offset:54912
	v_cvt_pk_bf16_f32 v32, v21, v5
	ds_write_b16 v199, v32 offset:38544
	ds_write_b16_d16_hi v199, v32 offset:55440
	v_cvt_pk_bf16_f32 v32, v22, v6
	ds_write_b16 v199, v32 offset:39072
	ds_write_b16_d16_hi v199, v32 offset:55968
	v_cvt_pk_bf16_f32 v32, v23, v7
	ds_write_b16 v199, v32 offset:39600
	ds_write_b16_d16_hi v199, v32 offset:56496
	v_cvt_pk_bf16_f32 v32, v24, v8
	ds_write_b16 v199, v32 offset:42240
	ds_write_b16_d16_hi v199, v32 offset:59136
	v_cvt_pk_bf16_f32 v32, v25, v9
	ds_write_b16 v199, v32 offset:42768
	ds_write_b16_d16_hi v199, v32 offset:59664
	v_cvt_pk_bf16_f32 v32, v26, v10
	ds_write_b16 v199, v32 offset:43296
	ds_write_b16_d16_hi v199, v32 offset:60192
	v_cvt_pk_bf16_f32 v32, v27, v11
	ds_write_b16 v199, v32 offset:43824
	ds_write_b16_d16_hi v199, v32 offset:60720
	v_cvt_pk_bf16_f32 v32, v28, v12
	ds_write_b16 v199, v32 offset:46464
	ds_write_b16_d16_hi v199, v32 offset:63360
	v_cvt_pk_bf16_f32 v32, v29, v13
	ds_write_b16 v199, v32 offset:46992
	ds_write_b16_d16_hi v199, v32 offset:63888
	v_cvt_pk_bf16_f32 v32, v30, v14
	v_mul_f32_e64 v36, v201, -v169
	ds_write_b16 v199, v32 offset:47520
	ds_write_b16_d16_hi v199, v32 offset:64416
	v_cvt_pk_bf16_f32 v32, v31, v15
	v_exp_f32_e32 v172, v36
	ds_write_b16 v199, v32 offset:48048
	ds_write_b16_d16_hi v199, v32 offset:64944
	s_waitcnt lgkmcnt(0)
	s_barrier
	s_setprio 1
.LBB0_97:
	s_mul_i32 s8, s0, 0x8400
	v_add_u32_e32 v174, s8, v217
	ds_read_b128 v[232:235], v174
	ds_read_b128 v[236:239], v174 offset:16896
	ds_read_b128 v[240:243], v174 offset:32
	ds_read_b128 v[244:247], v174 offset:16928
	ds_read_b128 v[248:251], v174 offset:64
	s_add_i32 s8, s9, 1
	v_mov_b32_e32 v169, v168
	s_and_b32 s34, s1, 0x4000
	s_waitcnt vmcnt(29)
	s_waitcnt lgkmcnt(4)
	v_mfma_f32_32x32x16_bf16 v[48:63], v[232:235], v[128:131], 0
	ds_read_b128 v[232:235], v174 offset:16960
	s_min_u32 s35, s8, s5
	v_mul_f32_e64 v30, v168, v30
	v_mul_f32_e64 v31, v169, v31
	v_pk_mul_f32 v[28:29], v[168:169], v[28:29]
	v_pk_mul_f32 v[26:27], v[168:169], v[26:27]
	v_pk_mul_f32 v[24:25], v[168:169], v[24:25]
	v_pk_mul_f32 v[22:23], v[168:169], v[22:23]
	s_waitcnt lgkmcnt(4)
	v_mfma_f32_32x32x16_bf16 v[32:47], v[236:239], v[128:131], 0
	ds_read_b128 v[236:239], v174 offset:96
	ds_read_b128 v[128:131], v174 offset:16992
	v_mul_f32_e64 v20, v168, v20
	v_mul_f32_e64 v21, v169, v21
	v_mul_f32_e64 v18, v168, v18
	v_mul_f32_e64 v19, v169, v19
	v_mul_f32_e64 v14, v168, v14
	v_mul_f32_e64 v15, v169, v15
	v_pk_mul_f32 v[12:13], v[168:169], v[12:13]
	v_pk_mul_f32 v[10:11], v[168:169], v[10:11]
	v_pk_mul_f32 v[8:9], v[168:169], v[8:9]
	v_pk_mul_f32 v[6:7], v[168:169], v[6:7]
	s_waitcnt vmcnt(28)
	s_waitcnt lgkmcnt(5)
	v_mfma_f32_32x32x16_bf16 v[48:63], v[240:243], v[124:127], v[48:63]
	ds_read_b128 v[240:243], v174 offset:128
	v_mul_f32_e64 v4, v168, v4
	v_mul_f32_e64 v5, v169, v5
	v_mul_f32_e64 v2, v168, v2
	v_mul_f32_e64 v3, v169, v3
	v_add_u32_e32 v169, s34, v218
	s_lshl_b32 s34, s35, 18
	v_add_u32_e32 v175, 0xffffff90, v173
	v_pk_mul_f32 v[16:17], v[170:171], v[16:17]
	v_pk_mul_f32 v[0:1], v[170:171], v[0:1]
	s_waitcnt lgkmcnt(5)
	v_mfma_f32_32x32x16_bf16 v[32:47], v[244:247], v[124:127], v[32:47]
	ds_read_b128 v[244:247], v174 offset:17024
	ds_read_b128 v[124:127], v174 offset:160
	v_add_u32_e32 v184, -16, v173
	v_subrev_u32_e32 v185, 64, v173
	s_addk_i32 s1, 0x4000
	s_add_i32 s9, s9, 2
	s_and_b32 s35, s1, 0x4000
	s_min_u32 s9, s9, s5
	s_waitcnt vmcnt(27)
	s_waitcnt lgkmcnt(6)
; #define LAS __attribute__((address_space(3)))
; #define MFMA32(a, b, c) __builtin_amdgcn_mfma_f32_32x32x16_bf16((a), (b), (c), 0, 0, 0)
; template <bool XW, int PASS, bool RMW> ...
;     ...
;         const LAS bf16_t* sp = Sb + pbuf * SBE + r * 264 + 8 * h;
; #pragma unroll
;         for (int sb = 0; sb < 8; ++sb) {
;           bf16x8 a0[2], a1[2];
; #pragma unroll
;           for (int k = 0; k < 2; ++k) { a0[k] = *(const LAS bf16x8*)(sp + 16 * (2 * sb + k)); a1[k] = *(const LAS bf16x8*)(sp + 32 * 264 + 16 * (2 * sb + k)); }
; #pragma unroll
;           for (int k = 0; k < 2; ++k) { yc0 = MFMA32(a0[k], qf[2 * sb + k], yc0); yc1 = MFMA32(a1[k], qf[2 * sb + k], yc1); }
;         }
;         asm volatile("" : "+v"(yc0), "+v"(yc1) :: "memory");
; #pragma unroll
;         for (int s = 0; s < 16; ++s) qf[s] = ldg16(qr, qoff0 + (unsigned)cn * 262144u + 1024u * s);
	v_mfma_f32_32x32x16_bf16 v[48:63], v[248:251], v[120:123], v[48:63]
	ds_read_b128 v[248:251], v174 offset:17056
	s_xor_b32 s0, s0, 1
	s_cmp_lg_u32 s4, s8
	s_waitcnt lgkmcnt(6)
	v_mfma_f32_32x32x16_bf16 v[32:47], v[232:235], v[120:123], v[32:47]
	ds_read_b128 v[232:235], v174 offset:192
	ds_read_b128 v[120:123], v174 offset:17088
	s_waitcnt vmcnt(26)
	s_waitcnt lgkmcnt(7)
	v_mfma_f32_32x32x16_bf16 v[48:63], v[236:239], v[116:119], v[48:63]
	ds_read_b128 v[236:239], v174 offset:224
	s_waitcnt lgkmcnt(7)
	v_mfma_f32_32x32x16_bf16 v[32:47], v[128:131], v[116:119], v[32:47]
	ds_read_b128 v[128:131], v174 offset:17120
	v_subrev_u32_e32 v178, 48, v173
	v_add_u32_e32 v179, 0xffffffa0, v173
	v_subrev_u32_e32 v180, 32, v173
	v_add_u32_e32 v181, 0xffffffb0, v173
	s_waitcnt vmcnt(25)
	s_waitcnt lgkmcnt(7)
	v_mfma_f32_32x32x16_bf16 v[48:63], v[240:243], v[112:115], v[48:63]
	ds_read_b128 v[240:243], v174 offset:256
	s_waitcnt lgkmcnt(7)
	v_mfma_f32_32x32x16_bf16 v[32:47], v[244:247], v[112:115], v[32:47]
	ds_read_b128 v[244:247], v174 offset:17152
	s_waitcnt vmcnt(24)
	s_waitcnt lgkmcnt(7)
	v_mfma_f32_32x32x16_bf16 v[48:63], v[124:127], v[108:111], v[48:63]
	ds_read_b128 v[124:127], v174 offset:288
	s_waitcnt lgkmcnt(7)
	v_mfma_f32_32x32x16_bf16 v[32:47], v[248:251], v[108:111], v[32:47]
	ds_read_b128 v[248:251], v174 offset:17184
	s_waitcnt vmcnt(23)
	s_waitcnt lgkmcnt(7)
	v_mfma_f32_32x32x16_bf16 v[48:63], v[232:235], v[104:107], v[48:63]
	ds_read_b128 v[232:235], v174 offset:320
	s_waitcnt lgkmcnt(7)
	v_mfma_f32_32x32x16_bf16 v[32:47], v[120:123], v[104:107], v[32:47]
	ds_read_b128 v[120:123], v174 offset:17216
	s_waitcnt vmcnt(22)
	s_waitcnt lgkmcnt(7)
	v_mfma_f32_32x32x16_bf16 v[48:63], v[236:239], v[100:103], v[48:63]
	ds_read_b128 v[236:239], v174 offset:352
	s_waitcnt lgkmcnt(7)
	v_mfma_f32_32x32x16_bf16 v[32:47], v[128:131], v[100:103], v[32:47]
	ds_read_b128 v[128:131], v174 offset:17248
	s_waitcnt vmcnt(21)
	s_waitcnt lgkmcnt(7)
	v_mfma_f32_32x32x16_bf16 v[48:63], v[240:243], v[96:99], v[48:63]
	ds_read_b128 v[240:243], v174 offset:384
	s_waitcnt lgkmcnt(7)
	v_mfma_f32_32x32x16_bf16 v[32:47], v[244:247], v[96:99], v[32:47]
	ds_read_b128 v[244:247], v174 offset:17280
	s_waitcnt vmcnt(20)
	s_waitcnt lgkmcnt(7)
	v_mfma_f32_32x32x16_bf16 v[48:63], v[124:127], v[92:95], v[48:63]
	ds_read_b128 v[124:127], v174 offset:416
	s_waitcnt lgkmcnt(7)
	v_mfma_f32_32x32x16_bf16 v[32:47], v[248:251], v[92:95], v[32:47]
	ds_read_b128 v[248:251], v174 offset:17312
	s_waitcnt vmcnt(19)
	s_waitcnt lgkmcnt(7)
	v_mfma_f32_32x32x16_bf16 v[48:63], v[232:235], v[88:91], v[48:63]
	ds_read_b128 v[232:235], v174 offset:448
	s_waitcnt lgkmcnt(7)
	v_mfma_f32_32x32x16_bf16 v[32:47], v[120:123], v[88:91], v[32:47]
	ds_read_b128 v[120:123], v174 offset:17344
	s_waitcnt vmcnt(18)
	s_waitcnt lgkmcnt(7)
	v_mfma_f32_32x32x16_bf16 v[48:63], v[236:239], v[80:83], v[48:63]
	ds_read_b128 v[236:239], v174 offset:480
	s_waitcnt lgkmcnt(7)
	v_mfma_f32_32x32x16_bf16 v[32:47], v[128:131], v[80:83], v[32:47]
	ds_read_b128 v[128:131], v174 offset:17376
	s_waitcnt vmcnt(17)
	s_waitcnt lgkmcnt(7)
	v_mfma_f32_32x32x16_bf16 v[48:63], v[240:243], v[76:79], v[48:63]
	s_waitcnt lgkmcnt(6)
	v_mfma_f32_32x32x16_bf16 v[32:47], v[244:247], v[76:79], v[32:47]
	s_waitcnt vmcnt(16)
	s_waitcnt lgkmcnt(5)
	v_mfma_f32_32x32x16_bf16 v[48:63], v[124:127], v[72:75], v[48:63]
	v_add_u32_e32 v88, s34, v226
	v_or_b32_e32 v89, 0x400, v88
	v_or_b32_e32 v186, 0x3800, v88
	v_or_b32_e32 v187, 0x3c00, v88
	s_waitcnt lgkmcnt(4)
	v_mfma_f32_32x32x16_bf16 v[32:47], v[248:251], v[72:75], v[32:47]
	s_waitcnt vmcnt(15)
	s_waitcnt lgkmcnt(3)
	v_mfma_f32_32x32x16_bf16 v[48:63], v[232:235], v[68:71], v[48:63]
	v_or_b32_e32 v174, 0x3400, v88
	s_waitcnt lgkmcnt(2)
	v_mfma_f32_32x32x16_bf16 v[32:47], v[120:123], v[68:71], v[32:47]
	v_or_b32_e32 v68, 0x800, v88
	v_or_b32_e32 v69, 0xc00, v88
	v_or_b32_e32 v70, 0x1000, v88
	v_or_b32_e32 v71, 0x1400, v88
	v_or_b32_e32 v72, 0x1800, v88
	v_or_b32_e32 v73, 0x1c00, v88
	v_or_b32_e32 v74, 0x2000, v88
	s_waitcnt vmcnt(14)
	s_waitcnt lgkmcnt(1)
	v_mfma_f32_32x32x16_bf16 v[48:63], v[236:239], v[64:67], v[48:63]
	v_or_b32_e32 v75, 0x2400, v88
	v_or_b32_e32 v76, 0x2800, v88
	v_or_b32_e32 v77, 0x2c00, v88
	v_or_b32_e32 v78, 0x3000, v88
	s_waitcnt lgkmcnt(0)
; #define LAS __attribute__((address_space(3)))
; DI unsigned cvt_pk_bf16(float lo, float hi) { unsigned r; asm volatile("v_cvt_pk_bf16_f32 %0, %1, %2" : "=v"(r) : "v"(lo), "v"(hi)); return r; }
; DI float bf_lo(unsigned w) { return __uint_as_float(w << 16); }
; DI float bf_hi(unsigned w) { return __uint_as_float(w & 0xffff0000u); }
; #define MFMA32(a, b, c) __builtin_amdgcn_mfma_f32_32x32x16_bf16((a), (b), (c), 0, 0, 0)
; template <bool XW, int PASS, bool RMW> ...
;     ...
;         for (int s = 0; s < 16; ++s) qf[s] = ldg16(qr, qoff0 + (unsigned)cn * 262144u + 1024u * s);
;         const float qe = cc > 0 ? qd : 0.f;
; #pragma unroll
;         for (int gq = 0; gq < 4; ++gq) {
;           u32x2 a; a.x = cvt_pk_bf16(bf_lo(ovn[gq].x) + qe * yc0[4 * gq], bf_hi(ovn[gq].x) + qe * yc0[4 * gq + 1]); a.y = cvt_pk_bf16(bf_lo(ovn[gq].y) + qe * yc0[4 * gq + 2], bf_hi(ovn[gq].y) + qe * yc0[4 * gq + 3]);
;           *(u32x2*)((char*)y + (yb + 16u * gq)) = a;
;           u32x2 c2; c2.x = cvt_pk_bf16(bf_lo(ovn[4 + gq].x) + qe * yc1[4 * gq], bf_hi(ovn[4 + gq].x) + qe * yc1[4 * gq + 1]); c2.y = cvt_pk_bf16(bf_lo(ovn[4 + gq].y) + qe * yc1[4 * gq + 2], bf_hi(ovn[4 + gq].y) + qe * yc1[4 * gq + 3]);
;           *(u32x2*)((char*)y + (yb + 64u + 16u * gq)) = c2;
;         }
;         if constexpr (PASS == 1 && RMW) {
;           const unsigned ybn = yoff0 + (unsigned)cn * 524288u;
; #pragma unroll
;           for (int gq = 0; gq < 8; ++gq) ovn[gq] = *(const u32x2*)((const char*)y + (ybn + 64u * (gq >> 2) + 16u * (gq & 3)));
;         }
;       }
; #pragma unroll
;       for (int i = 0; i < 16; ++i) { st0[i] *= cd; st1[i] *= cd; }
; #pragma unroll
;       for (int sb = 0; sb < 2; ++sb) {
;         bf16x8 a0[4], a1[4];
; #pragma unroll
;         for (int k = 0; k < 4; ++k) { a0[k] = *(const LAS bf16x8*)(vimg + (cc & 1) * 16384 + (4 * sb + k) * 1024 + lane * 16); a1[k] = *(const LAS bf16x8*)(vimg + (cc & 1) * 16384 + 8192 + (4 * sb + k) * 1024 + lane * 16); }
; #pragma unroll
;         for (int k = 0; k < 4; ++k) { st0 = MFMA32(a0[k], kb0[4 * sb + k], st0); st1 = MFMA32(a1[k], kb0[4 * sb + k], st1); }
;         asm volatile("" : "+v"(st0), "+v"(st1) :: "memory");
; #pragma unroll
;         for (int k = 0; k < 4; ++k) kb0[4 * sb + k] = ldg16(kT, kboff0 + (unsigned)cn * 262144u + 1024u * (4 * sb + k));
	v_mfma_f32_32x32x16_bf16 v[32:47], v[128:131], v[64:67], v[32:47]
	global_load_dwordx4 v[128:131], v88, s[92:93]
	global_load_dwordx4 v[124:127], v89, s[92:93]
	global_load_dwordx4 v[120:123], v68, s[92:93]
	global_load_dwordx4 v[116:119], v69, s[92:93]
	global_load_dwordx4 v[112:115], v70, s[92:93]
	global_load_dwordx4 v[108:111], v71, s[92:93]
	global_load_dwordx4 v[104:107], v72, s[92:93]
	global_load_dwordx4 v[100:103], v73, s[92:93]
	global_load_dwordx4 v[96:99], v74, s[92:93]
	global_load_dwordx4 v[92:95], v75, s[92:93]
	global_load_dwordx4 v[88:91], v76, s[92:93]
	global_load_dwordx4 v[80:83], v77, s[92:93]
	s_nop 0
	global_load_dwordx4 v[76:79], v78, s[92:93]
	s_nop 0
	global_load_dwordx4 v[72:75], v174, s[92:93]
	global_load_dwordx4 v[68:71], v186, s[92:93]
	global_load_dwordx4 v[64:67], v187, s[92:93]
	v_mbcnt_lo_u32_b32 v211, -1, 0
	v_mbcnt_hi_u32_b32 v211, -1, v211
	v_readlane_b32 s100, v255, 12
	v_and_b32_e32 v240, 31, v211
	v_lshrrev_b32_e32 v241, 5, v211
	v_lshrrev_b32_e32 v242, 3, v211
	v_and_b32_e32 v243, 7, v211
	v_mov_b32_e32 v245, s100
	v_mul_u32_u24_e32 v245, 0x44, v245
	v_add_u32_e32 v245, 0x1a000, v245
	v_mul_u32_u24_e32 v204, 0x88, v240
	v_lshl_add_u32 v204, v241, 3, v204
	v_add_u32_e32 v204, v245, v204
	v_mul_u32_u24_e32 v205, 0x88, v242
	v_lshl_add_u32 v205, v243, 4, v205
	v_add_u32_e32 v205, v245, v205
	v_sub_u32_e32 v244, v242, v240
	v_lshlrev_b32_e32 v244, 12, v244
	v_lshl_add_u32 v244, v243, 4, v244
	v_lshlrev_b32_e32 v241, 3, v241
	v_sub_u32_e32 v244, v244, v241
	v_add_u32_e32 v207, v173, v244
	v_add_u32_e32 v207, 0xffffff90, v207
	v_add_u32_e32 v208, 0x8000, v207
	v_add_u32_e32 v209, 0x10000, v207
	v_add_u32_e32 v210, 0x18000, v207
	v_fma_f32 v48, v172, v48, 0
	v_fma_f32 v49, v172, v49, 0
	v_fma_f32 v50, v172, v50, 0
	v_fma_f32 v51, v172, v51, 0
	v_fma_f32 v52, v172, v52, 0
	v_fma_f32 v53, v172, v53, 0
	v_fma_f32 v54, v172, v54, 0
	v_fma_f32 v55, v172, v55, 0
	v_fma_f32 v56, v172, v56, 0
	v_fma_f32 v57, v172, v57, 0
	v_fma_f32 v58, v172, v58, 0
	v_fma_f32 v59, v172, v59, 0
	v_fma_f32 v60, v172, v60, 0
	v_fma_f32 v61, v172, v61, 0
	v_fma_f32 v62, v172, v62, 0
	v_fma_f32 v63, v172, v63, 0
	v_fma_f32 v32, v172, v32, 0
	v_fma_f32 v33, v172, v33, 0
	v_fma_f32 v34, v172, v34, 0
	v_fma_f32 v35, v172, v35, 0
	v_fma_f32 v36, v172, v36, 0
	v_fma_f32 v37, v172, v37, 0
	v_fma_f32 v38, v172, v38, 0
	v_fma_f32 v39, v172, v39, 0
	v_fma_f32 v40, v172, v40, 0
	v_fma_f32 v41, v172, v41, 0
	v_fma_f32 v42, v172, v42, 0
	v_fma_f32 v43, v172, v43, 0
	v_fma_f32 v44, v172, v44, 0
	v_fma_f32 v45, v172, v45, 0
	v_fma_f32 v46, v172, v46, 0
	v_fma_f32 v47, v172, v47, 0
	v_cvt_pk_bf16_f32 v232, v48, v49
	v_cvt_pk_bf16_f32 v233, v50, v51
	v_cvt_pk_bf16_f32 v234, v52, v53
	v_cvt_pk_bf16_f32 v235, v54, v55
	v_cvt_pk_bf16_f32 v236, v56, v57
	v_cvt_pk_bf16_f32 v237, v58, v59
	v_cvt_pk_bf16_f32 v238, v60, v61
	v_cvt_pk_bf16_f32 v239, v62, v63
	v_cvt_pk_bf16_f32 v240, v32, v33
	v_cvt_pk_bf16_f32 v241, v34, v35
	v_cvt_pk_bf16_f32 v242, v36, v37
	v_cvt_pk_bf16_f32 v243, v38, v39
	v_cvt_pk_bf16_f32 v244, v40, v41
	v_cvt_pk_bf16_f32 v245, v42, v43
	v_cvt_pk_bf16_f32 v246, v44, v45
	v_cvt_pk_bf16_f32 v247, v46, v47
	ds_write_b64 v204, v[232:233]
	ds_write_b64 v204, v[234:235] offset:16
	ds_write_b64 v204, v[236:237] offset:32
	ds_write_b64 v204, v[238:239] offset:48
	ds_write_b64 v204, v[240:241] offset:64
	ds_write_b64 v204, v[242:243] offset:80
	ds_write_b64 v204, v[244:245] offset:96
	ds_write_b64 v204, v[246:247] offset:112
	s_waitcnt lgkmcnt(0)
	ds_read_b128 v[232:235], v205
	ds_read_b128 v[236:239], v205 offset:1088
	ds_read_b128 v[240:243], v205 offset:2176
	ds_read_b128 v[244:247], v205 offset:3264
	s_waitcnt lgkmcnt(0)
	global_store_dwordx4 v207, v[232:235], s[18:19]
	global_store_dwordx4 v208, v[236:239], s[18:19]
	global_store_dwordx4 v209, v[240:243], s[18:19]
	global_store_dwordx4 v210, v[244:247], s[18:19]
	s_nop 1
	ds_read_b128 v[232:235], v169
	ds_read_b128 v[236:239], v169 offset:8192
	ds_read_b128 v[240:243], v169 offset:1024
	ds_read_b128 v[244:247], v169 offset:9216
	ds_read_b128 v[248:251], v169 offset:2048
	s_waitcnt vmcnt(29)
	s_waitcnt lgkmcnt(4)
	v_mfma_f32_32x32x16_bf16 v[16:31], v[232:235], v[164:167], v[16:31]
	ds_read_b128 v[232:235], v169 offset:10240
	v_add_u32_e32 v62, s34, v223
	s_waitcnt vmcnt(21)
	v_lshlrev_b32_e32 v46, 16, v152
	v_and_b32_e32 v47, 0xffff0000, v152
	v_lshlrev_b32_e32 v48, 16, v153
	v_and_b32_e32 v49, 0xffff0000, v153
	v_add_u32_e32 v60, s35, v198
	s_waitcnt lgkmcnt(4)
	v_mfma_f32_32x32x16_bf16 v[0:15], v[236:239], v[164:167], v[0:15]
	ds_read_b128 v[236:239], v169 offset:3072
	v_lshlrev_b32_e32 v50, 16, v154
	v_and_b32_e32 v51, 0xffff0000, v154
	v_lshlrev_b32_e32 v52, 16, v155
	v_lshl_add_u32 v61, s9, 19, v224
	v_add_u32_e32 v63, s3, v60
	s_waitcnt vmcnt(20)
	v_and_b32_e32 v53, 0xffff0000, v148
	v_lshlrev_b32_e32 v54, 16, v149
	s_waitcnt lgkmcnt(4)
	v_mfma_f32_32x32x16_bf16 v[16:31], v[240:243], v[160:163], v[16:31]
	ds_read_b128 v[240:243], v169 offset:11264
	v_and_b32_e32 v55, 0xffff0000, v149
	v_lshlrev_b32_e32 v56, 16, v150
	v_and_b32_e32 v57, 0xffff0000, v150
	v_lshlrev_b32_e32 v58, 16, v151
	v_and_b32_e32 v59, 0xffff0000, v151
	s_mul_i32 s9, s0, 0x8400
	s_waitcnt lgkmcnt(4)
	v_mfma_f32_32x32x16_bf16 v[0:15], v[244:247], v[160:163], v[0:15]
	ds_read_b128 v[244:247], v169 offset:4096
	s_waitcnt lgkmcnt(4)
	v_mfma_f32_32x32x16_bf16 v[16:31], v[248:251], v[156:159], v[16:31]
	ds_read_b128 v[248:251], v169 offset:12288
	v_and_b32_e32 v44, 0xffff0000, v155
	v_lshlrev_b32_e32 v45, 16, v148
	v_or_b32_e32 v148, s3, v61
	v_or_b32_e32 v61, s33, v61
	v_add_u32_e32 v173, 0x80000, v173
	s_waitcnt lgkmcnt(4)
; #define LAS __attribute__((address_space(3)))
; DI unsigned cvt_pk_bf16(float lo, float hi) { unsigned r; asm volatile("v_cvt_pk_bf16_f32 %0, %1, %2" : "=v"(r) : "v"(lo), "v"(hi)); return r; }
; #define MFMA32(a, b, c) __builtin_amdgcn_mfma_f32_32x32x16_bf16((a), (b), (c), 0, 0, 0)
; template <bool XW, int PASS, bool RMW> ...
;     ...
;       for (int sb = 0; sb < 2; ++sb) {
;         bf16x8 a0[4], a1[4];
; #pragma unroll
;         for (int k = 0; k < 4; ++k) { a0[k] = *(const LAS bf16x8*)(vimg + (cc & 1) * 16384 + (4 * sb + k) * 1024 + lane * 16); a1[k] = *(const LAS bf16x8*)(vimg + (cc & 1) * 16384 + 8192 + (4 * sb + k) * 1024 + lane * 16); }
; #pragma unroll
;         for (int k = 0; k < 4; ++k) { st0 = MFMA32(a0[k], kb0[4 * sb + k], st0); st1 = MFMA32(a1[k], kb0[4 * sb + k], st1); }
;         asm volatile("" : "+v"(st0), "+v"(st1) :: "memory");
; #pragma unroll
;         for (int k = 0; k < 4; ++k) kb0[4 * sb + k] = ldg16(kT, kboff0 + (unsigned)cn * 262144u + 1024u * (4 * sb + k));
;       }
; #pragma unroll
;       for (int t = 0; t < 2; ++t) {
;         const int sv = 2 * dq + t;
;         *(LAS bf16x8*)(vimg + ((cc + 1) & 1) * 16384 + et * 8192 + sv * 1024 + lane * 16) = scale_tab(vr[t], kdec + 16 * sv + 8 * h);
;         vr[t] = ldg16(vT, vaoff0 + (unsigned)cnn * 524288u + 1024u * sv);
;       }
;       LAS bf16_t* sw = Sb + (pbuf ^ 1) * SBE + (4 * h) * 264 + 32 * w + r;
; #pragma unroll
;       for (int i = 0; i < 16; ++i) {
;         const int eo = ((i & 3) + 8 * (i >> 2)) * 264;
;         const unsigned pkw = cvt_pk_bf16(st0[i], st1[i]);
;         sw[eo] = (bf16_t)(pkw & 0xffffu);
;         sw[eo + 32 * 264] = (bf16_t)(pkw >> 16);
;       }
;       lds_barrier();
;       pbuf ^= 1;
	v_mfma_f32_32x32x16_bf16 v[0:15], v[232:235], v[156:159], v[0:15]
	ds_read_b128 v[232:235], v169 offset:5120
	s_waitcnt lgkmcnt(4)
	v_mfma_f32_32x32x16_bf16 v[16:31], v[236:239], v[140:143], v[16:31]
	ds_read_b128 v[236:239], v169 offset:13312
	s_waitcnt lgkmcnt(4)
	v_mfma_f32_32x32x16_bf16 v[0:15], v[240:243], v[140:143], v[0:15]
	ds_read_b128 v[240:243], v169 offset:6144
	s_waitcnt lgkmcnt(4)
	v_mfma_f32_32x32x16_bf16 v[16:31], v[244:247], v[144:147], v[16:31]
	ds_read_b128 v[244:247], v169 offset:14336
	s_waitcnt lgkmcnt(4)
	v_mfma_f32_32x32x16_bf16 v[0:15], v[248:251], v[144:147], v[0:15]
	ds_read_b128 v[248:251], v169 offset:7168
	s_waitcnt lgkmcnt(4)
	v_mfma_f32_32x32x16_bf16 v[16:31], v[232:235], v[136:139], v[16:31]
	ds_read_b128 v[232:235], v169 offset:15360
	s_waitcnt lgkmcnt(4)
	v_mfma_f32_32x32x16_bf16 v[0:15], v[236:239], v[136:139], v[0:15]
	s_waitcnt lgkmcnt(3)
	v_mfma_f32_32x32x16_bf16 v[16:31], v[240:243], v[132:135], v[16:31]
	s_waitcnt lgkmcnt(2)
	v_mfma_f32_32x32x16_bf16 v[0:15], v[244:247], v[132:135], v[0:15]
	v_or_b32_e32 v32, 0x400, v62
	v_or_b32_e32 v33, 0x800, v62
	v_or_b32_e32 v34, 0xc00, v62
	global_load_dwordx4 v[164:167], v62, s[14:15]
	global_load_dwordx4 v[160:163], v32, s[14:15]
	global_load_dwordx4 v[156:159], v33, s[14:15]
	global_load_dwordx4 v[140:143], v34, s[14:15]
	v_or_b32_e32 v132, 0x1000, v62
	s_waitcnt lgkmcnt(1)
	v_mfma_f32_32x32x16_bf16 v[16:31], v[248:251], v[84:87], v[16:31]
	v_or_b32_e32 v36, 0x1400, v62
	v_or_b32_e32 v37, 0x1800, v62
	v_or_b32_e32 v38, 0x1c00, v62
	s_waitcnt lgkmcnt(0)
	v_mfma_f32_32x32x16_bf16 v[0:15], v[232:235], v[84:87], v[0:15]
	ds_read_b128 v[32:35], v228
	global_load_dwordx4 v[144:147], v132, s[14:15]
	global_load_dwordx4 v[136:139], v36, s[14:15]
	s_nop 0
	global_load_dwordx4 v[132:135], v37, s[14:15]
	global_load_dwordx4 v[84:87], v38, s[14:15]
	ds_read_b128 v[36:39], v228 offset:16
	s_waitcnt lgkmcnt(1)
	v_mul_f32_e32 v32, v32, v46
	v_mul_f32_e32 v33, v33, v47
	v_mul_f32_e32 v34, v34, v48
	v_mul_f32_e32 v35, v35, v49
	s_waitcnt lgkmcnt(0)
	v_mul_f32_e32 v36, v36, v50
	v_mul_f32_e32 v37, v37, v51
	v_mul_f32_e32 v38, v38, v52
	v_mul_f32_e32 v39, v39, v44
	v_cvt_pk_bf16_f32 v32, v32, v33
	v_cvt_pk_bf16_f32 v33, v34, v35
	v_cvt_pk_bf16_f32 v34, v36, v37
	v_cvt_pk_bf16_f32 v35, v38, v39
	ds_write_b128 v63, v[32:35]
	global_load_dwordx4 v[152:155], v148, s[16:17]
	ds_read_b128 v[32:35], v229
	ds_read_b128 v[36:39], v229 offset:16
	s_waitcnt lgkmcnt(1)
	v_mul_f32_e32 v32, v32, v45
	v_mul_f32_e32 v33, v33, v53
	v_mul_f32_e32 v34, v34, v54
	v_mul_f32_e32 v35, v35, v55
	s_waitcnt lgkmcnt(0)
	v_mul_f32_e32 v36, v36, v56
	v_mul_f32_e32 v37, v37, v57
	v_mul_f32_e32 v38, v38, v58
	v_mul_f32_e32 v39, v39, v59
	v_cvt_pk_bf16_f32 v32, v32, v33
	v_cvt_pk_bf16_f32 v33, v34, v35
	v_cvt_pk_bf16_f32 v34, v36, v37
	v_cvt_pk_bf16_f32 v35, v38, v39
	global_load_dwordx4 v[148:151], v61, s[16:17]
	v_add_u32_e32 v37, s33, v60
	v_add_u32_e32 v36, s9, v199
	ds_write_b128 v37, v[32:35]
	v_mbcnt_lo_u32_b32 v251, -1, 0
	v_mbcnt_hi_u32_b32 v251, -1, v251
	v_and_b32_e32 v251, 1, v251
	v_sub_u32_e32 v250, 0, v251
	v_and_b32_e32 v248, 0x06060606, v250
	v_xor_b32_e32 v248, 0x05040100, v248
	v_and_b32_e32 v251, 0x107e, v250
	v_add_u32_e32 v249, v36, v251
	v_cvt_pk_bf16_f32 v232, v16, v20
	v_cvt_pk_bf16_f32 v233, v17, v21
	v_cvt_pk_bf16_f32 v234, v18, v22
	v_cvt_pk_bf16_f32 v235, v19, v23
	v_cvt_pk_bf16_f32 v236, v24, v28
	v_cvt_pk_bf16_f32 v237, v25, v29
	v_cvt_pk_bf16_f32 v238, v26, v30
	v_cvt_pk_bf16_f32 v239, v27, v31
	v_mov_b32_dpp v240, v232 quad_perm:[1,0,3,2] row_mask:0xf bank_mask:0xf
	v_mov_b32_dpp v241, v233 quad_perm:[1,0,3,2] row_mask:0xf bank_mask:0xf
	v_mov_b32_dpp v242, v234 quad_perm:[1,0,3,2] row_mask:0xf bank_mask:0xf
	v_mov_b32_dpp v243, v235 quad_perm:[1,0,3,2] row_mask:0xf bank_mask:0xf
	v_mov_b32_dpp v244, v236 quad_perm:[1,0,3,2] row_mask:0xf bank_mask:0xf
	v_mov_b32_dpp v245, v237 quad_perm:[1,0,3,2] row_mask:0xf bank_mask:0xf
	v_mov_b32_dpp v246, v238 quad_perm:[1,0,3,2] row_mask:0xf bank_mask:0xf
	v_mov_b32_dpp v247, v239 quad_perm:[1,0,3,2] row_mask:0xf bank_mask:0xf
	v_perm_b32 v240, v240, v232, v248
	v_perm_b32 v241, v241, v233, v248
	v_perm_b32 v242, v242, v234, v248
	v_perm_b32 v243, v243, v235, v248
	v_perm_b32 v244, v244, v236, v248
	v_perm_b32 v245, v245, v237, v248
	v_perm_b32 v246, v246, v238, v248
	v_perm_b32 v247, v247, v239, v248
	ds_write_b32 v249, v240 offset:0
	ds_write_b32 v249, v241 offset:528
	ds_write_b32 v249, v242 offset:1056
	ds_write_b32 v249, v243 offset:1584
	ds_write_b32 v249, v244 offset:8448
	ds_write_b32 v249, v245 offset:8976
	ds_write_b32 v249, v246 offset:9504
	ds_write_b32 v249, v247 offset:10032
	v_cvt_pk_bf16_f32 v232, v0, v4
	v_cvt_pk_bf16_f32 v233, v1, v5
	v_cvt_pk_bf16_f32 v234, v2, v6
	v_cvt_pk_bf16_f32 v235, v3, v7
	v_cvt_pk_bf16_f32 v236, v8, v12
	v_cvt_pk_bf16_f32 v237, v9, v13
	v_cvt_pk_bf16_f32 v238, v10, v14
	v_cvt_pk_bf16_f32 v239, v11, v15
	v_mov_b32_dpp v240, v232 quad_perm:[1,0,3,2] row_mask:0xf bank_mask:0xf
	v_mov_b32_dpp v241, v233 quad_perm:[1,0,3,2] row_mask:0xf bank_mask:0xf
	v_mov_b32_dpp v242, v234 quad_perm:[1,0,3,2] row_mask:0xf bank_mask:0xf
	v_mov_b32_dpp v243, v235 quad_perm:[1,0,3,2] row_mask:0xf bank_mask:0xf
	v_mov_b32_dpp v244, v236 quad_perm:[1,0,3,2] row_mask:0xf bank_mask:0xf
	v_mov_b32_dpp v245, v237 quad_perm:[1,0,3,2] row_mask:0xf bank_mask:0xf
	v_mov_b32_dpp v246, v238 quad_perm:[1,0,3,2] row_mask:0xf bank_mask:0xf
	v_mov_b32_dpp v247, v239 quad_perm:[1,0,3,2] row_mask:0xf bank_mask:0xf
	v_perm_b32 v240, v240, v232, v248
	v_perm_b32 v241, v241, v233, v248
	v_perm_b32 v242, v242, v234, v248
	v_perm_b32 v243, v243, v235, v248
	v_perm_b32 v244, v244, v236, v248
	v_perm_b32 v245, v245, v237, v248
	v_perm_b32 v246, v246, v238, v248
	v_perm_b32 v247, v247, v239, v248
	ds_write_b32 v249, v240 offset:16896
	ds_write_b32 v249, v241 offset:17424
	ds_write_b32 v249, v242 offset:17952
	ds_write_b32 v249, v243 offset:18480
	ds_write_b32 v249, v244 offset:25344
	ds_write_b32 v249, v245 offset:25872
	ds_write_b32 v249, v246 offset:26400
	ds_write_b32 v249, v247 offset:26928
	s_waitcnt lgkmcnt(0)
	s_barrier
	s_mov_b32 s9, s8
	s_cbranch_scc1 .LBB0_97
	s_setprio 0
	s_cmp_lg_u32 s31, 0
	s_cbranch_scc1 .LBB0_103
	s_and_saveexec_b64 s[0:1], s[6:7]
	s_cbranch_execz .LBB0_101
	v_mul_f32_e64 v0, v200, -v225
	v_exp_f32_e32 v0, v0
	ds_write_b32 v195, v0
; #define LAS __attribute__((address_space(3)))
; #define EX2(x) __builtin_amdgcn_exp2f(x)
; template <bool XW, int PASS, bool RMW> ...
;     ...
;     const float qd = pass == 0 ? EX2(lgf * (float)(icol + 1)) : EX2(lgb * (float)(128 - icol));
;     int pbuf = 0;
;     if (tids < 128) kdec[tids] = EX2(lg * (float)(PASS == 0 ? 127 - tids : tids));
;     __syncthreads();
;     bf16x8 qf[16], vr[2], kb0[8];
;     u32x2 ovn[8];
; #pragma unroll
;     for (int gq = 0; gq < 8; ++gq) { ovn[gq].x = 0u; ovn[gq].y = 0u; }
;     {
;       const int c0 = pass == 0 ? 0 : nc - 1, c1 = pass == 0 ? 1 : nc - 2;
;       if constexpr (XW) {
; #pragma unroll
;         for (int s = 0; s < 16; ++s) qf[s] = ldg16(qr, qoff0 + (unsigned)c0 * 262144u + 1024u * s);
;         if constexpr (PASS == 1 && RMW) {
; #pragma unroll
;           for (int gq = 0; gq < 8; ++gq) ovn[gq] = *(const u32x2*)((const char*)y + (yoff0 + (unsigned)c0 * 524288u + 64u * (gq >> 2) + 16u * (gq & 3)));
;         }
;       }
; #pragma unroll
;       for (int s = 0; s < 8; ++s) kb0[s] = ldg16(kT, kboff0 + (unsigned)c0 * 262144u + 1024u * s);
; #pragma unroll
;       for (int t = 0; t < 2; ++t) {
;         const int sv = 2 * dq + t;
;         const bf16x8 raw = ldg16(vT, vaoff0 + (unsigned)c0 * 524288u + 1024u * sv);
;         *(LAS bf16x8*)(vimg + et * 8192 + sv * 1024 + lane * 16) = scale_tab(raw, kdec + 16 * sv + 8 * h);
;         vr[t] = ldg16(vT, vaoff0 + (unsigned)c1 * 524288u + 1024u * sv);
;       }
;       lds_barrier();
.LBB0_101:
	s_or_b64 exec, exec, s[0:1]
	v_add_u32_e32 v0, s21, v224
	v_or_b32_e32 v1, s3, v0
	s_waitcnt lgkmcnt(0)
	s_barrier
	global_load_dwordx4 v[8:11], v1, s[16:17]
	ds_read_b128 v[12:15], v228
	ds_read_b128 v[16:19], v228 offset:16
	v_add_u32_e32 v1, s20, v226
	v_add_u32_e32 v6, s20, v223
	v_add_u32_e32 v7, s21, v227
	v_or_b32_e32 v2, 0x400, v1
	v_or_b32_e32 v3, 0x800, v1
	v_or_b32_e32 v4, 0xc00, v1
	v_or_b32_e32 v5, 0x1000, v1
	v_or_b32_e32 v40, 0x1800, v6
	v_or_b32_e32 v41, 0x1c00, v6
	v_or_b32_e32 v20, 0x1400, v1
	v_or_b32_e32 v21, 0x1800, v1
	v_or_b32_e32 v22, 0x1c00, v1
	v_or_b32_e32 v23, 0x2000, v1
	v_or_b32_e32 v28, 0x2400, v1
	v_or_b32_e32 v29, 0x2800, v1
	v_or_b32_e32 v30, 0x2c00, v1
	v_or_b32_e32 v31, 0x3000, v1
	v_or_b32_e32 v32, 0x3400, v1
	v_or_b32_e32 v33, 0x3800, v1
	v_or_b32_e32 v34, 0x3c00, v1
	s_waitcnt vmcnt(1)
	v_or_b32_e32 v148, 16, v7
	v_or_b32_e32 v146, 32, v7
	v_or_b32_e32 v145, 48, v7
	v_or_b32_e32 v150, 64, v7
	v_or_b32_e32 v149, 0x50, v7
	v_or_b32_e32 v147, 0x60, v7
	v_or_b32_e32 v144, 0x70, v7
	v_or_b32_e32 v35, 0x400, v6
	v_or_b32_e32 v36, 0x800, v6
	v_or_b32_e32 v37, 0xc00, v6
	v_or_b32_e32 v38, 0x1000, v6
	v_or_b32_e32 v39, 0x1400, v6
	global_load_dwordx4 v[24:27], v1, s[92:93]
	global_load_dwordx4 v[100:103], v2, s[92:93]
	global_load_dwordx4 v[104:107], v3, s[92:93]
	global_load_dwordx4 v[108:111], v4, s[92:93]
	global_load_dwordx4 v[112:115], v5, s[92:93]
	global_load_dwordx4 v[116:119], v20, s[92:93]
	global_load_dwordx4 v[120:123], v21, s[92:93]
	global_load_dwordx4 v[124:127], v22, s[92:93]
	global_load_dwordx4 v[152:155], v23, s[92:93]
	global_load_dwordx4 v[156:159], v28, s[92:93]
	global_load_dwordx4 v[80:83], v29, s[92:93]
	global_load_dwordx4 v[76:79], v30, s[92:93]
	global_load_dwordx4 v[2:5], v31, s[92:93]
	global_load_dwordx4 v[72:75], v32, s[92:93]
	global_load_dwordx4 v[68:71], v33, s[92:93]
	global_load_dwordx4 v[64:67], v34, s[92:93]
	global_load_dwordx2 v[98:99], v7, s[18:19]
	global_load_dwordx2 v[94:95], v148, s[18:19]
	global_load_dwordx2 v[88:89], v146, s[18:19]
	global_load_dwordx2 v[84:85], v145, s[18:19]
	global_load_dwordx2 v[96:97], v150, s[18:19]
	global_load_dwordx2 v[92:93], v149, s[18:19]
	global_load_dwordx2 v[90:91], v147, s[18:19]
	global_load_dwordx2 v[86:87], v144, s[18:19]
	global_load_dwordx4 v[132:135], v6, s[14:15]
	global_load_dwordx4 v[140:143], v35, s[14:15]
	global_load_dwordx4 v[136:139], v36, s[14:15]
	global_load_dwordx4 v[128:131], v37, s[14:15]
	global_load_dwordx4 v[60:63], v38, s[14:15]
	global_load_dwordx4 v[56:59], v39, s[14:15]
	global_load_dwordx4 v[44:47], v40, s[14:15]
	s_nop 0
	global_load_dwordx4 v[40:43], v41, s[14:15]
	v_or_b32_e32 v0, s33, v0
	s_mov_b32 s0, 1
	s_movk_i32 s1, 0x4000
	s_waitcnt vmcnt(32)
	v_lshlrev_b32_e32 v1, 16, v8
	v_and_b32_e32 v6, 0xffff0000, v8
	v_lshlrev_b32_e32 v8, 16, v9
	v_and_b32_e32 v9, 0xffff0000, v9
	v_lshlrev_b32_e32 v20, 16, v10
	v_and_b32_e32 v10, 0xffff0000, v10
	s_waitcnt lgkmcnt(1)
	v_mul_f32_e32 v1, v12, v1
	v_mul_f32_e32 v6, v13, v6
	v_mul_f32_e32 v12, v14, v8
	v_mul_f32_e32 v9, v15, v9
	v_cvt_pk_bf16_f32 v8, v1, v6
	s_waitcnt lgkmcnt(0)
	v_mul_f32_e32 v1, v17, v10
	v_mul_f32_e32 v13, v16, v20
	v_cvt_pk_bf16_f32 v9, v12, v9
	v_cvt_pk_bf16_f32 v10, v13, v1
	v_lshlrev_b32_e32 v1, 16, v11
	v_and_b32_e32 v6, 0xffff0000, v11
	v_mul_f32_e32 v1, v18, v1
	v_mul_f32_e32 v6, v19, v6
	v_cvt_pk_bf16_f32 v11, v1, v6
	global_load_dwordx4 v[12:15], v0, s[16:17]
	v_add_u32_e32 v0, s22, v224
	v_or_b32_e32 v1, s3, v0
	ds_write_b128 v183, v[8:11]
	global_load_dwordx4 v[52:55], v1, s[16:17]
	ds_read_b128 v[8:11], v229
	ds_read_b128 v[16:19], v229 offset:16
	v_or_b32_e32 v0, s33, v0
	s_waitcnt vmcnt(13)
	v_lshlrev_b32_e32 v169, 16, v97
	v_and_b32_e32 v170, 0xffff0000, v97
	v_lshlrev_b32_e32 v171, 16, v94
	v_and_b32_e32 v172, 0xffff0000, v94
	v_lshlrev_b32_e32 v173, 16, v95
	v_and_b32_e32 v174, 0xffff0000, v95
	s_waitcnt vmcnt(12)
	v_lshlrev_b32_e32 v175, 16, v92
	v_and_b32_e32 v178, 0xffff0000, v92
	v_lshlrev_b32_e32 v179, 16, v93
	v_and_b32_e32 v180, 0xffff0000, v93
	v_lshlrev_b32_e32 v181, 16, v88
	v_and_b32_e32 v184, 0xffff0000, v88
	v_lshlrev_b32_e32 v185, 16, v89
	v_and_b32_e32 v186, 0xffff0000, v89
	s_waitcnt vmcnt(11)
	v_lshlrev_b32_e32 v187, 16, v90
	v_and_b32_e32 v188, 0xffff0000, v90
	v_lshlrev_b32_e32 v189, 16, v91
	v_and_b32_e32 v204, 0xffff0000, v91
	v_lshlrev_b32_e32 v205, 16, v84
	v_and_b32_e32 v206, 0xffff0000, v84
	v_lshlrev_b32_e32 v207, 16, v85
	v_and_b32_e32 v208, 0xffff0000, v85
	s_waitcnt vmcnt(10)
	v_lshlrev_b32_e32 v209, 16, v86
	v_and_b32_e32 v210, 0xffff0000, v86
	v_lshlrev_b32_e32 v211, 16, v87
	v_and_b32_e32 v215, 0xffff0000, v87
	s_waitcnt vmcnt(1)
	v_lshlrev_b32_e32 v1, 16, v12
	v_and_b32_e32 v6, 0xffff0000, v12
	v_lshlrev_b32_e32 v12, 16, v13
	v_and_b32_e32 v13, 0xffff0000, v13
	v_lshlrev_b32_e32 v20, 16, v14
	v_and_b32_e32 v14, 0xffff0000, v14
	v_lshlrev_b32_e32 v21, 16, v15
	v_and_b32_e32 v15, 0xffff0000, v15
	s_waitcnt lgkmcnt(1)
	v_mul_f32_e32 v6, v9, v6
	v_mul_f32_e32 v9, v10, v12
	v_mul_f32_e32 v10, v11, v13
	s_waitcnt lgkmcnt(0)
	v_mul_f32_e32 v11, v16, v20
	v_mul_f32_e32 v1, v8, v1
	v_mul_f32_e32 v12, v17, v14
	v_mul_f32_e32 v13, v18, v21
	v_mul_f32_e32 v14, v19, v15
	v_cvt_pk_bf16_f32 v8, v1, v6
	v_cvt_pk_bf16_f32 v9, v9, v10
	v_cvt_pk_bf16_f32 v10, v11, v12
	v_cvt_pk_bf16_f32 v11, v13, v14
	ds_write_b128 v182, v[8:11]
	global_load_dwordx4 v[48:51], v0, s[16:17]
	s_waitcnt lgkmcnt(0)
	s_barrier
; #define LAS __attribute__((address_space(3)))
; #define MFMA32(a, b, c) __builtin_amdgcn_mfma_f32_32x32x16_bf16((a), (b), (c), 0, 0, 0)
; template <bool XW, int PASS, bool RMW> ...
;     ...
;     for (int cc = 0; cc < nc; ++cc) {
;       const int c = pass == 0 ? cc : nc - 1 - cc;
;       const int k1 = cc + 1 < nc ? cc + 1 : nc - 1, k2 = cc + 2 < nc ? cc + 2 : nc - 1;
;       const int cn = pass == 0 ? k1 : nc - 1 - k1, cnn = pass == 0 ? k2 : nc - 1 - k2;
;       if constexpr (XW) {
;         const unsigned yb = yoff0 + (unsigned)c * 524288u;
;         f32x16 yc0, yc1;
; #pragma unroll
;         for (int i = 0; i < 16; ++i) { yc0[i] = 0.f; yc1[i] = 0.f; }
;         const LAS bf16_t* sp = Sb + pbuf * SBE + r * 264 + 8 * h;
; #pragma unroll
;         for (int sb = 0; sb < 8; ++sb) {
;           bf16x8 a0[2], a1[2];
; #pragma unroll
;           for (int k = 0; k < 2; ++k) { a0[k] = *(const LAS bf16x8*)(sp + 16 * (2 * sb + k)); a1[k] = *(const LAS bf16x8*)(sp + 32 * 264 + 16 * (2 * sb + k)); }
; #pragma unroll
;           for (int k = 0; k < 2; ++k) { yc0 = MFMA32(a0[k], qf[2 * sb + k], yc0); yc1 = MFMA32(a1[k], qf[2 * sb + k], yc1); }
;         }
;         asm volatile("" : "+v"(yc0), "+v"(yc1) :: "memory");
	ds_read_b128 v[8:11], v217
	ds_read_b128 v[160:163], v217 offset:32
	s_waitcnt lgkmcnt(1)
	v_mfma_f32_32x32x16_bf16 v[8:23], v[8:11], v[24:27], 0
	ds_read_b128 v[28:31], v217 offset:16896
	ds_read_b128 v[164:167], v217 offset:16928
	v_mul_f32_e32 v0, 0xc3000000, v225
	v_exp_f32_e32 v168, v0
	s_nop 0
	v_mul_f32_e32 v0, 0, v168
	s_waitcnt lgkmcnt(1)
	v_mfma_f32_32x32x16_bf16 v[24:39], v[28:31], v[24:27], 0
	v_mov_b32_e32 v1, v0
	v_mov_b32_e32 v6, v0
	v_mfma_f32_32x32x16_bf16 v[8:23], v[160:163], v[100:103], v[8:23]
	s_waitcnt lgkmcnt(0)
	v_mfma_f32_32x32x16_bf16 v[24:39], v[164:167], v[100:103], v[24:39]
	ds_read_b128 v[100:103], v217 offset:64
	ds_read_b128 v[160:163], v217 offset:96
	s_waitcnt lgkmcnt(1)
	v_mfma_f32_32x32x16_bf16 v[8:23], v[100:103], v[104:107], v[8:23]
	ds_read_b128 v[100:103], v217 offset:16960
	ds_read_b128 v[164:167], v217 offset:16992
	s_waitcnt lgkmcnt(1)
	v_mfma_f32_32x32x16_bf16 v[24:39], v[100:103], v[104:107], v[24:39]
	ds_read_b128 v[100:103], v217 offset:128
	ds_read_b128 v[104:107], v217 offset:160
	v_mfma_f32_32x32x16_bf16 v[8:23], v[160:163], v[108:111], v[8:23]
	v_lshlrev_b32_e32 v162, 16, v98
	v_and_b32_e32 v163, 0xffff0000, v98
	s_waitcnt lgkmcnt(2)
	v_mfma_f32_32x32x16_bf16 v[24:39], v[164:167], v[108:111], v[24:39]
	v_lshlrev_b32_e32 v164, 16, v99
	v_and_b32_e32 v165, 0xffff0000, v99
	v_lshlrev_b32_e32 v166, 16, v96
	v_and_b32_e32 v167, 0xffff0000, v96
	s_waitcnt lgkmcnt(1)
	v_mfma_f32_32x32x16_bf16 v[8:23], v[100:103], v[112:115], v[8:23]
	ds_read_b128 v[100:103], v217 offset:17024
	ds_read_b128 v[108:111], v217 offset:17056
	s_waitcnt lgkmcnt(1)
	v_mfma_f32_32x32x16_bf16 v[24:39], v[100:103], v[112:115], v[24:39]
	v_add_u32_e32 v112, s23, v226
	v_or_b32_e32 v151, 0x1400, v112
	v_or_b32_e32 v160, 0x3800, v112
	v_or_b32_e32 v161, 0x3c00, v112
	v_mfma_f32_32x32x16_bf16 v[8:23], v[104:107], v[116:119], v[8:23]
	ds_read_b128 v[100:103], v217 offset:192
	ds_read_b128 v[104:107], v217 offset:224
	s_waitcnt lgkmcnt(2)
	v_mfma_f32_32x32x16_bf16 v[24:39], v[108:111], v[116:119], v[24:39]
	s_waitcnt lgkmcnt(1)
	v_mfma_f32_32x32x16_bf16 v[8:23], v[100:103], v[120:123], v[8:23]
	ds_read_b128 v[100:103], v217 offset:17088
	ds_read_b128 v[108:111], v217 offset:17120
	s_waitcnt lgkmcnt(1)
	v_mfma_f32_32x32x16_bf16 v[24:39], v[100:103], v[120:123], v[24:39]
	v_mfma_f32_32x32x16_bf16 v[8:23], v[104:107], v[124:127], v[8:23]
	ds_read_b128 v[100:103], v217 offset:256
	ds_read_b128 v[104:107], v217 offset:288
	s_waitcnt lgkmcnt(2)
	v_mfma_f32_32x32x16_bf16 v[24:39], v[108:111], v[124:127], v[24:39]
	s_waitcnt lgkmcnt(1)
	v_mfma_f32_32x32x16_bf16 v[8:23], v[100:103], v[152:155], v[8:23]
	ds_read_b128 v[100:103], v217 offset:17152
	ds_read_b128 v[108:111], v217 offset:17184
	s_waitcnt lgkmcnt(1)
	v_mfma_f32_32x32x16_bf16 v[24:39], v[100:103], v[152:155], v[24:39]
	v_or_b32_e32 v152, 0x1800, v112
	v_or_b32_e32 v153, 0x1c00, v112
	v_or_b32_e32 v154, 0x2000, v112
	v_or_b32_e32 v155, 0x2400, v112
	v_mfma_f32_32x32x16_bf16 v[8:23], v[104:107], v[156:159], v[8:23]
	ds_read_b128 v[100:103], v217 offset:320
	ds_read_b128 v[104:107], v217 offset:352
	s_waitcnt lgkmcnt(2)
	v_mfma_f32_32x32x16_bf16 v[24:39], v[108:111], v[156:159], v[24:39]
	v_or_b32_e32 v156, 0x2800, v112
	v_or_b32_e32 v157, 0x2c00, v112
	v_or_b32_e32 v158, 0x3000, v112
	v_or_b32_e32 v159, 0x3400, v112
	s_waitcnt lgkmcnt(1)
	v_mfma_f32_32x32x16_bf16 v[8:23], v[100:103], v[80:83], v[8:23]
	ds_read_b128 v[100:103], v217 offset:17216
	ds_read_b128 v[108:111], v217 offset:17248
	s_waitcnt lgkmcnt(1)
	v_mfma_f32_32x32x16_bf16 v[24:39], v[100:103], v[80:83], v[24:39]
	ds_read_b128 v[80:83], v217 offset:384
	v_mfma_f32_32x32x16_bf16 v[8:23], v[104:107], v[76:79], v[8:23]
	v_or_b32_e32 v104, 0x400, v112
	v_or_b32_e32 v105, 0x800, v112
	v_or_b32_e32 v106, 0xc00, v112
	v_or_b32_e32 v107, 0x1000, v112
	s_waitcnt lgkmcnt(1)
	v_mfma_f32_32x32x16_bf16 v[24:39], v[108:111], v[76:79], v[24:39]
	ds_read_b128 v[76:79], v217 offset:17280
	ds_read_b128 v[100:103], v217 offset:416
	s_waitcnt lgkmcnt(2)
	v_mfma_f32_32x32x16_bf16 v[8:23], v[80:83], v[2:5], v[8:23]
	ds_read_b128 v[80:83], v217 offset:17312
	s_waitcnt lgkmcnt(2)
	v_mfma_f32_32x32x16_bf16 v[24:39], v[76:79], v[2:5], v[24:39]
	ds_read_b128 v[76:79], v217 offset:448
	v_mov_b32_e32 v2, v0
	v_mov_b32_e32 v3, v0
	v_mov_b32_e32 v4, v0
	v_mov_b32_e32 v5, v0
	s_waitcnt lgkmcnt(2)
	v_mfma_f32_32x32x16_bf16 v[8:23], v[100:103], v[72:75], v[8:23]
	s_waitcnt lgkmcnt(1)
	v_mfma_f32_32x32x16_bf16 v[24:39], v[80:83], v[72:75], v[24:39]
	ds_read_b128 v[72:75], v217 offset:17344
	ds_read_b128 v[80:83], v217 offset:480
	s_waitcnt lgkmcnt(2)
	v_mfma_f32_32x32x16_bf16 v[8:23], v[76:79], v[68:71], v[8:23]
	ds_read_b128 v[76:79], v217 offset:17376
	s_waitcnt lgkmcnt(2)
	v_mfma_f32_32x32x16_bf16 v[24:39], v[72:75], v[68:71], v[24:39]
	s_waitcnt lgkmcnt(1)
	v_mfma_f32_32x32x16_bf16 v[8:23], v[80:83], v[64:67], v[8:23]
	s_waitcnt lgkmcnt(0)
; #define LAS __attribute__((address_space(3)))
; DI unsigned cvt_pk_bf16(float lo, float hi) { unsigned r; asm volatile("v_cvt_pk_bf16_f32 %0, %1, %2" : "=v"(r) : "v"(lo), "v"(hi)); return r; }
; DI float bf_lo(unsigned w) { return __uint_as_float(w << 16); }
; DI float bf_hi(unsigned w) { return __uint_as_float(w & 0xffff0000u); }
; #define MFMA32(a, b, c) __builtin_amdgcn_mfma_f32_32x32x16_bf16((a), (b), (c), 0, 0, 0)
; template <bool XW, int PASS, bool RMW> ...
;     ...
;         for (int s = 0; s < 16; ++s) qf[s] = ldg16(qr, qoff0 + (unsigned)cn * 262144u + 1024u * s);
;         const float qe = cc > 0 ? qd : 0.f;
; #pragma unroll
;         for (int gq = 0; gq < 4; ++gq) {
;           u32x2 a; a.x = cvt_pk_bf16(bf_lo(ovn[gq].x) + qe * yc0[4 * gq], bf_hi(ovn[gq].x) + qe * yc0[4 * gq + 1]); a.y = cvt_pk_bf16(bf_lo(ovn[gq].y) + qe * yc0[4 * gq + 2], bf_hi(ovn[gq].y) + qe * yc0[4 * gq + 3]);
;           *(u32x2*)((char*)y + (yb + 16u * gq)) = a;
;           u32x2 c2; c2.x = cvt_pk_bf16(bf_lo(ovn[4 + gq].x) + qe * yc1[4 * gq], bf_hi(ovn[4 + gq].x) + qe * yc1[4 * gq + 1]); c2.y = cvt_pk_bf16(bf_lo(ovn[4 + gq].y) + qe * yc1[4 * gq + 2], bf_hi(ovn[4 + gq].y) + qe * yc1[4 * gq + 3]);
;           *(u32x2*)((char*)y + (yb + 64u + 16u * gq)) = c2;
;         }
;         if constexpr (PASS == 1 && RMW) {
;           const unsigned ybn = yoff0 + (unsigned)cn * 524288u;
; #pragma unroll
;           for (int gq = 0; gq < 8; ++gq) ovn[gq] = *(const u32x2*)((const char*)y + (ybn + 64u * (gq >> 2) + 16u * (gq & 3)));
;         }
;       }
; #pragma unroll
;       for (int i = 0; i < 16; ++i) { st0[i] *= cd; st1[i] *= cd; }
; #pragma unroll
;       for (int sb = 0; sb < 2; ++sb) {
;         bf16x8 a0[4], a1[4];
; #pragma unroll
;         for (int k = 0; k < 4; ++k) { a0[k] = *(const LAS bf16x8*)(vimg + (cc & 1) * 16384 + (4 * sb + k) * 1024 + lane * 16); a1[k] = *(const LAS bf16x8*)(vimg + (cc & 1) * 16384 + 8192 + (4 * sb + k) * 1024 + lane * 16); }
; #pragma unroll
;         for (int k = 0; k < 4; ++k) { st0 = MFMA32(a0[k], kb0[4 * sb + k], st0); st1 = MFMA32(a1[k], kb0[4 * sb + k], st1); }
;         asm volatile("" : "+v"(st0), "+v"(st1) :: "memory");
; #pragma unroll
;         for (int k = 0; k < 4; ++k) kb0[4 * sb + k] = ldg16(kT, kboff0 + (unsigned)cn * 262144u + 1024u * (4 * sb + k));
	v_mfma_f32_32x32x16_bf16 v[24:39], v[76:79], v[64:67], v[24:39]
	global_load_dwordx4 v[120:123], v112, s[92:93]
	global_load_dwordx4 v[124:127], v104, s[92:93]
	s_nop 0
	global_load_dwordx4 v[112:115], v105, s[92:93]
	global_load_dwordx4 v[116:119], v106, s[92:93]
	s_nop 0
	global_load_dwordx4 v[104:107], v107, s[92:93]
	s_nop 0
	global_load_dwordx4 v[108:111], v151, s[92:93]
	global_load_dwordx4 v[96:99], v152, s[92:93]
	global_load_dwordx4 v[100:103], v153, s[92:93]
	global_load_dwordx4 v[88:91], v154, s[92:93]
	global_load_dwordx4 v[92:95], v155, s[92:93]
	global_load_dwordx4 v[80:83], v156, s[92:93]
	global_load_dwordx4 v[84:87], v157, s[92:93]
	global_load_dwordx4 v[72:75], v158, s[92:93]
	global_load_dwordx4 v[76:79], v159, s[92:93]
	global_load_dwordx4 v[64:67], v160, s[92:93]
	global_load_dwordx4 v[68:71], v161, s[92:93]
	v_fmac_f32_e32 v162, 0, v8
	v_fmac_f32_e32 v163, 0, v9
	v_fmac_f32_e32 v164, 0, v10
	v_fmac_f32_e32 v165, 0, v11
	v_cvt_pk_bf16_f32 v8, v162, v163
	v_cvt_pk_bf16_f32 v9, v164, v165
	v_fmac_f32_e32 v166, 0, v24
	v_fmac_f32_e32 v167, 0, v25
	v_fmac_f32_e32 v169, 0, v26
	v_fmac_f32_e32 v170, 0, v27
	global_store_dwordx2 v7, v[8:9], s[18:19]
	v_cvt_pk_bf16_f32 v8, v166, v167
	v_cvt_pk_bf16_f32 v9, v169, v170
	v_fmac_f32_e32 v171, 0, v12
	v_fmac_f32_e32 v172, 0, v13
	v_fmac_f32_e32 v173, 0, v14
	v_fmac_f32_e32 v174, 0, v15
	global_store_dwordx2 v150, v[8:9], s[18:19]
	v_cvt_pk_bf16_f32 v8, v171, v172
	v_cvt_pk_bf16_f32 v9, v173, v174
	v_fmac_f32_e32 v175, 0, v28
	v_fmac_f32_e32 v178, 0, v29
	v_fmac_f32_e32 v179, 0, v30
	v_fmac_f32_e32 v180, 0, v31
	global_store_dwordx2 v148, v[8:9], s[18:19]
	v_cvt_pk_bf16_f32 v8, v175, v178
	v_cvt_pk_bf16_f32 v9, v179, v180
	v_fmac_f32_e32 v181, 0, v16
	v_fmac_f32_e32 v184, 0, v17
	v_fmac_f32_e32 v185, 0, v18
	v_fmac_f32_e32 v186, 0, v19
	global_store_dwordx2 v149, v[8:9], s[18:19]
	v_cvt_pk_bf16_f32 v8, v181, v184
	v_cvt_pk_bf16_f32 v9, v185, v186
	v_fmac_f32_e32 v187, 0, v32
	v_fmac_f32_e32 v188, 0, v33
	v_fmac_f32_e32 v189, 0, v34
	v_fmac_f32_e32 v204, 0, v35
	global_store_dwordx2 v146, v[8:9], s[18:19]
	v_cvt_pk_bf16_f32 v8, v187, v188
	v_cvt_pk_bf16_f32 v9, v189, v204
	v_fmac_f32_e32 v205, 0, v20
	v_fmac_f32_e32 v206, 0, v21
	v_fmac_f32_e32 v207, 0, v22
	v_fmac_f32_e32 v208, 0, v23
	v_fmac_f32_e32 v209, 0, v36
	v_fmac_f32_e32 v210, 0, v37
	v_fmac_f32_e32 v211, 0, v38
	v_fmac_f32_e32 v215, 0, v39
	global_store_dwordx2 v147, v[8:9], s[18:19]
	v_cvt_pk_bf16_f32 v8, v205, v206
	v_cvt_pk_bf16_f32 v9, v207, v208
	global_store_dwordx2 v145, v[8:9], s[18:19]
	v_cvt_pk_bf16_f32 v150, v209, v210
	v_cvt_pk_bf16_f32 v151, v211, v215
	ds_read_b128 v[32:35], v231
	ds_read_b128 v[36:39], v231 offset:1024
	v_mov_b32_e32 v7, v0
	v_mov_b32_e32 v8, v0
	v_mov_b32_e32 v9, v0
	v_mov_b32_e32 v10, v0
	v_mov_b32_e32 v11, v0
	v_mov_b32_e32 v12, v0
	v_mov_b32_e32 v13, v0
	v_mov_b32_e32 v14, v0
	v_mov_b32_e32 v15, v0
	s_waitcnt vmcnt(24)
	v_lshlrev_b32_e32 v160, 16, v52
	v_and_b32_e32 v52, 0xffff0000, v52
	s_waitcnt lgkmcnt(1)
	v_mfma_f32_32x32x16_bf16 v[16:31], v[32:35], v[132:135], v[0:15]
	ds_read_b128 v[32:35], v230
	ds_read_b128 v[146:149], v230 offset:1024
	v_lshlrev_b32_e32 v161, 16, v53
	v_and_b32_e32 v53, 0xffff0000, v53
	s_waitcnt lgkmcnt(2)
	v_mfma_f32_32x32x16_bf16 v[16:31], v[36:39], v[140:143], v[16:31]
	s_waitcnt lgkmcnt(1)
	v_mfma_f32_32x32x16_bf16 v[0:15], v[32:35], v[132:135], v[0:15]
	ds_read_b128 v[32:35], v231 offset:2048
	ds_read_b128 v[36:39], v231 offset:3072
	ds_read_b128 v[132:135], v230 offset:3072
	global_store_dwordx2 v144, v[150:151], s[18:19]
	s_waitcnt lgkmcnt(2)
	v_mfma_f32_32x32x16_bf16 v[16:31], v[32:35], v[136:139], v[16:31]
	ds_read_b128 v[32:35], v230 offset:2048
	v_mfma_f32_32x32x16_bf16 v[0:15], v[146:149], v[140:143], v[0:15]
	v_add_u32_e32 v140, s24, v227
	v_or_b32_e32 v141, 16, v140
	s_waitcnt lgkmcnt(0)
	v_mfma_f32_32x32x16_bf16 v[0:15], v[32:35], v[136:139], v[0:15]
	v_or_b32_e32 v32, 32, v140
	v_or_b32_e32 v33, 48, v140
	global_load_dwordx2 v[188:189], v140, s[18:19]
	global_load_dwordx2 v[184:185], v141, s[18:19]
	global_load_dwordx2 v[178:179], v32, s[18:19]
	global_load_dwordx2 v[172:173], v33, s[18:19]
	v_or_b32_e32 v32, 64, v140
	v_or_b32_e32 v33, 0x50, v140
	v_or_b32_e32 v34, 0x60, v140
	v_or_b32_e32 v35, 0x70, v140
	v_mfma_f32_32x32x16_bf16 v[16:31], v[36:39], v[128:131], v[16:31]
	global_load_dwordx2 v[186:187], v32, s[18:19]
	global_load_dwordx2 v[180:181], v33, s[18:19]
	global_load_dwordx2 v[174:175], v34, s[18:19]
	global_load_dwordx2 v[170:171], v35, s[18:19]
	v_mfma_f32_32x32x16_bf16 v[0:15], v[132:135], v[128:131], v[0:15]
	ds_read_b128 v[32:35], v231 offset:4096
	ds_read_b128 v[36:39], v231 offset:5120
	s_waitcnt lgkmcnt(1)
	v_mfma_f32_32x32x16_bf16 v[16:31], v[32:35], v[60:63], v[16:31]
	ds_read_b128 v[32:35], v230 offset:4096
	ds_read_b128 v[128:131], v230 offset:5120
	s_waitcnt lgkmcnt(2)
	v_mfma_f32_32x32x16_bf16 v[16:31], v[36:39], v[56:59], v[16:31]
	s_waitcnt lgkmcnt(1)
; #define LAS __attribute__((address_space(3)))
; DI unsigned cvt_pk_bf16(float lo, float hi) { unsigned r; asm volatile("v_cvt_pk_bf16_f32 %0, %1, %2" : "=v"(r) : "v"(lo), "v"(hi)); return r; }
; #define MFMA32(a, b, c) __builtin_amdgcn_mfma_f32_32x32x16_bf16((a), (b), (c), 0, 0, 0)
; template <bool XW, int PASS, bool RMW> ...
;     ...
;         for (int k = 0; k < 4; ++k) { a0[k] = *(const LAS bf16x8*)(vimg + (cc & 1) * 16384 + (4 * sb + k) * 1024 + lane * 16); a1[k] = *(const LAS bf16x8*)(vimg + (cc & 1) * 16384 + 8192 + (4 * sb + k) * 1024 + lane * 16); }
; #pragma unroll
;         for (int k = 0; k < 4; ++k) { st0 = MFMA32(a0[k], kb0[4 * sb + k], st0); st1 = MFMA32(a1[k], kb0[4 * sb + k], st1); }
;         asm volatile("" : "+v"(st0), "+v"(st1) :: "memory");
; #pragma unroll
;         for (int k = 0; k < 4; ++k) kb0[4 * sb + k] = ldg16(kT, kboff0 + (unsigned)cn * 262144u + 1024u * (4 * sb + k));
;       }
; #pragma unroll
;       for (int t = 0; t < 2; ++t) {
;         const int sv = 2 * dq + t;
;         *(LAS bf16x8*)(vimg + ((cc + 1) & 1) * 16384 + et * 8192 + sv * 1024 + lane * 16) = scale_tab(vr[t], kdec + 16 * sv + 8 * h);
;         vr[t] = ldg16(vT, vaoff0 + (unsigned)cnn * 524288u + 1024u * sv);
;       }
;       LAS bf16_t* sw = Sb + (pbuf ^ 1) * SBE + (4 * h) * 264 + 32 * w + r;
; #pragma unroll
;       for (int i = 0; i < 16; ++i) {
;         const int eo = ((i & 3) + 8 * (i >> 2)) * 264;
;         const unsigned pkw = cvt_pk_bf16(st0[i], st1[i]);
;         sw[eo] = (bf16_t)(pkw & 0xffffu);
;         sw[eo + 32 * 264] = (bf16_t)(pkw >> 16);
;       }
;       lds_barrier();
;       pbuf ^= 1;
;     }
	v_mfma_f32_32x32x16_bf16 v[0:15], v[32:35], v[60:63], v[0:15]
	ds_read_b128 v[32:35], v231 offset:6144
	ds_read_b128 v[36:39], v231 offset:7168
	v_add_u32_e32 v60, s23, v223
	v_or_b32_e32 v62, 0x400, v60
	v_or_b32_e32 v63, 0x800, v60
	v_add_u32_e32 v61, s25, v224
	v_add3_u32 v231, v222, v203, s2
	s_mov_b32 s2, 1
	s_waitcnt lgkmcnt(1)
	v_mfma_f32_32x32x16_bf16 v[16:31], v[32:35], v[44:47], v[16:31]
	ds_read_b128 v[32:35], v230 offset:6144
	v_mfma_f32_32x32x16_bf16 v[0:15], v[128:131], v[56:59], v[0:15]
	ds_read_b128 v[56:59], v230 offset:7168
	s_waitcnt lgkmcnt(1)
	v_mfma_f32_32x32x16_bf16 v[0:15], v[32:35], v[44:47], v[0:15]
	v_or_b32_e32 v32, 0xc00, v60
	global_load_dwordx4 v[128:131], v60, s[14:15]
	global_load_dwordx4 v[132:135], v62, s[14:15]
	global_load_dwordx4 v[136:139], v63, s[14:15]
	global_load_dwordx4 v[140:143], v32, s[14:15]
	v_or_b32_e32 v44, 0x1000, v60
	v_or_b32_e32 v45, 0x1400, v60
	v_or_b32_e32 v46, 0x1800, v60
	v_or_b32_e32 v47, 0x1c00, v60
	v_lshlrev_b32_e32 v60, 16, v54
	v_mfma_f32_32x32x16_bf16 v[16:31], v[36:39], v[40:43], v[16:31]
	s_waitcnt lgkmcnt(0)
	v_mfma_f32_32x32x16_bf16 v[0:15], v[56:59], v[40:43], v[0:15]
	ds_read_b128 v[32:35], v228
	global_load_dwordx4 v[144:147], v44, s[14:15]
	global_load_dwordx4 v[148:151], v45, s[14:15]
	global_load_dwordx4 v[152:155], v46, s[14:15]
	global_load_dwordx4 v[156:159], v47, s[14:15]
	ds_read_b128 v[36:39], v228 offset:16
	s_waitcnt vmcnt(40)
	v_lshlrev_b32_e32 v40, 16, v48
	s_waitcnt lgkmcnt(1)
	v_mul_f32_e32 v32, v32, v160
	v_mul_f32_e32 v33, v33, v52
	v_mul_f32_e32 v35, v35, v53
	v_mul_f32_e32 v34, v34, v161
	v_cvt_pk_bf16_f32 v32, v32, v33
	v_cvt_pk_bf16_f32 v33, v34, v35
	v_and_b32_e32 v35, 0xffff0000, v54
	s_waitcnt lgkmcnt(0)
	v_mul_f32_e32 v34, v36, v60
	v_mul_f32_e32 v35, v37, v35
	v_cvt_pk_bf16_f32 v34, v34, v35
	v_lshlrev_b32_e32 v35, 16, v55
	v_mul_f32_e32 v35, v38, v35
	v_and_b32_e32 v36, 0xffff0000, v55
	v_mul_f32_e32 v36, v39, v36
	v_cvt_pk_bf16_f32 v35, v35, v36
	ds_write_b128 v183, v[32:35] offset:16384
	ds_read_b128 v[32:35], v229
	v_or_b32_e32 v36, s3, v61
	global_load_dwordx4 v[160:163], v36, s[16:17]
	ds_read_b128 v[36:39], v229 offset:16
	v_mov_b32_e32 v183, v168
	s_waitcnt lgkmcnt(1)
	v_mul_f32_e32 v32, v32, v40
	v_and_b32_e32 v40, 0xffff0000, v48
	v_mul_f32_e32 v33, v33, v40
	v_cvt_pk_bf16_f32 v32, v32, v33
	v_lshlrev_b32_e32 v33, 16, v49
	v_mul_f32_e32 v33, v34, v33
	v_and_b32_e32 v34, 0xffff0000, v49
	v_mul_f32_e32 v34, v35, v34
	v_cvt_pk_bf16_f32 v33, v33, v34
	v_lshlrev_b32_e32 v34, 16, v50
	v_and_b32_e32 v35, 0xffff0000, v50
	s_waitcnt lgkmcnt(0)
	v_mul_f32_e32 v34, v36, v34
	v_mul_f32_e32 v35, v37, v35
	v_cvt_pk_bf16_f32 v34, v34, v35
	v_lshlrev_b32_e32 v35, 16, v51
	v_and_b32_e32 v36, 0xffff0000, v51
	v_mul_f32_e32 v35, v38, v35
	v_mul_f32_e32 v36, v39, v36
	v_cvt_pk_bf16_f32 v35, v35, v36
	v_or_b32_e32 v36, s33, v61
	global_load_dwordx4 v[164:167], v36, s[16:17]
	ds_write_b128 v182, v[32:35] offset:16384
	v_cvt_pk_bf16_f32 v32, v16, v0
	ds_write_b16 v199, v32 offset:33792
	ds_write_b16_d16_hi v199, v32 offset:50688
	v_cvt_pk_bf16_f32 v32, v17, v1
	ds_write_b16 v199, v32 offset:34320
	ds_write_b16_d16_hi v199, v32 offset:51216
	v_cvt_pk_bf16_f32 v32, v18, v2
	ds_write_b16 v199, v32 offset:34848
	ds_write_b16_d16_hi v199, v32 offset:51744
	v_cvt_pk_bf16_f32 v32, v19, v3
	ds_write_b16 v199, v32 offset:35376
	ds_write_b16_d16_hi v199, v32 offset:52272
	v_cvt_pk_bf16_f32 v32, v20, v4
	ds_write_b16 v199, v32 offset:38016
	ds_write_b16_d16_hi v199, v32 offset:54912
	v_cvt_pk_bf16_f32 v32, v21, v5
	ds_write_b16 v199, v32 offset:38544
	ds_write_b16_d16_hi v199, v32 offset:55440
	v_cvt_pk_bf16_f32 v32, v22, v6
	ds_write_b16 v199, v32 offset:39072
	ds_write_b16_d16_hi v199, v32 offset:55968
	v_cvt_pk_bf16_f32 v32, v23, v7
	ds_write_b16 v199, v32 offset:39600
	ds_write_b16_d16_hi v199, v32 offset:56496
	v_cvt_pk_bf16_f32 v32, v24, v8
	ds_write_b16 v199, v32 offset:42240
	ds_write_b16_d16_hi v199, v32 offset:59136
	v_cvt_pk_bf16_f32 v32, v25, v9
	ds_write_b16 v199, v32 offset:42768
	ds_write_b16_d16_hi v199, v32 offset:59664
	v_cvt_pk_bf16_f32 v32, v26, v10
	ds_write_b16 v199, v32 offset:43296
	ds_write_b16_d16_hi v199, v32 offset:60192
	v_cvt_pk_bf16_f32 v32, v27, v11
	ds_write_b16 v199, v32 offset:43824
	ds_write_b16_d16_hi v199, v32 offset:60720
	v_cvt_pk_bf16_f32 v32, v28, v12
	ds_write_b16 v199, v32 offset:46464
	ds_write_b16_d16_hi v199, v32 offset:63360
	v_cvt_pk_bf16_f32 v32, v29, v13
	ds_write_b16 v199, v32 offset:46992
	ds_write_b16_d16_hi v199, v32 offset:63888
	v_cvt_pk_bf16_f32 v32, v30, v14
	v_mul_f32_e64 v36, v219, -v225
	ds_write_b16 v199, v32 offset:47520
	ds_write_b16_d16_hi v199, v32 offset:64416
	v_cvt_pk_bf16_f32 v32, v31, v15
	v_exp_f32_e32 v230, v36
	ds_write_b16 v199, v32 offset:48048
	ds_write_b16_d16_hi v199, v32 offset:64944
	s_waitcnt lgkmcnt(0)
	s_barrier
	v_mov_b32_e32 v182, v168
	s_mov_b32 s101, 0
	s_setprio 1

; #define LAS __attribute__((address_space(3)))
; #define MFMA32(a, b, c) __builtin_amdgcn_mfma_f32_32x32x16_bf16((a), (b), (c), 0, 0, 0)
; template <bool XW, int PASS, bool RMW> ...
;     ...
;     for (int cc = 0; cc < nc; ++cc) {
;       const int c = pass == 0 ? cc : nc - 1 - cc;
;       const int k1 = cc + 1 < nc ? cc + 1 : nc - 1, k2 = cc + 2 < nc ? cc + 2 : nc - 1;
;       const int cn = pass == 0 ? k1 : nc - 1 - k1, cnn = pass == 0 ? k2 : nc - 1 - k2;
;       if constexpr (XW) {
;         const unsigned yb = yoff0 + (unsigned)c * 524288u;
;         f32x16 yc0, yc1;
; #pragma unroll
;         for (int i = 0; i < 16; ++i) { yc0[i] = 0.f; yc1[i] = 0.f; }
;         const LAS bf16_t* sp = Sb + pbuf * SBE + r * 264 + 8 * h;
; #pragma unroll
;         for (int sb = 0; sb < 8; ++sb) {
;           bf16x8 a0[2], a1[2];
; #pragma unroll
;           for (int k = 0; k < 2; ++k) { a0[k] = *(const LAS bf16x8*)(sp + 16 * (2 * sb + k)); a1[k] = *(const LAS bf16x8*)(sp + 32 * 264 + 16 * (2 * sb + k)); }
; #pragma unroll
;           for (int k = 0; k < 2; ++k) { yc0 = MFMA32(a0[k], qf[2 * sb + k], yc0); yc1 = MFMA32(a1[k], qf[2 * sb + k], yc1); }
;         }
;         asm volatile("" : "+v"(yc0), "+v"(yc1) :: "memory");
.Lrmw_skip:
	s_add_i32 s8, s2, 1
	v_mov_b32_e32 v32, s8
	s_add_i32 s2, s2, 2
	v_sub_u32_e64 v169, s5, v32 clamp
	v_mov_b32_e32 v32, s2
	s_mul_i32 s2, s0, 0x8400
	v_add_u32_e32 v204, s2, v217
	v_sub_u32_e64 v203, s5, v32 clamp
	ds_read_b128 v[232:235], v204
	ds_read_b128 v[236:239], v204 offset:16896
	ds_read_b128 v[240:243], v204 offset:32
	ds_read_b128 v[244:247], v204 offset:16928
	ds_read_b128 v[248:251], v204 offset:64
	s_waitcnt vmcnt(33)
	s_waitcnt lgkmcnt(4)
	v_mfma_f32_32x32x16_bf16 v[48:63], v[232:235], v[120:123], 0
	ds_read_b128 v[232:235], v204 offset:16960
	v_lshlrev_b32_e32 v206, 18, v169
	s_waitcnt vmcnt(10)
	v_lshlrev_b32_e32 v205, 16, v188
	s_and_b32 s2, s1, 0x4000
	v_mul_f32_e64 v16, v182, v16
	v_mul_f32_e64 v17, v183, v17
	v_pk_mul_f32 v[0:1], v[182:183], v[0:1]
	s_addk_i32 s1, 0x4000
	s_xor_b32 s0, s0, 1
	s_waitcnt lgkmcnt(4)
	v_mfma_f32_32x32x16_bf16 v[32:47], v[236:239], v[120:123], 0
	ds_read_b128 v[236:239], v204 offset:96
	ds_read_b128 v[120:123], v204 offset:16992
	s_waitcnt lgkmcnt(5)
	v_mfma_f32_32x32x16_bf16 v[48:63], v[240:243], v[124:127], v[48:63]
	ds_read_b128 v[240:243], v204 offset:128
	s_waitcnt lgkmcnt(5)
	v_mfma_f32_32x32x16_bf16 v[32:47], v[244:247], v[124:127], v[32:47]
	ds_read_b128 v[244:247], v204 offset:17024
	ds_read_b128 v[124:127], v204 offset:160
	s_waitcnt lgkmcnt(6)
	v_mfma_f32_32x32x16_bf16 v[48:63], v[248:251], v[112:115], v[48:63]
	ds_read_b128 v[248:251], v204 offset:17056
	s_waitcnt lgkmcnt(6)
	v_mfma_f32_32x32x16_bf16 v[32:47], v[232:235], v[112:115], v[32:47]
	ds_read_b128 v[232:235], v204 offset:192
	ds_read_b128 v[112:115], v204 offset:17088
	s_waitcnt lgkmcnt(7)
	v_mfma_f32_32x32x16_bf16 v[48:63], v[236:239], v[116:119], v[48:63]
	ds_read_b128 v[236:239], v204 offset:224
	s_waitcnt lgkmcnt(7)
	v_mfma_f32_32x32x16_bf16 v[32:47], v[120:123], v[116:119], v[32:47]
	ds_read_b128 v[120:123], v204 offset:17120
	s_waitcnt lgkmcnt(7)
	v_mfma_f32_32x32x16_bf16 v[48:63], v[240:243], v[104:107], v[48:63]
	ds_read_b128 v[240:243], v204 offset:256
	s_waitcnt lgkmcnt(7)
	v_mfma_f32_32x32x16_bf16 v[32:47], v[244:247], v[104:107], v[32:47]
	ds_read_b128 v[244:247], v204 offset:17152
	s_waitcnt lgkmcnt(7)
	v_mfma_f32_32x32x16_bf16 v[48:63], v[124:127], v[108:111], v[48:63]
	ds_read_b128 v[124:127], v204 offset:288
	s_waitcnt lgkmcnt(7)
	v_mfma_f32_32x32x16_bf16 v[32:47], v[248:251], v[108:111], v[32:47]
	ds_read_b128 v[248:251], v204 offset:17184
	s_waitcnt lgkmcnt(7)
	v_mfma_f32_32x32x16_bf16 v[48:63], v[232:235], v[96:99], v[48:63]
	ds_read_b128 v[232:235], v204 offset:320
	s_waitcnt lgkmcnt(7)
	v_mfma_f32_32x32x16_bf16 v[32:47], v[112:115], v[96:99], v[32:47]
	ds_read_b128 v[112:115], v204 offset:17216
	s_waitcnt lgkmcnt(7)
	v_mfma_f32_32x32x16_bf16 v[48:63], v[236:239], v[100:103], v[48:63]
	ds_read_b128 v[236:239], v204 offset:352
	s_waitcnt lgkmcnt(7)
	v_mfma_f32_32x32x16_bf16 v[32:47], v[120:123], v[100:103], v[32:47]
	ds_read_b128 v[120:123], v204 offset:17248
	s_waitcnt lgkmcnt(7)
	v_mfma_f32_32x32x16_bf16 v[48:63], v[240:243], v[88:91], v[48:63]
	ds_read_b128 v[240:243], v204 offset:384
	s_waitcnt lgkmcnt(7)
	v_mfma_f32_32x32x16_bf16 v[32:47], v[244:247], v[88:91], v[32:47]
	ds_read_b128 v[244:247], v204 offset:17280
	s_waitcnt lgkmcnt(7)
	v_mfma_f32_32x32x16_bf16 v[48:63], v[124:127], v[92:95], v[48:63]
	ds_read_b128 v[124:127], v204 offset:416
	s_waitcnt lgkmcnt(7)
	v_mfma_f32_32x32x16_bf16 v[32:47], v[248:251], v[92:95], v[32:47]
	ds_read_b128 v[248:251], v204 offset:17312
	s_waitcnt lgkmcnt(7)
	v_mfma_f32_32x32x16_bf16 v[48:63], v[232:235], v[80:83], v[48:63]
	ds_read_b128 v[232:235], v204 offset:448
	s_waitcnt lgkmcnt(7)
	v_mfma_f32_32x32x16_bf16 v[32:47], v[112:115], v[80:83], v[32:47]
	ds_read_b128 v[112:115], v204 offset:17344
	s_waitcnt lgkmcnt(7)
	v_mfma_f32_32x32x16_bf16 v[48:63], v[236:239], v[84:87], v[48:63]
	ds_read_b128 v[236:239], v204 offset:480
	s_waitcnt lgkmcnt(7)
	v_mfma_f32_32x32x16_bf16 v[32:47], v[120:123], v[84:87], v[32:47]
	ds_read_b128 v[120:123], v204 offset:17376
	s_waitcnt lgkmcnt(7)
	v_mfma_f32_32x32x16_bf16 v[48:63], v[240:243], v[72:75], v[48:63]
	s_waitcnt lgkmcnt(6)
	v_mfma_f32_32x32x16_bf16 v[32:47], v[244:247], v[72:75], v[32:47]
	s_waitcnt lgkmcnt(5)
	v_mfma_f32_32x32x16_bf16 v[48:63], v[124:127], v[76:79], v[48:63]
	s_waitcnt lgkmcnt(4)
	v_mfma_f32_32x32x16_bf16 v[32:47], v[248:251], v[76:79], v[32:47]
	v_add_u32_e32 v204, 64, v231
	s_waitcnt lgkmcnt(3)
	v_mfma_f32_32x32x16_bf16 v[48:63], v[232:235], v[64:67], v[48:63]
	s_waitcnt lgkmcnt(2)
	v_mfma_f32_32x32x16_bf16 v[32:47], v[112:115], v[64:67], v[32:47]
	s_waitcnt lgkmcnt(1)
	v_mfma_f32_32x32x16_bf16 v[48:63], v[236:239], v[68:71], v[48:63]
	s_waitcnt lgkmcnt(0)
; DI unsigned cvt_pk_bf16(float lo, float hi) { unsigned r; asm volatile("v_cvt_pk_bf16_f32 %0, %1, %2" : "=v"(r) : "v"(lo), "v"(hi)); return r; }
; DI float bf_lo(unsigned w) { return __uint_as_float(w << 16); }
; DI float bf_hi(unsigned w) { return __uint_as_float(w & 0xffff0000u); }
; template <bool XW, int PASS, bool RMW> ...
;     ...
;         for (int s = 0; s < 16; ++s) qf[s] = ldg16(qr, qoff0 + (unsigned)cn * 262144u + 1024u * s);
;         const float qe = cc > 0 ? qd : 0.f;
; #pragma unroll
;         for (int gq = 0; gq < 4; ++gq) {
;           u32x2 a; a.x = cvt_pk_bf16(bf_lo(ovn[gq].x) + qe * yc0[4 * gq], bf_hi(ovn[gq].x) + qe * yc0[4 * gq + 1]); a.y = cvt_pk_bf16(bf_lo(ovn[gq].y) + qe * yc0[4 * gq + 2], bf_hi(ovn[gq].y) + qe * yc0[4 * gq + 3]);
;           *(u32x2*)((char*)y + (yb + 16u * gq)) = a;
;           u32x2 c2; c2.x = cvt_pk_bf16(bf_lo(ovn[4 + gq].x) + qe * yc1[4 * gq], bf_hi(ovn[4 + gq].x) + qe * yc1[4 * gq + 1]); c2.y = cvt_pk_bf16(bf_lo(ovn[4 + gq].y) + qe * yc1[4 * gq + 2], bf_hi(ovn[4 + gq].y) + qe * yc1[4 * gq + 3]);
;           *(u32x2*)((char*)y + (yb + 64u + 16u * gq)) = c2;
;         }
	v_mfma_f32_32x32x16_bf16 v[32:47], v[120:123], v[68:71], v[32:47]
	v_add_u32_e32 v68, v206, v226
	v_or_b32_e32 v64, 0x400, v68
	global_load_dwordx4 v[120:123], v68, s[92:93]
	global_load_dwordx4 v[124:127], v64, s[92:93]
	v_or_b32_e32 v64, 0x800, v68
	global_load_dwordx4 v[112:115], v64, s[92:93]
	v_or_b32_e32 v64, 0xc00, v68
	global_load_dwordx4 v[116:119], v64, s[92:93]
	v_or_b32_e32 v64, 0x1000, v68
	global_load_dwordx4 v[104:107], v64, s[92:93]
	v_or_b32_e32 v64, 0x1400, v68
	global_load_dwordx4 v[108:111], v64, s[92:93]
	v_or_b32_e32 v64, 0x1800, v68
	global_load_dwordx4 v[96:99], v64, s[92:93]
	v_or_b32_e32 v64, 0x1c00, v68
	global_load_dwordx4 v[100:103], v64, s[92:93]
	v_or_b32_e32 v64, 0x2000, v68
	global_load_dwordx4 v[88:91], v64, s[92:93]
	v_or_b32_e32 v64, 0x2400, v68
	global_load_dwordx4 v[92:95], v64, s[92:93]
	v_or_b32_e32 v64, 0x2800, v68
	global_load_dwordx4 v[80:83], v64, s[92:93]
	v_or_b32_e32 v64, 0x2c00, v68
	global_load_dwordx4 v[84:87], v64, s[92:93]
	v_or_b32_e32 v64, 0x3000, v68
	global_load_dwordx4 v[72:75], v64, s[92:93]
	v_or_b32_e32 v64, 0x3400, v68
	v_fmac_f32_e32 v205, v230, v48
	v_and_b32_e32 v48, 0xffff0000, v188
	global_load_dwordx4 v[76:79], v64, s[92:93]
	v_or_b32_e32 v64, 0x3800, v68
	v_or_b32_e32 v68, 0x3c00, v68
	v_fmac_f32_e32 v48, v230, v49
	v_lshlrev_b32_e32 v49, 16, v189
	global_load_dwordx4 v[64:67], v64, s[92:93]
	v_fmac_f32_e32 v49, v230, v50
	global_load_dwordx4 v[68:71], v68, s[92:93]
	v_cvt_pk_bf16_f32 v48, v205, v48
	v_and_b32_e32 v50, 0xffff0000, v189
	v_fmac_f32_e32 v50, v230, v51
	v_cvt_pk_bf16_f32 v49, v49, v50
	v_mbcnt_lo_u32_b32 v240, -1, 0
	v_mbcnt_hi_u32_b32 v240, -1, v240
	v_readlane_b32 s100, v255, 12
	v_and_b32_e32 v241, 31, v240
	v_lshrrev_b32_e32 v242, 5, v240
	v_lshrrev_b32_e32 v243, 3, v240
	v_and_b32_e32 v244, 7, v240
	v_mov_b32_e32 v245, s100
	v_mul_u32_u24_e32 v245, 0x44, v245
	v_add_u32_e32 v245, 0x1a000, v245
	v_mul_u32_u24_e32 v252, 0x88, v241
	v_lshl_add_u32 v252, v242, 3, v252
	v_add_u32_e32 v252, v245, v252
	v_mul_u32_u24_e32 v253, 0x88, v243
	v_lshl_add_u32 v253, v244, 4, v253
	v_add_u32_e32 v253, v245, v253
	v_sub_u32_e32 v207, v243, v241
	v_lshlrev_b32_e32 v207, 12, v207
	v_lshl_add_u32 v207, v244, 4, v207
	v_lshlrev_b32_e32 v242, 3, v242
	v_sub_u32_e32 v207, v207, v242
	v_add_u32_e32 v248, v231, v207
	v_add_u32_e32 v249, 0x8000, v248
	v_add_u32_e32 v250, 0x10000, v248
	v_add_u32_e32 v251, 0x18000, v248
	ds_write_b64 v252, v[48:49]
	s_waitcnt vmcnt(26)
	v_lshlrev_b32_e32 v48, 16, v186
	v_fmac_f32_e32 v48, v230, v32
	v_and_b32_e32 v32, 0xffff0000, v186
	v_fmac_f32_e32 v32, v230, v33
	v_lshlrev_b32_e32 v33, 16, v187
	v_fmac_f32_e32 v33, v230, v34
	v_and_b32_e32 v34, 0xffff0000, v187
	v_cvt_pk_bf16_f32 v32, v48, v32
	v_fmac_f32_e32 v34, v230, v35
	v_cvt_pk_bf16_f32 v33, v33, v34
	ds_write_b64 v252, v[32:33] offset:64
	v_lshlrev_b32_e32 v32, 16, v184
	v_and_b32_e32 v33, 0xffff0000, v184
	v_fmac_f32_e32 v32, v230, v52
	v_fmac_f32_e32 v33, v230, v53
	v_cvt_pk_bf16_f32 v32, v32, v33
	v_lshlrev_b32_e32 v33, 16, v185
	v_and_b32_e32 v34, 0xffff0000, v185
	v_fmac_f32_e32 v33, v230, v54
	v_fmac_f32_e32 v34, v230, v55
	v_cvt_pk_bf16_f32 v33, v33, v34
	v_add_u32_e32 v34, 16, v231
	ds_write_b64 v252, v[32:33] offset:16
	s_waitcnt vmcnt(26)
	v_lshlrev_b32_e32 v32, 16, v180
	v_and_b32_e32 v33, 0xffff0000, v180
	v_fmac_f32_e32 v32, v230, v36
	v_fmac_f32_e32 v33, v230, v37
	v_cvt_pk_bf16_f32 v32, v32, v33
	v_lshlrev_b32_e32 v33, 16, v181
	v_and_b32_e32 v34, 0xffff0000, v181
	v_fmac_f32_e32 v33, v230, v38
	v_fmac_f32_e32 v34, v230, v39
	v_cvt_pk_bf16_f32 v33, v33, v34
	v_add_u32_e32 v34, 0x50, v231
	ds_write_b64 v252, v[32:33] offset:80
	v_lshlrev_b32_e32 v32, 16, v178
	v_and_b32_e32 v33, 0xffff0000, v178
	v_fmac_f32_e32 v32, v230, v56
	v_fmac_f32_e32 v33, v230, v57
	v_cvt_pk_bf16_f32 v32, v32, v33
	v_lshlrev_b32_e32 v33, 16, v179
	v_and_b32_e32 v34, 0xffff0000, v179
	v_fmac_f32_e32 v33, v230, v58
	v_fmac_f32_e32 v34, v230, v59
	v_cvt_pk_bf16_f32 v33, v33, v34
	v_add_u32_e32 v34, 32, v231
	ds_write_b64 v252, v[32:33] offset:32
	s_waitcnt vmcnt(26)
	v_lshlrev_b32_e32 v32, 16, v174
	v_and_b32_e32 v33, 0xffff0000, v174
	v_fmac_f32_e32 v32, v230, v40
	v_fmac_f32_e32 v33, v230, v41
	v_cvt_pk_bf16_f32 v32, v32, v33
	v_lshlrev_b32_e32 v33, 16, v175
	v_and_b32_e32 v34, 0xffff0000, v175
	v_fmac_f32_e32 v33, v230, v42
	v_fmac_f32_e32 v34, v230, v43
	v_cvt_pk_bf16_f32 v33, v33, v34
	v_add_u32_e32 v34, 0x60, v231
	ds_write_b64 v252, v[32:33] offset:96
	v_lshlrev_b32_e32 v32, 16, v172
	v_and_b32_e32 v33, 0xffff0000, v172
	v_fmac_f32_e32 v32, v230, v60
	v_fmac_f32_e32 v33, v230, v61
	v_cvt_pk_bf16_f32 v32, v32, v33
	v_lshlrev_b32_e32 v33, 16, v173
	v_and_b32_e32 v34, 0xffff0000, v173
	v_fmac_f32_e32 v33, v230, v62
	v_fmac_f32_e32 v34, v230, v63
	v_cvt_pk_bf16_f32 v33, v33, v34
	v_add_u32_e32 v34, 48, v231
	ds_write_b64 v252, v[32:33] offset:48
	s_waitcnt vmcnt(26)
	v_lshlrev_b32_e32 v32, 16, v170
	v_and_b32_e32 v33, 0xffff0000, v170
	v_fmac_f32_e32 v32, v230, v44
	v_fmac_f32_e32 v33, v230, v45
	v_cvt_pk_bf16_f32 v32, v32, v33
	v_lshlrev_b32_e32 v33, 16, v171
	v_and_b32_e32 v34, 0xffff0000, v171
	v_fmac_f32_e32 v33, v230, v46
	v_fmac_f32_e32 v34, v230, v47
	v_cvt_pk_bf16_f32 v33, v33, v34
	v_add_u32_e32 v34, 0x70, v231
	ds_write_b64 v252, v[32:33] offset:112
	s_waitcnt lgkmcnt(0)
	ds_read_b128 v[232:235], v253
	ds_read_b128 v[236:239], v253 offset:1088
	ds_read_b128 v[240:243], v253 offset:2176
	ds_read_b128 v[244:247], v253 offset:3264
	s_waitcnt lgkmcnt(0)
; #define LAS __attribute__((address_space(3)))
; #define MFMA32(a, b, c) __builtin_amdgcn_mfma_f32_32x32x16_bf16((a), (b), (c), 0, 0, 0)
; template <bool XW, int PASS, bool RMW> ...
;     ...
;         if constexpr (PASS == 1 && RMW) {
;           const unsigned ybn = yoff0 + (unsigned)cn * 524288u;
; #pragma unroll
;           for (int gq = 0; gq < 8; ++gq) ovn[gq] = *(const u32x2*)((const char*)y + (ybn + 64u * (gq >> 2) + 16u * (gq & 3)));
;         }
;       }
; #pragma unroll
;       for (int i = 0; i < 16; ++i) { st0[i] *= cd; st1[i] *= cd; }
; #pragma unroll
;       for (int sb = 0; sb < 2; ++sb) {
;         bf16x8 a0[4], a1[4];
; #pragma unroll
;         for (int k = 0; k < 4; ++k) { a0[k] = *(const LAS bf16x8*)(vimg + (cc & 1) * 16384 + (4 * sb + k) * 1024 + lane * 16); a1[k] = *(const LAS bf16x8*)(vimg + (cc & 1) * 16384 + 8192 + (4 * sb + k) * 1024 + lane * 16); }
; #pragma unroll
;         for (int k = 0; k < 4; ++k) { st0 = MFMA32(a0[k], kb0[4 * sb + k], st0); st1 = MFMA32(a1[k], kb0[4 * sb + k], st1); }
;         asm volatile("" : "+v"(st0), "+v"(st1) :: "memory");
; #pragma unroll
;         for (int k = 0; k < 4; ++k) kb0[4 * sb + k] = ldg16(kT, kboff0 + (unsigned)cn * 262144u + 1024u * (4 * sb + k));
;       }
	global_store_dwordx4 v248, v[232:235], s[18:19]
	global_store_dwordx4 v249, v[236:239], s[18:19]
	global_store_dwordx4 v250, v[240:243], s[18:19]
	global_store_dwordx4 v251, v[244:247], s[18:19]
	s_nop 1
	v_lshl_add_u32 v32, v169, 19, v227
	v_or_b32_e32 v33, 16, v32
	v_add_u32_e32 v244, v32, v207
	global_load_dwordx4 v[172:175], v244, s[18:19]
	v_add_u32_e32 v245, 0x8000, v244
	global_load_dwordx4 v[184:187], v245, s[18:19]
	v_add_u32_e32 v246, 0x10000, v244
	global_load_dwordx4 v[178:181], v246, s[18:19]
	v_add_u32_e32 v247, 0x18000, v244
	global_load_dwordx4 v[208:211], v247, s[18:19]
	v_or_b32_e32 v33, 32, v32
	v_or_b32_e32 v33, 48, v32
	v_or_b32_e32 v33, 64, v32
	v_or_b32_e32 v33, 0x50, v32
	v_mov_b32_e32 v169, v168
	v_or_b32_e32 v33, 0x60, v32
	v_or_b32_e32 v32, 0x70, v32
	v_pk_mul_f32 v[30:31], v[168:169], v[30:31]
	v_pk_mul_f32 v[28:29], v[168:169], v[28:29]
	v_pk_mul_f32 v[26:27], v[168:169], v[26:27]
	v_pk_mul_f32 v[24:25], v[168:169], v[24:25]
	v_pk_mul_f32 v[22:23], v[168:169], v[22:23]
	v_pk_mul_f32 v[20:21], v[168:169], v[20:21]
	v_pk_mul_f32 v[18:19], v[168:169], v[18:19]
	v_pk_mul_f32 v[14:15], v[168:169], v[14:15]
	v_pk_mul_f32 v[12:13], v[168:169], v[12:13]
	v_pk_mul_f32 v[10:11], v[168:169], v[10:11]
	v_pk_mul_f32 v[8:9], v[168:169], v[8:9]
	v_pk_mul_f32 v[6:7], v[168:169], v[6:7]
	v_pk_mul_f32 v[4:5], v[168:169], v[4:5]
	v_pk_mul_f32 v[2:3], v[168:169], v[2:3]
	v_add_u32_e32 v169, s2, v218
	ds_read_b128 v[32:35], v169
	ds_read_b128 v[36:39], v169 offset:8192
	ds_read_b128 v[40:43], v169 offset:1024
	ds_read_b128 v[44:47], v169 offset:9216
	ds_read_b128 v[48:51], v169 offset:2048
	ds_read_b128 v[52:55], v169 offset:10240
	ds_read_b128 v[56:59], v169 offset:3072
	ds_read_b128 v[60:63], v169 offset:11264
	s_waitcnt vmcnt(33) lgkmcnt(7)
	v_mfma_f32_32x32x16_bf16 v[16:31], v[32:35], v[128:131], v[16:31]
	v_add_u32_e32 v204, v206, v223
	v_or_b32_e32 v32, 0x400, v204
	s_and_b32 s2, s1, 0x4000
	v_add_u32_e32 v231, 0xfff80000, v231
	s_cmp_eq_u32 s4, s8
	s_waitcnt lgkmcnt(6)
	v_mfma_f32_32x32x16_bf16 v[0:15], v[36:39], v[128:131], v[0:15]
	s_waitcnt vmcnt(32) lgkmcnt(5)
	v_mfma_f32_32x32x16_bf16 v[16:31], v[40:43], v[132:135], v[16:31]
	s_waitcnt lgkmcnt(4)
	v_mfma_f32_32x32x16_bf16 v[0:15], v[44:47], v[132:135], v[0:15]
	s_waitcnt vmcnt(31) lgkmcnt(3)
	v_mfma_f32_32x32x16_bf16 v[16:31], v[48:51], v[136:139], v[16:31]
	s_waitcnt lgkmcnt(2)
	v_mfma_f32_32x32x16_bf16 v[0:15], v[52:55], v[136:139], v[0:15]
	s_waitcnt vmcnt(30) lgkmcnt(1)
	v_mfma_f32_32x32x16_bf16 v[16:31], v[56:59], v[140:143], v[16:31]
	s_waitcnt lgkmcnt(0)
	v_mfma_f32_32x32x16_bf16 v[0:15], v[60:63], v[140:143], v[0:15]
	global_load_dwordx4 v[128:131], v204, s[14:15]
	global_load_dwordx4 v[132:135], v32, s[14:15]
	v_or_b32_e32 v32, 0x800, v204
	global_load_dwordx4 v[136:139], v32, s[14:15]
	v_or_b32_e32 v32, 0xc00, v204
	global_load_dwordx4 v[140:143], v32, s[14:15]
	ds_read_b128 v[32:35], v169 offset:4096
	ds_read_b128 v[36:39], v169 offset:12288
	ds_read_b128 v[40:43], v169 offset:5120
	ds_read_b128 v[44:47], v169 offset:13312
	ds_read_b128 v[48:51], v169 offset:6144
	ds_read_b128 v[52:55], v169 offset:14336
	ds_read_b128 v[56:59], v169 offset:7168
	ds_read_b128 v[60:63], v169 offset:15360
	s_waitcnt vmcnt(33) lgkmcnt(7)
	v_mfma_f32_32x32x16_bf16 v[16:31], v[32:35], v[144:147], v[16:31]
	v_or_b32_e32 v32, 0x1000, v204
	s_waitcnt lgkmcnt(6)
	v_mfma_f32_32x32x16_bf16 v[0:15], v[36:39], v[144:147], v[0:15]
	s_waitcnt vmcnt(32) lgkmcnt(5)
	v_mfma_f32_32x32x16_bf16 v[16:31], v[40:43], v[148:151], v[16:31]
	s_waitcnt vmcnt(29)
	v_lshlrev_b32_e32 v42, 16, v160
	v_add_u32_e32 v40, s2, v198
	v_lshl_add_u32 v41, v203, 19, v224
	s_mul_i32 s2, s0, 0x8400
	s_waitcnt lgkmcnt(4)
	v_mfma_f32_32x32x16_bf16 v[0:15], v[44:47], v[148:151], v[0:15]
	s_waitcnt lgkmcnt(3)
	v_mfma_f32_32x32x16_bf16 v[16:31], v[48:51], v[152:155], v[16:31]
	s_waitcnt lgkmcnt(2)
	v_mfma_f32_32x32x16_bf16 v[0:15], v[52:55], v[152:155], v[0:15]
	s_waitcnt lgkmcnt(1)
	v_mfma_f32_32x32x16_bf16 v[16:31], v[56:59], v[156:159], v[16:31]
	s_waitcnt lgkmcnt(0)
	v_mfma_f32_32x32x16_bf16 v[0:15], v[60:63], v[156:159], v[0:15]
	global_load_dwordx4 v[144:147], v32, s[14:15]
	v_or_b32_e32 v32, 0x1400, v204
	global_load_dwordx4 v[148:151], v32, s[14:15]
	v_or_b32_e32 v32, 0x1800, v204
	global_load_dwordx4 v[152:155], v32, s[14:15]
	v_or_b32_e32 v32, 0x1c00, v204
	global_load_dwordx4 v[156:159], v32, s[14:15]
	ds_read_b128 v[32:35], v228
	ds_read_b128 v[36:39], v228 offset:16
	s_waitcnt lgkmcnt(1)
	v_mul_f32_e32 v32, v32, v42
	v_and_b32_e32 v42, 0xffff0000, v160
	v_mul_f32_e32 v33, v33, v42
	v_cvt_pk_bf16_f32 v32, v32, v33
	v_lshlrev_b32_e32 v33, 16, v161
	v_mul_f32_e32 v33, v34, v33
	v_and_b32_e32 v34, 0xffff0000, v161
	v_mul_f32_e32 v34, v35, v34
	v_cvt_pk_bf16_f32 v33, v33, v34
	v_lshlrev_b32_e32 v34, 16, v162
	v_and_b32_e32 v35, 0xffff0000, v162
	s_waitcnt lgkmcnt(0)
; #define LAS __attribute__((address_space(3)))
; DI unsigned cvt_pk_bf16(float lo, float hi) { unsigned r; asm volatile("v_cvt_pk_bf16_f32 %0, %1, %2" : "=v"(r) : "v"(lo), "v"(hi)); return r; }
; template <bool XW, int PASS, bool RMW> ...
;     ...
; #pragma unroll
;       for (int t = 0; t < 2; ++t) {
;         const int sv = 2 * dq + t;
;         *(LAS bf16x8*)(vimg + ((cc + 1) & 1) * 16384 + et * 8192 + sv * 1024 + lane * 16) = scale_tab(vr[t], kdec + 16 * sv + 8 * h);
;         vr[t] = ldg16(vT, vaoff0 + (unsigned)cnn * 524288u + 1024u * sv);
;       }
;       LAS bf16_t* sw = Sb + (pbuf ^ 1) * SBE + (4 * h) * 264 + 32 * w + r;
; #pragma unroll
;       for (int i = 0; i < 16; ++i) {
;         const int eo = ((i & 3) + 8 * (i >> 2)) * 264;
;         const unsigned pkw = cvt_pk_bf16(st0[i], st1[i]);
;         sw[eo] = (bf16_t)(pkw & 0xffffu);
;         sw[eo + 32 * 264] = (bf16_t)(pkw >> 16);
;       }
;       lds_barrier();
;       pbuf ^= 1;
	v_mul_f32_e32 v34, v36, v34
	v_mul_f32_e32 v35, v37, v35
	v_cvt_pk_bf16_f32 v34, v34, v35
	v_lshlrev_b32_e32 v35, 16, v163
	v_and_b32_e32 v36, 0xffff0000, v163
	v_mul_f32_e32 v35, v38, v35
	v_mul_f32_e32 v36, v39, v36
	v_cvt_pk_bf16_f32 v35, v35, v36
	v_add_u32_e32 v36, s3, v40
	ds_write_b128 v36, v[32:35]
	v_or_b32_e32 v32, s3, v41
	global_load_dwordx4 v[160:163], v32, s[16:17]
	ds_read_b128 v[32:35], v229
	ds_read_b128 v[36:39], v229 offset:16
	s_waitcnt vmcnt(33)
	v_lshlrev_b32_e32 v42, 16, v164
	s_waitcnt lgkmcnt(1)
	v_mul_f32_e32 v32, v32, v42
	v_and_b32_e32 v42, 0xffff0000, v164
	v_mul_f32_e32 v33, v33, v42
	v_cvt_pk_bf16_f32 v32, v32, v33
	v_lshlrev_b32_e32 v33, 16, v165
	v_mul_f32_e32 v33, v34, v33
	v_and_b32_e32 v34, 0xffff0000, v165
	v_mul_f32_e32 v34, v35, v34
	v_cvt_pk_bf16_f32 v33, v33, v34
	v_lshlrev_b32_e32 v34, 16, v166
	v_and_b32_e32 v35, 0xffff0000, v166
	s_waitcnt lgkmcnt(0)
	v_mul_f32_e32 v34, v36, v34
	v_mul_f32_e32 v35, v37, v35
	v_cvt_pk_bf16_f32 v34, v34, v35
	v_lshlrev_b32_e32 v35, 16, v167
	v_and_b32_e32 v36, 0xffff0000, v167
	v_mul_f32_e32 v35, v38, v35
	v_mul_f32_e32 v36, v39, v36
	v_cvt_pk_bf16_f32 v35, v35, v36
	v_add_u32_e32 v36, s33, v40
	ds_write_b128 v36, v[32:35]
	v_or_b32_e32 v32, s33, v41
	global_load_dwordx4 v[164:167], v32, s[16:17]
	v_add_u32_e32 v32, s2, v199
	v_mbcnt_lo_u32_b32 v251, -1, 0
	v_mbcnt_hi_u32_b32 v251, -1, v251
	v_and_b32_e32 v251, 1, v251
	v_sub_u32_e32 v250, 0, v251
	v_and_b32_e32 v248, 0x06060606, v250
	v_xor_b32_e32 v248, 0x05040100, v248
	v_and_b32_e32 v251, 0x107e, v250
	v_add_u32_e32 v249, v32, v251
	v_cvt_pk_bf16_f32 v232, v16, v20
	v_cvt_pk_bf16_f32 v233, v17, v21
	v_cvt_pk_bf16_f32 v234, v18, v22
	v_cvt_pk_bf16_f32 v235, v19, v23
	v_cvt_pk_bf16_f32 v236, v24, v28
	v_cvt_pk_bf16_f32 v237, v25, v29
	v_cvt_pk_bf16_f32 v238, v26, v30
	v_cvt_pk_bf16_f32 v239, v27, v31
	v_mov_b32_dpp v240, v232 quad_perm:[1,0,3,2] row_mask:0xf bank_mask:0xf
	v_mov_b32_dpp v241, v233 quad_perm:[1,0,3,2] row_mask:0xf bank_mask:0xf
	v_mov_b32_dpp v242, v234 quad_perm:[1,0,3,2] row_mask:0xf bank_mask:0xf
	v_mov_b32_dpp v243, v235 quad_perm:[1,0,3,2] row_mask:0xf bank_mask:0xf
	v_mov_b32_dpp v244, v236 quad_perm:[1,0,3,2] row_mask:0xf bank_mask:0xf
	v_mov_b32_dpp v245, v237 quad_perm:[1,0,3,2] row_mask:0xf bank_mask:0xf
	v_mov_b32_dpp v246, v238 quad_perm:[1,0,3,2] row_mask:0xf bank_mask:0xf
	v_mov_b32_dpp v247, v239 quad_perm:[1,0,3,2] row_mask:0xf bank_mask:0xf
	v_perm_b32 v240, v240, v232, v248
	v_perm_b32 v241, v241, v233, v248
	v_perm_b32 v242, v242, v234, v248
	v_perm_b32 v243, v243, v235, v248
	v_perm_b32 v244, v244, v236, v248
	v_perm_b32 v245, v245, v237, v248
	v_perm_b32 v246, v246, v238, v248
	v_perm_b32 v247, v247, v239, v248
	ds_write_b32 v249, v240 offset:0
	ds_write_b32 v249, v241 offset:528
	ds_write_b32 v249, v242 offset:1056
	ds_write_b32 v249, v243 offset:1584
	ds_write_b32 v249, v244 offset:8448
	ds_write_b32 v249, v245 offset:8976
	ds_write_b32 v249, v246 offset:9504
	ds_write_b32 v249, v247 offset:10032
	v_cvt_pk_bf16_f32 v232, v0, v4
	v_cvt_pk_bf16_f32 v233, v1, v5
	v_cvt_pk_bf16_f32 v234, v2, v6
	v_cvt_pk_bf16_f32 v235, v3, v7
	v_cvt_pk_bf16_f32 v236, v8, v12
	v_cvt_pk_bf16_f32 v237, v9, v13
	v_cvt_pk_bf16_f32 v238, v10, v14
	v_cvt_pk_bf16_f32 v239, v11, v15
	v_mov_b32_dpp v240, v232 quad_perm:[1,0,3,2] row_mask:0xf bank_mask:0xf
	v_mov_b32_dpp v241, v233 quad_perm:[1,0,3,2] row_mask:0xf bank_mask:0xf
	v_mov_b32_dpp v242, v234 quad_perm:[1,0,3,2] row_mask:0xf bank_mask:0xf
	v_mov_b32_dpp v243, v235 quad_perm:[1,0,3,2] row_mask:0xf bank_mask:0xf
	v_mov_b32_dpp v244, v236 quad_perm:[1,0,3,2] row_mask:0xf bank_mask:0xf
	v_mov_b32_dpp v245, v237 quad_perm:[1,0,3,2] row_mask:0xf bank_mask:0xf
	v_mov_b32_dpp v246, v238 quad_perm:[1,0,3,2] row_mask:0xf bank_mask:0xf
	v_mov_b32_dpp v247, v239 quad_perm:[1,0,3,2] row_mask:0xf bank_mask:0xf
	v_perm_b32 v240, v240, v232, v248
	v_perm_b32 v241, v241, v233, v248
	v_perm_b32 v242, v242, v234, v248
	v_perm_b32 v243, v243, v235, v248
	v_perm_b32 v244, v244, v236, v248
	v_perm_b32 v245, v245, v237, v248
	v_perm_b32 v246, v246, v238, v248
	v_perm_b32 v247, v247, v239, v248
	ds_write_b32 v249, v240 offset:16896
	ds_write_b32 v249, v241 offset:17424
	ds_write_b32 v249, v242 offset:17952
	ds_write_b32 v249, v243 offset:18480
	ds_write_b32 v249, v244 offset:25344
	ds_write_b32 v249, v245 offset:25872
	ds_write_b32 v249, v246 offset:26400
	ds_write_b32 v249, v247 offset:26928
	s_waitcnt lgkmcnt(0)
	s_barrier
	s_mov_b32 s2, s8
	s_mov_b32 s101, 1
	s_cbranch_scc0 .LBB0_102
	s_setprio 0

; #define LAS __attribute__((address_space(3)))
; template <bool XW, int PASS, bool RMW> ...
;     ...
;     bf16x8 qf[16], vr[2], kb0[8];
;     u32x2 ovn[8];
; #pragma unroll
;     for (int gq = 0; gq < 8; ++gq) { ovn[gq].x = 0u; ovn[gq].y = 0u; }
;     {
;       const int c0 = pass == 0 ? 0 : nc - 1, c1 = pass == 0 ? 1 : nc - 2;
;       if constexpr (XW) {
; #pragma unroll
;         for (int s = 0; s < 16; ++s) qf[s] = ldg16(qr, qoff0 + (unsigned)c0 * 262144u + 1024u * s);
;         if constexpr (PASS == 1 && RMW) {
; #pragma unroll
;           for (int gq = 0; gq < 8; ++gq) ovn[gq] = *(const u32x2*)((const char*)y + (yoff0 + (unsigned)c0 * 524288u + 64u * (gq >> 2) + 16u * (gq & 3)));
;         }
;       }
; #pragma unroll
;       for (int s = 0; s < 8; ++s) kb0[s] = ldg16(kT, kboff0 + (unsigned)c0 * 262144u + 1024u * s);
; #pragma unroll
;       for (int t = 0; t < 2; ++t) {
;         const int sv = 2 * dq + t;
;         const bf16x8 raw = ldg16(vT, vaoff0 + (unsigned)c0 * 524288u + 1024u * sv);
;         *(LAS bf16x8*)(vimg + et * 8192 + sv * 1024 + lane * 16) = scale_tab(raw, kdec + 16 * sv + 8 * h);
;         vr[t] = ldg16(vT, vaoff0 + (unsigned)c1 * 524288u + 1024u * sv);
;       }
;       lds_barrier();
.LBB0_107:
	s_or_b64 exec, exec, s[0:1]
	v_add_u32_e32 v0, s21, v224
	v_or_b32_e32 v1, s3, v0
	s_waitcnt lgkmcnt(0)
	s_barrier
	global_load_dwordx4 v[8:11], v1, s[16:17]
	v_readlane_b32 s0, v254, 15
	v_add_u32_e32 v1, s20, v226
	v_add_u32_e32 v2, s20, v223
	s_waitcnt vmcnt(15)
	v_add_u32_e32 v172, s0, v197
	ds_read_b128 v[12:15], v172
	ds_read_b128 v[16:19], v172 offset:16
	v_or_b32_e32 v3, 0x400, v1
	v_or_b32_e32 v4, 0x800, v1
	v_or_b32_e32 v5, 0xc00, v1
	v_or_b32_e32 v6, 0x1000, v1
	v_or_b32_e32 v7, 0x1400, v1
	v_or_b32_e32 v24, 0x1800, v1
	v_or_b32_e32 v25, 0x1c00, v1
	v_or_b32_e32 v26, 0x2000, v1
	v_or_b32_e32 v27, 0x2400, v1
	s_waitcnt vmcnt(5)
	v_or_b32_e32 v40, 0x1c00, v2
	v_or_b32_e32 v28, 0x2800, v1
	v_or_b32_e32 v29, 0x2c00, v1
	v_or_b32_e32 v30, 0x3000, v1
	v_or_b32_e32 v31, 0x3400, v1
	s_waitcnt vmcnt(3)
	v_or_b32_e32 v32, 0x3800, v1
	v_or_b32_e32 v33, 0x3c00, v1
	v_or_b32_e32 v34, 0x400, v2
	v_or_b32_e32 v35, 0x800, v2
	v_or_b32_e32 v36, 0xc00, v2
	v_or_b32_e32 v37, 0x1000, v2
	v_or_b32_e32 v38, 0x1400, v2
	v_or_b32_e32 v39, 0x1800, v2
	v_or_b32_e32 v48, s33, v0
	global_load_dwordx4 v[20:23], v1, s[92:93]
	global_load_dwordx4 v[132:135], v2, s[14:15]
	global_load_dwordx4 v[84:87], v3, s[92:93]
	global_load_dwordx4 v[88:91], v4, s[92:93]
	global_load_dwordx4 v[92:95], v5, s[92:93]
	global_load_dwordx4 v[96:99], v6, s[92:93]
	global_load_dwordx4 v[100:103], v7, s[92:93]
	global_load_dwordx4 v[104:107], v24, s[92:93]
	global_load_dwordx4 v[108:111], v25, s[92:93]
	global_load_dwordx4 v[112:115], v26, s[92:93]
	global_load_dwordx4 v[80:83], v27, s[92:93]
	global_load_dwordx4 v[76:79], v28, s[92:93]
	global_load_dwordx4 v[72:75], v29, s[92:93]
	global_load_dwordx4 v[68:71], v30, s[92:93]
	global_load_dwordx4 v[4:7], v31, s[92:93]
	global_load_dwordx4 v[0:3], v32, s[92:93]
	global_load_dwordx4 v[64:67], v33, s[92:93]
	global_load_dwordx4 v[140:143], v34, s[14:15]
	global_load_dwordx4 v[136:139], v35, s[14:15]
	global_load_dwordx4 v[128:131], v36, s[14:15]
	global_load_dwordx4 v[60:63], v37, s[14:15]
	global_load_dwordx4 v[56:59], v38, s[14:15]
	global_load_dwordx4 v[44:47], v39, s[14:15]
	s_nop 0
	global_load_dwordx4 v[40:43], v40, s[14:15]
	s_waitcnt vmcnt(25)
	v_add_u32_e32 v148, s3, v198
	v_readlane_b32 s0, v254, 16
	v_add_u32_e32 v169, s33, v198
	v_add_u32_e32 v144, s21, v227
	v_add_u32_e32 v173, s0, v197
	v_or_b32_e32 v153, 64, v144
	v_or_b32_e32 v154, 16, v144
	v_or_b32_e32 v155, 0x50, v144
	v_or_b32_e32 v156, 32, v144
	v_or_b32_e32 v157, 0x60, v144
	v_or_b32_e32 v158, 48, v144
	s_add_i32 s30, s30, s29
	s_mov_b32 s0, 1
	s_movk_i32 s1, 0x4000
	s_mov_b32 s8, 1
	s_waitcnt vmcnt(24)
	v_lshlrev_b32_e32 v24, 16, v8
	v_and_b32_e32 v8, 0xffff0000, v8
	v_lshlrev_b32_e32 v25, 16, v9
	v_and_b32_e32 v9, 0xffff0000, v9
	v_lshlrev_b32_e32 v26, 16, v10
	v_and_b32_e32 v10, 0xffff0000, v10
	v_lshlrev_b32_e32 v27, 16, v11
	v_and_b32_e32 v11, 0xffff0000, v11
	s_waitcnt lgkmcnt(1)
	v_mul_f32_e32 v12, v12, v24
	v_mul_f32_e32 v8, v13, v8
	v_mul_f32_e32 v13, v14, v25
	v_mul_f32_e32 v9, v15, v9
	s_waitcnt lgkmcnt(0)
	v_mul_f32_e32 v14, v16, v26
	v_mul_f32_e32 v10, v17, v10
	v_mul_f32_e32 v15, v18, v27
	v_mul_f32_e32 v11, v19, v11
	v_cvt_pk_bf16_f32 v8, v12, v8
	v_cvt_pk_bf16_f32 v9, v13, v9
	v_cvt_pk_bf16_f32 v10, v14, v10
	v_cvt_pk_bf16_f32 v11, v15, v11
	global_load_dwordx4 v[12:15], v48, s[16:17]
	v_add_u32_e32 v16, s22, v224
	v_or_b32_e32 v17, s3, v16
	ds_write_b128 v148, v[8:11]
	v_or_b32_e32 v24, s33, v16
	global_load_dwordx4 v[52:55], v17, s[16:17]
	ds_read_b128 v[8:11], v173
	ds_read_b128 v[16:19], v173 offset:16
	s_waitcnt vmcnt(1)
	v_lshlrev_b32_e32 v25, 16, v12
	v_and_b32_e32 v12, 0xffff0000, v12
	v_lshlrev_b32_e32 v26, 16, v13
	v_and_b32_e32 v13, 0xffff0000, v13
	v_lshlrev_b32_e32 v27, 16, v14
	v_and_b32_e32 v14, 0xffff0000, v14
	v_lshlrev_b32_e32 v28, 16, v15
	v_and_b32_e32 v15, 0xffff0000, v15
	s_waitcnt lgkmcnt(1)
	v_mul_f32_e32 v8, v8, v25
	v_mul_f32_e32 v9, v9, v12
	v_mul_f32_e32 v10, v10, v26
	v_mul_f32_e32 v11, v11, v13
	s_waitcnt lgkmcnt(0)
	v_mul_f32_e32 v12, v16, v27
	v_mul_f32_e32 v13, v17, v14
	v_mul_f32_e32 v14, v18, v28
	v_mul_f32_e32 v15, v19, v15
	v_cvt_pk_bf16_f32 v8, v8, v9
	v_cvt_pk_bf16_f32 v9, v10, v11
	v_cvt_pk_bf16_f32 v10, v12, v13
	v_cvt_pk_bf16_f32 v11, v14, v15
	ds_write_b128 v169, v[8:11]
	global_load_dwordx4 v[48:51], v24, s[16:17]
	s_waitcnt lgkmcnt(0)
	s_barrier
; #define LAS __attribute__((address_space(3)))
; #define MFMA32(a, b, c) __builtin_amdgcn_mfma_f32_32x32x16_bf16((a), (b), (c), 0, 0, 0)
; template <bool XW, int PASS, bool RMW> ...
;     ...
;         const LAS bf16_t* sp = Sb + pbuf * SBE + r * 264 + 8 * h;
; #pragma unroll
;         for (int sb = 0; sb < 8; ++sb) {
;           bf16x8 a0[2], a1[2];
; #pragma unroll
;           for (int k = 0; k < 2; ++k) { a0[k] = *(const LAS bf16x8*)(sp + 16 * (2 * sb + k)); a1[k] = *(const LAS bf16x8*)(sp + 32 * 264 + 16 * (2 * sb + k)); }
; #pragma unroll
;           for (int k = 0; k < 2; ++k) { yc0 = MFMA32(a0[k], qf[2 * sb + k], yc0); yc1 = MFMA32(a1[k], qf[2 * sb + k], yc1); }
;         }
;         asm volatile("" : "+v"(yc0), "+v"(yc1) :: "memory");
	ds_read_b128 v[8:11], v217
	ds_read_b128 v[116:119], v217 offset:32
	s_waitcnt lgkmcnt(1)
	v_mfma_f32_32x32x16_bf16 v[24:39], v[8:11], v[20:23], 0
	ds_read_b128 v[8:11], v217 offset:16896
	s_waitcnt lgkmcnt(1)
	v_mfma_f32_32x32x16_bf16 v[24:39], v[116:119], v[84:87], v[24:39]
	ds_read_b128 v[116:119], v217 offset:16928
	s_waitcnt lgkmcnt(1)
	v_mfma_f32_32x32x16_bf16 v[8:23], v[8:11], v[20:23], 0
	s_waitcnt lgkmcnt(0)
	v_mfma_f32_32x32x16_bf16 v[8:23], v[116:119], v[84:87], v[8:23]
	ds_read_b128 v[84:87], v217 offset:64
	s_waitcnt lgkmcnt(0)
	v_mfma_f32_32x32x16_bf16 v[24:39], v[84:87], v[88:91], v[24:39]
	ds_read_b128 v[84:87], v217 offset:16960
	s_waitcnt lgkmcnt(0)
	v_mfma_f32_32x32x16_bf16 v[8:23], v[84:87], v[88:91], v[8:23]
	ds_read_b128 v[84:87], v217 offset:96
	s_waitcnt lgkmcnt(0)
	v_mfma_f32_32x32x16_bf16 v[24:39], v[84:87], v[92:95], v[24:39]
	ds_read_b128 v[84:87], v217 offset:16992
	s_waitcnt lgkmcnt(0)
	v_mfma_f32_32x32x16_bf16 v[8:23], v[84:87], v[92:95], v[8:23]
	ds_read_b128 v[84:87], v217 offset:128
	s_waitcnt lgkmcnt(0)
	v_mfma_f32_32x32x16_bf16 v[24:39], v[84:87], v[96:99], v[24:39]
	ds_read_b128 v[84:87], v217 offset:17024
	s_waitcnt lgkmcnt(0)
	v_mfma_f32_32x32x16_bf16 v[8:23], v[84:87], v[96:99], v[8:23]
	ds_read_b128 v[84:87], v217 offset:160
	s_waitcnt lgkmcnt(0)
	v_mfma_f32_32x32x16_bf16 v[24:39], v[84:87], v[100:103], v[24:39]
	ds_read_b128 v[84:87], v217 offset:17056
	s_waitcnt lgkmcnt(0)
	v_mfma_f32_32x32x16_bf16 v[8:23], v[84:87], v[100:103], v[8:23]
	ds_read_b128 v[84:87], v217 offset:192
	s_waitcnt lgkmcnt(0)
	v_mfma_f32_32x32x16_bf16 v[24:39], v[84:87], v[104:107], v[24:39]
	ds_read_b128 v[84:87], v217 offset:17088
	s_waitcnt lgkmcnt(0)
	v_mfma_f32_32x32x16_bf16 v[8:23], v[84:87], v[104:107], v[8:23]
	ds_read_b128 v[84:87], v217 offset:224
	s_waitcnt lgkmcnt(0)
	v_mfma_f32_32x32x16_bf16 v[24:39], v[84:87], v[108:111], v[24:39]
	ds_read_b128 v[84:87], v217 offset:17120
	s_waitcnt lgkmcnt(0)
	v_mfma_f32_32x32x16_bf16 v[8:23], v[84:87], v[108:111], v[8:23]
	ds_read_b128 v[84:87], v217 offset:256
	s_waitcnt lgkmcnt(0)
	v_mfma_f32_32x32x16_bf16 v[24:39], v[84:87], v[112:115], v[24:39]
	ds_read_b128 v[84:87], v217 offset:17152
	s_waitcnt lgkmcnt(0)
	v_mfma_f32_32x32x16_bf16 v[8:23], v[84:87], v[112:115], v[8:23]
	ds_read_b128 v[84:87], v217 offset:288
	s_waitcnt lgkmcnt(0)
	v_mfma_f32_32x32x16_bf16 v[24:39], v[84:87], v[80:83], v[24:39]
	ds_read_b128 v[84:87], v217 offset:17184
	s_waitcnt lgkmcnt(0)
	v_mfma_f32_32x32x16_bf16 v[8:23], v[84:87], v[80:83], v[8:23]
	ds_read_b128 v[80:83], v217 offset:320
	s_waitcnt lgkmcnt(0)
	v_mfma_f32_32x32x16_bf16 v[24:39], v[80:83], v[76:79], v[24:39]
	ds_read_b128 v[80:83], v217 offset:17216
	s_waitcnt lgkmcnt(0)
	v_mfma_f32_32x32x16_bf16 v[8:23], v[80:83], v[76:79], v[8:23]
	ds_read_b128 v[76:79], v217 offset:352
	s_waitcnt lgkmcnt(0)
	v_mfma_f32_32x32x16_bf16 v[24:39], v[76:79], v[72:75], v[24:39]
	ds_read_b128 v[76:79], v217 offset:17248
	s_waitcnt lgkmcnt(0)
	v_mfma_f32_32x32x16_bf16 v[8:23], v[76:79], v[72:75], v[8:23]
	ds_read_b128 v[72:75], v217 offset:384
	v_add_u32_e32 v76, s26, v226
	v_add_u32_e32 v77, 0, v190
	v_or_b32_e32 v78, 0x400, v76
	v_or_b32_e32 v79, 0x800, v76
	v_or_b32_e32 v80, 0xc00, v76
	v_or_b32_e32 v81, 0x1000, v76
	s_waitcnt lgkmcnt(0)
	v_mfma_f32_32x32x16_bf16 v[24:39], v[72:75], v[68:71], v[24:39]
	ds_read_b128 v[72:75], v217 offset:17280
	v_or_b32_e32 v82, 0x1400, v76
	v_or_b32_e32 v83, 0x1800, v76
	v_or_b32_e32 v84, 0x1c00, v76
	v_or_b32_e32 v85, 0x2000, v76
	v_or_b32_e32 v86, 0x2400, v76
	v_or_b32_e32 v87, 0x2800, v76
	s_waitcnt lgkmcnt(0)
	v_mfma_f32_32x32x16_bf16 v[8:23], v[72:75], v[68:71], v[8:23]
	ds_read_b128 v[68:71], v217 offset:416
	v_mul_f32_e32 v72, 0xc3000000, v225
	v_exp_f32_e32 v168, v72
	ds_read_b128 v[72:75], v217 offset:17312
	v_or_b32_e32 v147, 0x2c00, v76
	v_or_b32_e32 v149, 0x3000, v76
	v_or_b32_e32 v150, 0x3400, v76
	s_waitcnt lgkmcnt(1)
	v_mfma_f32_32x32x16_bf16 v[24:39], v[68:71], v[4:7], v[24:39]
	ds_read_b128 v[68:71], v217 offset:448
	v_or_b32_e32 v151, 0x3800, v76
	v_or_b32_e32 v152, 0x3c00, v76
	v_add_u32_e32 v146, 0x11400, v77
	v_add_u32_e32 v145, 0x13400, v77
	v_mov_b32_e32 v170, v168
	v_mov_b32_e32 v171, v168
	s_waitcnt lgkmcnt(1)
	v_mfma_f32_32x32x16_bf16 v[8:23], v[72:75], v[4:7], v[8:23]
	ds_read_b128 v[4:7], v217 offset:17344
	ds_read_b128 v[72:75], v217 offset:17376
	s_waitcnt lgkmcnt(2)
	v_mfma_f32_32x32x16_bf16 v[24:39], v[68:71], v[0:3], v[24:39]
	ds_read_b128 v[68:71], v217 offset:480
	s_waitcnt lgkmcnt(2)
	v_mfma_f32_32x32x16_bf16 v[8:23], v[4:7], v[0:3], v[8:23]
	v_mul_f32_e32 v0, 0, v168
	v_mov_b32_e32 v1, v0
	v_mov_b32_e32 v2, v0
	v_mov_b32_e32 v3, v0
	v_mov_b32_e32 v4, v0
	v_mov_b32_e32 v5, v0
	v_mov_b32_e32 v6, v0
	s_waitcnt lgkmcnt(0)
; #define LAS __attribute__((address_space(3)))
; DI unsigned cvt_pk_bf16(float lo, float hi) { unsigned r; asm volatile("v_cvt_pk_bf16_f32 %0, %1, %2" : "=v"(r) : "v"(lo), "v"(hi)); return r; }
; DI float bf_lo(unsigned w) { return __uint_as_float(w << 16); }
; DI float bf_hi(unsigned w) { return __uint_as_float(w & 0xffff0000u); }
; #define MFMA32(a, b, c) __builtin_amdgcn_mfma_f32_32x32x16_bf16((a), (b), (c), 0, 0, 0)
; template <bool XW, int PASS, bool RMW> ...
;     ...
;         for (int s = 0; s < 16; ++s) qf[s] = ldg16(qr, qoff0 + (unsigned)cn * 262144u + 1024u * s);
;         const float qe = cc > 0 ? qd : 0.f;
; #pragma unroll
;         for (int gq = 0; gq < 4; ++gq) {
;           u32x2 a; a.x = cvt_pk_bf16(bf_lo(ovn[gq].x) + qe * yc0[4 * gq], bf_hi(ovn[gq].x) + qe * yc0[4 * gq + 1]); a.y = cvt_pk_bf16(bf_lo(ovn[gq].y) + qe * yc0[4 * gq + 2], bf_hi(ovn[gq].y) + qe * yc0[4 * gq + 3]);
;           *(u32x2*)((char*)y + (yb + 16u * gq)) = a;
;           u32x2 c2; c2.x = cvt_pk_bf16(bf_lo(ovn[4 + gq].x) + qe * yc1[4 * gq], bf_hi(ovn[4 + gq].x) + qe * yc1[4 * gq + 1]); c2.y = cvt_pk_bf16(bf_lo(ovn[4 + gq].y) + qe * yc1[4 * gq + 2], bf_hi(ovn[4 + gq].y) + qe * yc1[4 * gq + 3]);
;           *(u32x2*)((char*)y + (yb + 64u + 16u * gq)) = c2;
;         }
;         if constexpr (PASS == 1 && RMW) {
;           const unsigned ybn = yoff0 + (unsigned)cn * 524288u;
; #pragma unroll
;           for (int gq = 0; gq < 8; ++gq) ovn[gq] = *(const u32x2*)((const char*)y + (ybn + 64u * (gq >> 2) + 16u * (gq & 3)));
;         }
;       }
; #pragma unroll
;       for (int i = 0; i < 16; ++i) { st0[i] *= cd; st1[i] *= cd; }
; #pragma unroll
;       for (int sb = 0; sb < 2; ++sb) {
;         bf16x8 a0[4], a1[4];
; #pragma unroll
;         for (int k = 0; k < 4; ++k) { a0[k] = *(const LAS bf16x8*)(vimg + (cc & 1) * 16384 + (4 * sb + k) * 1024 + lane * 16); a1[k] = *(const LAS bf16x8*)(vimg + (cc & 1) * 16384 + 8192 + (4 * sb + k) * 1024 + lane * 16); }
; #pragma unroll
;         for (int k = 0; k < 4; ++k) { st0 = MFMA32(a0[k], kb0[4 * sb + k], st0); st1 = MFMA32(a1[k], kb0[4 * sb + k], st1); }
;         asm volatile("" : "+v"(st0), "+v"(st1) :: "memory");
; #pragma unroll
;         for (int k = 0; k < 4; ++k) kb0[4 * sb + k] = ldg16(kT, kboff0 + (unsigned)cn * 262144u + 1024u * (4 * sb + k));
	v_mfma_f32_32x32x16_bf16 v[24:39], v[68:71], v[64:67], v[24:39]
	v_mov_b32_e32 v7, v0
	v_mfma_f32_32x32x16_bf16 v[8:23], v[72:75], v[64:67], v[8:23]
	global_load_dwordx4 v[124:127], v76, s[92:93]
	global_load_dwordx4 v[120:123], v78, s[92:93]
	global_load_dwordx4 v[116:119], v79, s[92:93]
	global_load_dwordx4 v[112:115], v80, s[92:93]
	global_load_dwordx4 v[108:111], v81, s[92:93]
	global_load_dwordx4 v[104:107], v82, s[92:93]
	global_load_dwordx4 v[100:103], v83, s[92:93]
	global_load_dwordx4 v[96:99], v84, s[92:93]
	global_load_dwordx4 v[92:95], v85, s[92:93]
	global_load_dwordx4 v[88:91], v86, s[92:93]
	s_nop 0
	global_load_dwordx4 v[84:87], v87, s[92:93]
	s_nop 0
	global_load_dwordx4 v[80:83], v147, s[92:93]
	global_load_dwordx4 v[76:79], v149, s[92:93]
	global_load_dwordx4 v[72:75], v150, s[92:93]
	global_load_dwordx4 v[68:71], v151, s[92:93]
	global_load_dwordx4 v[64:67], v152, s[92:93]
	v_fma_f32 v24, v24, 0, 0
	v_fma_f32 v25, v25, 0, 0
	v_fma_f32 v26, v26, 0, 0
	v_fma_f32 v27, v27, 0, 0
	v_fma_f32 v147, v8, 0, 0
	v_fma_f32 v149, v9, 0, 0
	v_cvt_pk_bf16_f32 v8, v24, v25
	v_cvt_pk_bf16_f32 v9, v26, v27
	v_fma_f32 v10, v10, 0, 0
	v_fma_f32 v11, v11, 0, 0
	global_store_dwordx2 v144, v[8:9], s[10:11]
	v_cvt_pk_bf16_f32 v8, v147, v149
	v_cvt_pk_bf16_f32 v9, v10, v11
	v_fma_f32 v28, v28, 0, 0
	v_fma_f32 v29, v29, 0, 0
	v_fma_f32 v30, v30, 0, 0
	v_fma_f32 v31, v31, 0, 0
	global_store_dwordx2 v153, v[8:9], s[10:11]
	v_cvt_pk_bf16_f32 v8, v28, v29
	v_cvt_pk_bf16_f32 v9, v30, v31
	v_fma_f32 v12, v12, 0, 0
	v_fma_f32 v13, v13, 0, 0
	v_fma_f32 v14, v14, 0, 0
	v_fma_f32 v15, v15, 0, 0
	global_store_dwordx2 v154, v[8:9], s[10:11]
	v_cvt_pk_bf16_f32 v8, v12, v13
	v_cvt_pk_bf16_f32 v9, v14, v15
	v_fma_f32 v32, v32, 0, 0
	v_fma_f32 v33, v33, 0, 0
	v_fma_f32 v34, v34, 0, 0
	v_fma_f32 v35, v35, 0, 0
	global_store_dwordx2 v155, v[8:9], s[10:11]
	v_cvt_pk_bf16_f32 v8, v32, v33
	v_cvt_pk_bf16_f32 v9, v34, v35
	v_fma_f32 v16, v16, 0, 0
	v_fma_f32 v17, v17, 0, 0
	v_fma_f32 v18, v18, 0, 0
	v_fma_f32 v19, v19, 0, 0
	v_fma_f32 v36, v36, 0, 0
	v_fma_f32 v37, v37, 0, 0
	global_store_dwordx2 v156, v[8:9], s[10:11]
	v_cvt_pk_bf16_f32 v8, v16, v17
	v_cvt_pk_bf16_f32 v9, v18, v19
	v_fma_f32 v38, v38, 0, 0
	v_fma_f32 v39, v39, 0, 0
	v_fma_f32 v20, v20, 0, 0
	v_fma_f32 v21, v21, 0, 0
	v_fma_f32 v22, v22, 0, 0
	v_fma_f32 v23, v23, 0, 0
	global_store_dwordx2 v157, v[8:9], s[10:11]
	v_cvt_pk_bf16_f32 v8, v36, v37
	v_cvt_pk_bf16_f32 v9, v38, v39
	global_store_dwordx2 v158, v[8:9], s[10:11]
	v_cvt_pk_bf16_f32 v36, v20, v21
	v_cvt_pk_bf16_f32 v37, v22, v23
	ds_read_b128 v[32:35], v146
	v_mov_b32_e32 v8, v0
	v_mov_b32_e32 v9, v0
	v_mov_b32_e32 v10, v0
	v_mov_b32_e32 v11, v0
	v_mov_b32_e32 v12, v0
	v_mov_b32_e32 v13, v0
	v_mov_b32_e32 v14, v0
	v_mov_b32_e32 v15, v0
	v_or_b32_e32 v38, 0x70, v144
	global_store_dwordx2 v38, v[36:37], s[10:11]
	s_waitcnt lgkmcnt(0)
	v_mfma_f32_32x32x16_bf16 v[16:31], v[32:35], v[132:135], v[0:15]
	ds_read_b128 v[32:35], v145
	s_waitcnt vmcnt(25)
	v_lshlrev_b32_e32 v150, 16, v52
	v_and_b32_e32 v52, 0xffff0000, v52
	v_lshlrev_b32_e32 v151, 16, v53
	v_and_b32_e32 v53, 0xffff0000, v53
	v_lshlrev_b32_e32 v152, 16, v54
	s_waitcnt lgkmcnt(0)
	v_mfma_f32_32x32x16_bf16 v[0:15], v[32:35], v[132:135], v[0:15]
	ds_read_b128 v[32:35], v146 offset:1024
	s_waitcnt lgkmcnt(0)
	v_mfma_f32_32x32x16_bf16 v[16:31], v[32:35], v[140:143], v[16:31]
	ds_read_b128 v[32:35], v145 offset:1024
	s_waitcnt lgkmcnt(0)
	v_mfma_f32_32x32x16_bf16 v[0:15], v[32:35], v[140:143], v[0:15]
	ds_read_b128 v[32:35], v146 offset:2048
	s_waitcnt lgkmcnt(0)
	v_mfma_f32_32x32x16_bf16 v[16:31], v[32:35], v[136:139], v[16:31]
	ds_read_b128 v[32:35], v145 offset:2048
	s_waitcnt lgkmcnt(0)
	v_mfma_f32_32x32x16_bf16 v[0:15], v[32:35], v[136:139], v[0:15]
	ds_read_b128 v[32:35], v146 offset:3072
	s_waitcnt lgkmcnt(0)
	v_mfma_f32_32x32x16_bf16 v[16:31], v[32:35], v[128:131], v[16:31]
	ds_read_b128 v[32:35], v145 offset:3072
	s_waitcnt lgkmcnt(0)
	v_mfma_f32_32x32x16_bf16 v[0:15], v[32:35], v[128:131], v[0:15]
	ds_read_b128 v[32:35], v146 offset:4096
	ds_read_b128 v[36:39], v146 offset:6144
	s_waitcnt lgkmcnt(1)
	v_mfma_f32_32x32x16_bf16 v[16:31], v[32:35], v[60:63], v[16:31]
	ds_read_b128 v[32:35], v145 offset:4096
	s_waitcnt lgkmcnt(0)
	v_mfma_f32_32x32x16_bf16 v[0:15], v[32:35], v[60:63], v[0:15]
	ds_read_b128 v[32:35], v146 offset:5120
	v_add_u32_e32 v60, s26, v223
	v_or_b32_e32 v62, 0x400, v60
	v_or_b32_e32 v63, 0x800, v60
	v_or_b32_e32 v128, 0x1c00, v60
	v_add_u32_e32 v61, s25, v224
	v_or_b32_e32 v149, s3, v61
	s_waitcnt lgkmcnt(0)
	v_mfma_f32_32x32x16_bf16 v[16:31], v[32:35], v[56:59], v[16:31]
	ds_read_b128 v[32:35], v145 offset:5120
	v_or_b32_e32 v61, s33, v61
	v_mfma_f32_32x32x16_bf16 v[16:31], v[36:39], v[44:47], v[16:31]
	ds_read_b128 v[36:39], v146 offset:7168
	s_waitcnt lgkmcnt(1)
	v_mfma_f32_32x32x16_bf16 v[0:15], v[32:35], v[56:59], v[0:15]
	ds_read_b128 v[32:35], v145 offset:6144
	v_or_b32_e32 v56, 0xc00, v60
	v_or_b32_e32 v57, 0x1000, v60
	v_or_b32_e32 v58, 0x1400, v60
	v_or_b32_e32 v59, 0x1800, v60
	s_waitcnt lgkmcnt(0)
	v_mfma_f32_32x32x16_bf16 v[0:15], v[32:35], v[44:47], v[0:15]
	ds_read_b128 v[32:35], v145 offset:7168
	global_load_dwordx4 v[164:167], v60, s[14:15]
	global_load_dwordx4 v[160:163], v62, s[14:15]
	global_load_dwordx4 v[156:159], v63, s[14:15]
	global_load_dwordx4 v[140:143], v56, s[14:15]
	v_and_b32_e32 v44, 0xffff0000, v54
	v_lshlrev_b32_e32 v45, 16, v55
	v_and_b32_e32 v46, 0xffff0000, v55
	s_waitcnt vmcnt(28)
	v_lshlrev_b32_e32 v47, 16, v48
	v_and_b32_e32 v48, 0xffff0000, v48
	v_mfma_f32_32x32x16_bf16 v[16:31], v[36:39], v[40:43], v[16:31]
	v_lshlrev_b32_e32 v54, 16, v49
	v_and_b32_e32 v49, 0xffff0000, v49
	v_lshlrev_b32_e32 v55, 16, v50
	v_and_b32_e32 v50, 0xffff0000, v50
	s_waitcnt lgkmcnt(0)
; #define LAS __attribute__((address_space(3)))
; DI unsigned cvt_pk_bf16(float lo, float hi) { unsigned r; asm volatile("v_cvt_pk_bf16_f32 %0, %1, %2" : "=v"(r) : "v"(lo), "v"(hi)); return r; }
; #define MFMA32(a, b, c) __builtin_amdgcn_mfma_f32_32x32x16_bf16((a), (b), (c), 0, 0, 0)
; template <bool XW, int PASS, bool RMW> ...
;     ...
;         const LAS bf16_t* sp = Sb + pbuf * SBE + r * 264 + 8 * h;
; #pragma unroll
;         for (int sb = 0; sb < 8; ++sb) {
;           bf16x8 a0[2], a1[2];
; #pragma unroll
;           for (int k = 0; k < 2; ++k) { a0[k] = *(const LAS bf16x8*)(sp + 16 * (2 * sb + k)); a1[k] = *(const LAS bf16x8*)(sp + 32 * 264 + 16 * (2 * sb + k)); }
; #pragma unroll
;           for (int k = 0; k < 2; ++k) { yc0 = MFMA32(a0[k], qf[2 * sb + k], yc0); yc1 = MFMA32(a1[k], qf[2 * sb + k], yc1); }
;     ...
;       for (int t = 0; t < 2; ++t) {
;         const int sv = 2 * dq + t;
;         *(LAS bf16x8*)(vimg + ((cc + 1) & 1) * 16384 + et * 8192 + sv * 1024 + lane * 16) = scale_tab(vr[t], kdec + 16 * sv + 8 * h);
;         vr[t] = ldg16(vT, vaoff0 + (unsigned)cnn * 524288u + 1024u * sv);
;       }
;       LAS bf16_t* sw = Sb + (pbuf ^ 1) * SBE + (4 * h) * 264 + 32 * w + r;
; #pragma unroll
;       for (int i = 0; i < 16; ++i) {
;         const int eo = ((i & 3) + 8 * (i >> 2)) * 264;
;         const unsigned pkw = cvt_pk_bf16(st0[i], st1[i]);
;         sw[eo] = (bf16_t)(pkw & 0xffffu);
;         sw[eo + 32 * 264] = (bf16_t)(pkw >> 16);
;       }
;       lds_barrier();
	v_mfma_f32_32x32x16_bf16 v[0:15], v[32:35], v[40:43], v[0:15]
	ds_read_b128 v[32:35], v172
	global_load_dwordx4 v[144:147], v57, s[14:15]
	global_load_dwordx4 v[136:139], v58, s[14:15]
	global_load_dwordx4 v[132:135], v59, s[14:15]
	s_nop 0
	global_load_dwordx4 v[128:131], v128, s[14:15]
	ds_read_b128 v[36:39], v172 offset:16
	v_lshlrev_b32_e32 v40, 16, v51
	v_and_b32_e32 v41, 0xffff0000, v51
	s_waitcnt lgkmcnt(1)
	v_mul_f32_e32 v32, v32, v150
	v_mul_f32_e32 v33, v33, v52
	v_mul_f32_e32 v34, v34, v151
	v_mul_f32_e32 v35, v35, v53
	s_waitcnt lgkmcnt(0)
	v_mul_f32_e32 v36, v36, v152
	v_mul_f32_e32 v37, v37, v44
	v_mul_f32_e32 v38, v38, v45
	v_mul_f32_e32 v39, v39, v46
	v_cvt_pk_bf16_f32 v32, v32, v33
	v_cvt_pk_bf16_f32 v33, v34, v35
	v_cvt_pk_bf16_f32 v34, v36, v37
	v_cvt_pk_bf16_f32 v35, v38, v39
	ds_write_b128 v148, v[32:35] offset:16384
	ds_read_b128 v[32:35], v173
	ds_read_b128 v[36:39], v173 offset:16
	global_load_dwordx4 v[152:155], v149, s[16:17]
	s_waitcnt lgkmcnt(1)
	v_mul_f32_e32 v32, v32, v47
	v_mul_f32_e32 v33, v33, v48
	v_mul_f32_e32 v34, v34, v54
	v_mul_f32_e32 v35, v35, v49
	s_waitcnt lgkmcnt(0)
	v_mul_f32_e32 v36, v36, v55
	v_mul_f32_e32 v37, v37, v50
	v_mul_f32_e32 v38, v38, v40
	v_mul_f32_e32 v39, v39, v41
	v_cvt_pk_bf16_f32 v32, v32, v33
	v_cvt_pk_bf16_f32 v33, v34, v35
	v_cvt_pk_bf16_f32 v34, v36, v37
	v_cvt_pk_bf16_f32 v35, v38, v39
	global_load_dwordx4 v[148:151], v61, s[16:17]
	ds_write_b128 v169, v[32:35] offset:16384
	v_cvt_pk_bf16_f32 v32, v16, v0
	ds_write_b16 v199, v32 offset:33792
	ds_write_b16_d16_hi v199, v32 offset:50688
	v_cvt_pk_bf16_f32 v32, v17, v1
	ds_write_b16 v199, v32 offset:34320
	ds_write_b16_d16_hi v199, v32 offset:51216
	v_cvt_pk_bf16_f32 v32, v18, v2
	ds_write_b16 v199, v32 offset:34848
	ds_write_b16_d16_hi v199, v32 offset:51744
	v_cvt_pk_bf16_f32 v32, v19, v3
	ds_write_b16 v199, v32 offset:35376
	ds_write_b16_d16_hi v199, v32 offset:52272
	v_cvt_pk_bf16_f32 v32, v20, v4
	ds_write_b16 v199, v32 offset:38016
	ds_write_b16_d16_hi v199, v32 offset:54912
	v_cvt_pk_bf16_f32 v32, v21, v5
	ds_write_b16 v199, v32 offset:38544
	ds_write_b16_d16_hi v199, v32 offset:55440
	v_cvt_pk_bf16_f32 v32, v22, v6
	ds_write_b16 v199, v32 offset:39072
	ds_write_b16_d16_hi v199, v32 offset:55968
	v_cvt_pk_bf16_f32 v32, v23, v7
	ds_write_b16 v199, v32 offset:39600
	ds_write_b16_d16_hi v199, v32 offset:56496
	v_cvt_pk_bf16_f32 v32, v24, v8
	ds_write_b16 v199, v32 offset:42240
	ds_write_b16_d16_hi v199, v32 offset:59136
	v_cvt_pk_bf16_f32 v32, v25, v9
	ds_write_b16 v199, v32 offset:42768
	ds_write_b16_d16_hi v199, v32 offset:59664
	v_cvt_pk_bf16_f32 v32, v26, v10
	ds_write_b16 v199, v32 offset:43296
	ds_write_b16_d16_hi v199, v32 offset:60192
	v_cvt_pk_bf16_f32 v32, v27, v11
	ds_write_b16 v199, v32 offset:43824
	ds_write_b16_d16_hi v199, v32 offset:60720
	v_cvt_pk_bf16_f32 v32, v28, v12
	ds_write_b16 v199, v32 offset:46464
	ds_write_b16_d16_hi v199, v32 offset:63360
	v_cvt_pk_bf16_f32 v32, v29, v13
	ds_write_b16 v199, v32 offset:46992
	ds_write_b16_d16_hi v199, v32 offset:63888
	v_cvt_pk_bf16_f32 v32, v30, v14
	v_mul_f32_e64 v36, v219, -v225
	ds_write_b16 v199, v32 offset:47520
	ds_write_b16_d16_hi v199, v32 offset:64416
	v_cvt_pk_bf16_f32 v32, v31, v15
	v_exp_f32_e32 v174, v36
	ds_write_b16 v199, v32 offset:48048
	ds_write_b16_d16_hi v199, v32 offset:64944
	s_waitcnt lgkmcnt(0)
	s_barrier
	v_add_lshl_u32 v32, v221, s28, 12
	v_add3_u32 v175, v222, v32, s30
	s_setprio 1
.LBB0_108:
	s_mul_i32 s2, s0, 0x8400
	v_add_u32_e32 v186, s2, v217
	ds_read_b128 v[228:231], v186
	ds_read_b128 v[232:235], v186 offset:16896
	ds_read_b128 v[236:239], v186 offset:32
	ds_read_b128 v[240:243], v186 offset:16928
	ds_read_b128 v[244:247], v186 offset:64
	ds_read_b128 v[248:251], v186 offset:16960
	s_add_i32 s2, s8, 1
	v_mov_b32_e32 v169, v168
	s_and_b32 s9, s1, 0x4000
	s_waitcnt vmcnt(29)
	s_waitcnt lgkmcnt(5)
	v_mfma_f32_32x32x16_bf16 v[48:63], v[228:231], v[124:127], 0
	ds_read_b128 v[228:231], v186 offset:96
	v_mul_f32_e64 v30, v168, v30
	v_mul_f32_e64 v31, v169, v31
	v_mul_f32_e64 v28, v168, v28
	v_mul_f32_e64 v29, v169, v29
	v_pk_mul_f32 v[26:27], v[168:169], v[26:27]
	v_pk_mul_f32 v[24:25], v[168:169], v[24:25]
	v_pk_mul_f32 v[22:23], v[168:169], v[22:23]
	v_pk_mul_f32 v[20:21], v[168:169], v[20:21]
	s_waitcnt lgkmcnt(5)
	v_mfma_f32_32x32x16_bf16 v[32:47], v[232:235], v[124:127], 0
	ds_read_b128 v[232:235], v186 offset:16992
	ds_read_b128 v[124:127], v186 offset:128
	v_mul_f32_e64 v18, v168, v18
	v_mul_f32_e64 v19, v169, v19
	v_mul_f32_e64 v14, v168, v14
	v_mul_f32_e64 v15, v169, v15
	v_mul_f32_e64 v12, v168, v12
	v_mul_f32_e64 v13, v169, v13
	v_pk_mul_f32 v[10:11], v[168:169], v[10:11]
	v_pk_mul_f32 v[8:9], v[168:169], v[8:9]
	v_pk_mul_f32 v[6:7], v[168:169], v[6:7]
	v_pk_mul_f32 v[4:5], v[168:169], v[4:5]
	s_waitcnt vmcnt(28)
	s_waitcnt lgkmcnt(6)
	v_mfma_f32_32x32x16_bf16 v[48:63], v[236:239], v[120:123], v[48:63]
	ds_read_b128 v[236:239], v186 offset:17024
	v_mul_f32_e64 v2, v168, v2
	v_mul_f32_e64 v3, v169, v3
	v_add_u32_e32 v169, s9, v218
	v_mul_f32_e64 v16, v170, v16
	v_mul_f32_e64 v17, v171, v17
	v_pk_mul_f32 v[0:1], v[170:171], v[0:1]
	s_add_i32 s8, s8, 2
	s_addk_i32 s1, 0x4000
	s_xor_b32 s0, s0, 1
	s_waitcnt lgkmcnt(6)
	v_mfma_f32_32x32x16_bf16 v[32:47], v[240:243], v[120:123], v[32:47]
	ds_read_b128 v[240:243], v186 offset:160
	ds_read_b128 v[120:123], v186 offset:17056
	v_add_u32_e32 v182, 0x60, v175
	v_add_u32_e32 v183, 48, v175
	s_waitcnt vmcnt(27)
	s_waitcnt lgkmcnt(7)
	v_mfma_f32_32x32x16_bf16 v[48:63], v[244:247], v[116:119], v[48:63]
	ds_read_b128 v[244:247], v186 offset:192
	s_waitcnt lgkmcnt(7)
; #define LAS __attribute__((address_space(3)))
; #define MFMA32(a, b, c) __builtin_amdgcn_mfma_f32_32x32x16_bf16((a), (b), (c), 0, 0, 0)
; template <bool XW, int PASS, bool RMW> ...
;     ...
;         for (int sb = 0; sb < 8; ++sb) {
;           bf16x8 a0[2], a1[2];
; #pragma unroll
;           for (int k = 0; k < 2; ++k) { a0[k] = *(const LAS bf16x8*)(sp + 16 * (2 * sb + k)); a1[k] = *(const LAS bf16x8*)(sp + 32 * 264 + 16 * (2 * sb + k)); }
; #pragma unroll
;           for (int k = 0; k < 2; ++k) { yc0 = MFMA32(a0[k], qf[2 * sb + k], yc0); yc1 = MFMA32(a1[k], qf[2 * sb + k], yc1); }
;         }
;         asm volatile("" : "+v"(yc0), "+v"(yc1) :: "memory");
; #pragma unroll
;         for (int s = 0; s < 16; ++s) qf[s] = ldg16(qr, qoff0 + (unsigned)cn * 262144u + 1024u * s);
	v_mfma_f32_32x32x16_bf16 v[32:47], v[248:251], v[116:119], v[32:47]
	ds_read_b128 v[248:251], v186 offset:17088
	s_waitcnt vmcnt(26)
	s_waitcnt lgkmcnt(7)
	v_mfma_f32_32x32x16_bf16 v[48:63], v[228:231], v[112:115], v[48:63]
	ds_read_b128 v[228:231], v186 offset:224
	s_waitcnt lgkmcnt(7)
	v_mfma_f32_32x32x16_bf16 v[32:47], v[232:235], v[112:115], v[32:47]
	ds_read_b128 v[232:235], v186 offset:17120
	v_add_u32_e32 v178, 64, v175
	v_add_u32_e32 v179, 16, v175
	v_add_u32_e32 v180, 0x50, v175
	v_add_u32_e32 v181, 32, v175
	s_waitcnt vmcnt(25)
	s_waitcnt lgkmcnt(7)
	v_mfma_f32_32x32x16_bf16 v[48:63], v[124:127], v[108:111], v[48:63]
	ds_read_b128 v[124:127], v186 offset:256
	s_waitcnt lgkmcnt(7)
	v_mfma_f32_32x32x16_bf16 v[32:47], v[236:239], v[108:111], v[32:47]
	ds_read_b128 v[236:239], v186 offset:17152
	s_waitcnt vmcnt(24)
	s_waitcnt lgkmcnt(7)
	v_mfma_f32_32x32x16_bf16 v[48:63], v[240:243], v[104:107], v[48:63]
	ds_read_b128 v[240:243], v186 offset:288
	s_waitcnt lgkmcnt(7)
	v_mfma_f32_32x32x16_bf16 v[32:47], v[120:123], v[104:107], v[32:47]
	ds_read_b128 v[120:123], v186 offset:17184
	s_waitcnt vmcnt(23)
	s_waitcnt lgkmcnt(7)
	v_mfma_f32_32x32x16_bf16 v[48:63], v[244:247], v[100:103], v[48:63]
	ds_read_b128 v[244:247], v186 offset:320
	s_waitcnt lgkmcnt(7)
	v_mfma_f32_32x32x16_bf16 v[32:47], v[248:251], v[100:103], v[32:47]
	ds_read_b128 v[248:251], v186 offset:17216
	s_waitcnt vmcnt(22)
	s_waitcnt lgkmcnt(7)
	v_mfma_f32_32x32x16_bf16 v[48:63], v[228:231], v[96:99], v[48:63]
	ds_read_b128 v[228:231], v186 offset:352
	s_waitcnt lgkmcnt(7)
	v_mfma_f32_32x32x16_bf16 v[32:47], v[232:235], v[96:99], v[32:47]
	ds_read_b128 v[232:235], v186 offset:17248
	s_waitcnt vmcnt(21)
	s_waitcnt lgkmcnt(7)
	v_mfma_f32_32x32x16_bf16 v[48:63], v[124:127], v[92:95], v[48:63]
	ds_read_b128 v[124:127], v186 offset:384
	s_waitcnt lgkmcnt(7)
	v_mfma_f32_32x32x16_bf16 v[32:47], v[236:239], v[92:95], v[32:47]
	ds_read_b128 v[236:239], v186 offset:17280
	s_waitcnt vmcnt(20)
	s_waitcnt lgkmcnt(7)
	v_mfma_f32_32x32x16_bf16 v[48:63], v[240:243], v[88:91], v[48:63]
	ds_read_b128 v[240:243], v186 offset:416
	s_waitcnt lgkmcnt(7)
	v_mfma_f32_32x32x16_bf16 v[32:47], v[120:123], v[88:91], v[32:47]
	ds_read_b128 v[120:123], v186 offset:17312
	s_waitcnt vmcnt(19)
	s_waitcnt lgkmcnt(7)
	v_mfma_f32_32x32x16_bf16 v[48:63], v[244:247], v[84:87], v[48:63]
	ds_read_b128 v[244:247], v186 offset:448
	s_waitcnt lgkmcnt(7)
	v_mfma_f32_32x32x16_bf16 v[32:47], v[248:251], v[84:87], v[32:47]
	ds_read_b128 v[248:251], v186 offset:17344
	s_waitcnt vmcnt(18)
	s_waitcnt lgkmcnt(7)
	v_mfma_f32_32x32x16_bf16 v[48:63], v[228:231], v[80:83], v[48:63]
	ds_read_b128 v[228:231], v186 offset:480
	v_mov_b32_e32 v92, s2
	s_waitcnt lgkmcnt(7)
	v_mfma_f32_32x32x16_bf16 v[32:47], v[232:235], v[80:83], v[32:47]
	ds_read_b128 v[232:235], v186 offset:17376
	s_waitcnt vmcnt(17)
	s_waitcnt lgkmcnt(7)
	v_mfma_f32_32x32x16_bf16 v[48:63], v[124:127], v[76:79], v[48:63]
	s_waitcnt lgkmcnt(6)
	v_mfma_f32_32x32x16_bf16 v[32:47], v[236:239], v[76:79], v[32:47]
	s_waitcnt vmcnt(16)
	s_waitcnt lgkmcnt(5)
	v_mfma_f32_32x32x16_bf16 v[48:63], v[240:243], v[72:75], v[48:63]
	v_sub_u32_e64 v84, s5, v92 clamp
	v_lshlrev_b32_e32 v184, 18, v84
	v_add_u32_e32 v84, v184, v226
	v_or_b32_e32 v85, 0x400, v84
	v_or_b32_e32 v185, 0x3400, v84
	v_or_b32_e32 v187, 0x3c00, v84
	s_waitcnt lgkmcnt(4)
	v_mfma_f32_32x32x16_bf16 v[32:47], v[120:123], v[72:75], v[32:47]
	s_waitcnt vmcnt(15)
	s_waitcnt lgkmcnt(3)
	v_mfma_f32_32x32x16_bf16 v[48:63], v[244:247], v[68:71], v[48:63]
	v_or_b32_e32 v186, 0x3800, v84
	s_waitcnt lgkmcnt(2)
	v_mfma_f32_32x32x16_bf16 v[32:47], v[248:251], v[68:71], v[32:47]
	v_or_b32_e32 v68, 0x800, v84
	v_or_b32_e32 v69, 0xc00, v84
	v_or_b32_e32 v70, 0x1000, v84
	v_or_b32_e32 v71, 0x1400, v84
	v_or_b32_e32 v72, 0x1800, v84
	v_or_b32_e32 v73, 0x1c00, v84
	v_or_b32_e32 v74, 0x2000, v84
	s_waitcnt vmcnt(14)
	s_waitcnt lgkmcnt(1)
	v_mfma_f32_32x32x16_bf16 v[48:63], v[228:231], v[64:67], v[48:63]
	v_or_b32_e32 v75, 0x2400, v84
	v_or_b32_e32 v76, 0x2800, v84
	v_or_b32_e32 v77, 0x2c00, v84
	v_or_b32_e32 v78, 0x3000, v84
	s_waitcnt lgkmcnt(0)
	v_mfma_f32_32x32x16_bf16 v[32:47], v[232:235], v[64:67], v[32:47]
	global_load_dwordx4 v[124:127], v84, s[92:93]
	global_load_dwordx4 v[120:123], v85, s[92:93]
	global_load_dwordx4 v[116:119], v68, s[92:93]
	global_load_dwordx4 v[112:115], v69, s[92:93]
	global_load_dwordx4 v[108:111], v70, s[92:93]
	global_load_dwordx4 v[104:107], v71, s[92:93]
	global_load_dwordx4 v[100:103], v72, s[92:93]
	global_load_dwordx4 v[96:99], v73, s[92:93]
	global_load_dwordx4 v[92:95], v74, s[92:93]
	global_load_dwordx4 v[88:91], v75, s[92:93]
	global_load_dwordx4 v[84:87], v76, s[92:93]
	global_load_dwordx4 v[80:83], v77, s[92:93]
	s_nop 0
	global_load_dwordx4 v[76:79], v78, s[92:93]
	s_nop 0
	global_load_dwordx4 v[72:75], v185, s[92:93]
	global_load_dwordx4 v[68:71], v186, s[92:93]
	global_load_dwordx4 v[64:67], v187, s[92:93]
	v_mbcnt_lo_u32_b32 v211, -1, 0
	v_mbcnt_hi_u32_b32 v211, -1, v211
	v_readlane_b32 s100, v255, 12
	v_and_b32_e32 v240, 31, v211
	v_lshrrev_b32_e32 v241, 5, v211
	v_lshrrev_b32_e32 v242, 3, v211
	v_and_b32_e32 v243, 7, v211
	v_mov_b32_e32 v245, s100
	v_mul_u32_u24_e32 v245, 0x44, v245
	v_add_u32_e32 v245, 0x1a000, v245
	v_mul_u32_u24_e32 v204, 0x88, v240
	v_lshl_add_u32 v204, v241, 3, v204
	v_add_u32_e32 v204, v245, v204
	v_mul_u32_u24_e32 v205, 0x88, v242
	v_lshl_add_u32 v205, v243, 4, v205
	v_add_u32_e32 v205, v245, v205
	v_sub_u32_e32 v244, v242, v240
	v_lshlrev_b32_e32 v244, 12, v244
	v_lshl_add_u32 v244, v243, 4, v244
	v_lshlrev_b32_e32 v241, 3, v241
	v_sub_u32_e32 v244, v244, v241
; #define LAS __attribute__((address_space(3)))
; DI unsigned cvt_pk_bf16(float lo, float hi) { unsigned r; asm volatile("v_cvt_pk_bf16_f32 %0, %1, %2" : "=v"(r) : "v"(lo), "v"(hi)); return r; }
; DI float bf_lo(unsigned w) { return __uint_as_float(w << 16); }
; DI float bf_hi(unsigned w) { return __uint_as_float(w & 0xffff0000u); }
; #define MFMA32(a, b, c) __builtin_amdgcn_mfma_f32_32x32x16_bf16((a), (b), (c), 0, 0, 0)
; template <bool XW, int PASS, bool RMW> ...
;     ...
;         const float qe = cc > 0 ? qd : 0.f;
; #pragma unroll
;         for (int gq = 0; gq < 4; ++gq) {
;           u32x2 a; a.x = cvt_pk_bf16(bf_lo(ovn[gq].x) + qe * yc0[4 * gq], bf_hi(ovn[gq].x) + qe * yc0[4 * gq + 1]); a.y = cvt_pk_bf16(bf_lo(ovn[gq].y) + qe * yc0[4 * gq + 2], bf_hi(ovn[gq].y) + qe * yc0[4 * gq + 3]);
;           *(u32x2*)((char*)y + (yb + 16u * gq)) = a;
;           u32x2 c2; c2.x = cvt_pk_bf16(bf_lo(ovn[4 + gq].x) + qe * yc1[4 * gq], bf_hi(ovn[4 + gq].x) + qe * yc1[4 * gq + 1]); c2.y = cvt_pk_bf16(bf_lo(ovn[4 + gq].y) + qe * yc1[4 * gq + 2], bf_hi(ovn[4 + gq].y) + qe * yc1[4 * gq + 3]);
;           *(u32x2*)((char*)y + (yb + 64u + 16u * gq)) = c2;
;         }
;         if constexpr (PASS == 1 && RMW) {
;           const unsigned ybn = yoff0 + (unsigned)cn * 524288u;
; #pragma unroll
;           for (int gq = 0; gq < 8; ++gq) ovn[gq] = *(const u32x2*)((const char*)y + (ybn + 64u * (gq >> 2) + 16u * (gq & 3)));
;         }
;       }
; #pragma unroll
;       for (int i = 0; i < 16; ++i) { st0[i] *= cd; st1[i] *= cd; }
; #pragma unroll
;       for (int sb = 0; sb < 2; ++sb) {
;         bf16x8 a0[4], a1[4];
; #pragma unroll
;         for (int k = 0; k < 4; ++k) { a0[k] = *(const LAS bf16x8*)(vimg + (cc & 1) * 16384 + (4 * sb + k) * 1024 + lane * 16); a1[k] = *(const LAS bf16x8*)(vimg + (cc & 1) * 16384 + 8192 + (4 * sb + k) * 1024 + lane * 16); }
; #pragma unroll
;         for (int k = 0; k < 4; ++k) { st0 = MFMA32(a0[k], kb0[4 * sb + k], st0); st1 = MFMA32(a1[k], kb0[4 * sb + k], st1); }
;         asm volatile("" : "+v"(st0), "+v"(st1) :: "memory");
; #pragma unroll
;         for (int k = 0; k < 4; ++k) kb0[4 * sb + k] = ldg16(kT, kboff0 + (unsigned)cn * 262144u + 1024u * (4 * sb + k));
	v_add_u32_e32 v207, v175, v244
	v_add_u32_e32 v208, 0x8000, v207
	v_add_u32_e32 v209, 0x10000, v207
	v_add_u32_e32 v210, 0x18000, v207
	v_fma_f32 v48, v174, v48, 0
	v_fma_f32 v49, v174, v49, 0
	v_fma_f32 v50, v174, v50, 0
	v_fma_f32 v51, v174, v51, 0
	v_fma_f32 v52, v174, v52, 0
	v_fma_f32 v53, v174, v53, 0
	v_fma_f32 v54, v174, v54, 0
	v_fma_f32 v55, v174, v55, 0
	v_fma_f32 v56, v174, v56, 0
	v_fma_f32 v57, v174, v57, 0
	v_fma_f32 v58, v174, v58, 0
	v_fma_f32 v59, v174, v59, 0
	v_fma_f32 v60, v174, v60, 0
	v_fma_f32 v61, v174, v61, 0
	v_fma_f32 v62, v174, v62, 0
	v_fma_f32 v63, v174, v63, 0
	v_fma_f32 v32, v174, v32, 0
	v_fma_f32 v33, v174, v33, 0
	v_fma_f32 v34, v174, v34, 0
	v_fma_f32 v35, v174, v35, 0
	v_fma_f32 v36, v174, v36, 0
	v_fma_f32 v37, v174, v37, 0
	v_fma_f32 v38, v174, v38, 0
	v_fma_f32 v39, v174, v39, 0
	v_fma_f32 v40, v174, v40, 0
	v_fma_f32 v41, v174, v41, 0
	v_fma_f32 v42, v174, v42, 0
	v_fma_f32 v43, v174, v43, 0
	v_fma_f32 v44, v174, v44, 0
	v_fma_f32 v45, v174, v45, 0
	v_fma_f32 v46, v174, v46, 0
	v_fma_f32 v47, v174, v47, 0
	v_cvt_pk_bf16_f32 v232, v48, v49
	v_cvt_pk_bf16_f32 v233, v50, v51
	v_cvt_pk_bf16_f32 v234, v52, v53
	v_cvt_pk_bf16_f32 v235, v54, v55
	v_cvt_pk_bf16_f32 v236, v56, v57
	v_cvt_pk_bf16_f32 v237, v58, v59
	v_cvt_pk_bf16_f32 v238, v60, v61
	v_cvt_pk_bf16_f32 v239, v62, v63
	v_cvt_pk_bf16_f32 v240, v32, v33
	v_cvt_pk_bf16_f32 v241, v34, v35
	v_cvt_pk_bf16_f32 v242, v36, v37
	v_cvt_pk_bf16_f32 v243, v38, v39
	v_cvt_pk_bf16_f32 v244, v40, v41
	v_cvt_pk_bf16_f32 v245, v42, v43
	v_cvt_pk_bf16_f32 v246, v44, v45
	v_cvt_pk_bf16_f32 v247, v46, v47
	ds_write_b64 v204, v[232:233]
	ds_write_b64 v204, v[234:235] offset:16
	ds_write_b64 v204, v[236:237] offset:32
	ds_write_b64 v204, v[238:239] offset:48
	ds_write_b64 v204, v[240:241] offset:64
	ds_write_b64 v204, v[242:243] offset:80
	ds_write_b64 v204, v[244:245] offset:96
	ds_write_b64 v204, v[246:247] offset:112
	s_waitcnt lgkmcnt(0)
	ds_read_b128 v[232:235], v205
	ds_read_b128 v[236:239], v205 offset:1088
	ds_read_b128 v[240:243], v205 offset:2176
	ds_read_b128 v[244:247], v205 offset:3264
	s_waitcnt lgkmcnt(0)
	global_store_dwordx4 v207, v[232:235], s[10:11]
	global_store_dwordx4 v208, v[236:239], s[10:11]
	global_store_dwordx4 v209, v[240:243], s[10:11]
	global_store_dwordx4 v210, v[244:247], s[10:11]
	s_nop 1
	ds_read_b128 v[228:231], v169
	ds_read_b128 v[232:235], v169 offset:8192
	ds_read_b128 v[236:239], v169 offset:1024
	ds_read_b128 v[240:243], v169 offset:9216
	ds_read_b128 v[244:247], v169 offset:2048
	ds_read_b128 v[248:251], v169 offset:10240
	s_waitcnt vmcnt(29)
	s_waitcnt lgkmcnt(5)
	v_mfma_f32_32x32x16_bf16 v[16:31], v[228:231], v[164:167], v[16:31]
	ds_read_b128 v[228:231], v169 offset:3072
	s_waitcnt vmcnt(21)
	v_lshlrev_b32_e32 v46, 16, v152
	v_and_b32_e32 v47, 0xffff0000, v152
	v_lshlrev_b32_e32 v48, 16, v153
	v_and_b32_e32 v49, 0xffff0000, v153
	v_lshlrev_b32_e32 v50, 16, v154
	v_and_b32_e32 v51, 0xffff0000, v154
	s_waitcnt lgkmcnt(5)
	v_mfma_f32_32x32x16_bf16 v[0:15], v[232:235], v[164:167], v[0:15]
	ds_read_b128 v[232:235], v169 offset:11264
	v_lshlrev_b32_e32 v52, 16, v155
	v_and_b32_e32 v53, 0xffff0000, v155
	s_waitcnt vmcnt(20)
	v_lshlrev_b32_e32 v54, 16, v149
	v_and_b32_e32 v55, 0xffff0000, v149
	v_lshlrev_b32_e32 v56, 16, v150
	v_and_b32_e32 v57, 0xffff0000, v150
	v_lshlrev_b32_e32 v58, 16, v151
	s_waitcnt lgkmcnt(5)
	v_mfma_f32_32x32x16_bf16 v[16:31], v[236:239], v[160:163], v[16:31]
	ds_read_b128 v[236:239], v169 offset:4096
	v_and_b32_e32 v59, 0xffff0000, v151
	s_waitcnt lgkmcnt(5)
	v_mfma_f32_32x32x16_bf16 v[0:15], v[240:243], v[160:163], v[0:15]
	ds_read_b128 v[240:243], v169 offset:12288
	s_waitcnt lgkmcnt(5)
	v_mfma_f32_32x32x16_bf16 v[16:31], v[244:247], v[156:159], v[16:31]
	ds_read_b128 v[244:247], v169 offset:5120
	s_waitcnt lgkmcnt(5)
	v_mfma_f32_32x32x16_bf16 v[0:15], v[248:251], v[156:159], v[0:15]
	ds_read_b128 v[248:251], v169 offset:13312
	v_lshlrev_b32_e32 v44, 16, v148
	v_and_b32_e32 v45, 0xffff0000, v148
	v_add_u32_e32 v175, 0xfff80000, v175
	s_waitcnt lgkmcnt(5)
	v_mfma_f32_32x32x16_bf16 v[16:31], v[228:231], v[140:143], v[16:31]
	ds_read_b128 v[228:231], v169 offset:6144
	s_waitcnt lgkmcnt(5)
	v_mfma_f32_32x32x16_bf16 v[0:15], v[232:235], v[140:143], v[0:15]
	ds_read_b128 v[232:235], v169 offset:14336
	s_waitcnt lgkmcnt(5)
	v_mfma_f32_32x32x16_bf16 v[16:31], v[236:239], v[144:147], v[16:31]
	ds_read_b128 v[236:239], v169 offset:7168
	s_waitcnt lgkmcnt(5)
	v_mfma_f32_32x32x16_bf16 v[0:15], v[240:243], v[144:147], v[0:15]
	ds_read_b128 v[240:243], v169 offset:15360
	v_mov_b32_e32 v32, s8
	v_sub_u32_e64 v32, s5, v32 clamp
	v_lshl_add_u32 v61, v32, 19, v224
	s_and_b32 s8, s1, 0x4000
	v_add_u32_e32 v60, s8, v198
	v_add_u32_e32 v62, s3, v60
	v_or_b32_e32 v63, s3, v61
	s_waitcnt lgkmcnt(5)
	v_mfma_f32_32x32x16_bf16 v[16:31], v[244:247], v[136:139], v[16:31]
	v_or_b32_e32 v61, s33, v61
	s_mul_i32 s8, s0, 0x8400
	s_cmp_eq_u32 s4, s2
	s_waitcnt lgkmcnt(4)
	v_mfma_f32_32x32x16_bf16 v[0:15], v[248:251], v[136:139], v[0:15]
	s_waitcnt lgkmcnt(3)
	v_mfma_f32_32x32x16_bf16 v[16:31], v[228:231], v[132:135], v[16:31]
	s_waitcnt lgkmcnt(2)
; #define LAS __attribute__((address_space(3)))
; DI unsigned cvt_pk_bf16(float lo, float hi) { unsigned r; asm volatile("v_cvt_pk_bf16_f32 %0, %1, %2" : "=v"(r) : "v"(lo), "v"(hi)); return r; }
; #define MFMA32(a, b, c) __builtin_amdgcn_mfma_f32_32x32x16_bf16((a), (b), (c), 0, 0, 0)
; template <bool XW, int PASS, bool RMW> ...
;     ...
;       for (int sb = 0; sb < 2; ++sb) {
;         bf16x8 a0[4], a1[4];
; #pragma unroll
;         for (int k = 0; k < 4; ++k) { a0[k] = *(const LAS bf16x8*)(vimg + (cc & 1) * 16384 + (4 * sb + k) * 1024 + lane * 16); a1[k] = *(const LAS bf16x8*)(vimg + (cc & 1) * 16384 + 8192 + (4 * sb + k) * 1024 + lane * 16); }
; #pragma unroll
;         for (int k = 0; k < 4; ++k) { st0 = MFMA32(a0[k], kb0[4 * sb + k], st0); st1 = MFMA32(a1[k], kb0[4 * sb + k], st1); }
;         asm volatile("" : "+v"(st0), "+v"(st1) :: "memory");
; #pragma unroll
;         for (int k = 0; k < 4; ++k) kb0[4 * sb + k] = ldg16(kT, kboff0 + (unsigned)cn * 262144u + 1024u * (4 * sb + k));
;       }
; #pragma unroll
;       for (int t = 0; t < 2; ++t) {
;         const int sv = 2 * dq + t;
;         *(LAS bf16x8*)(vimg + ((cc + 1) & 1) * 16384 + et * 8192 + sv * 1024 + lane * 16) = scale_tab(vr[t], kdec + 16 * sv + 8 * h);
;         vr[t] = ldg16(vT, vaoff0 + (unsigned)cnn * 524288u + 1024u * sv);
;       }
;       LAS bf16_t* sw = Sb + (pbuf ^ 1) * SBE + (4 * h) * 264 + 32 * w + r;
; #pragma unroll
;       for (int i = 0; i < 16; ++i) {
;         const int eo = ((i & 3) + 8 * (i >> 2)) * 264;
;         const unsigned pkw = cvt_pk_bf16(st0[i], st1[i]);
;         sw[eo] = (bf16_t)(pkw & 0xffffu);
;         sw[eo + 32 * 264] = (bf16_t)(pkw >> 16);
;       }
;       lds_barrier();
;       pbuf ^= 1;
;     }
	v_mfma_f32_32x32x16_bf16 v[0:15], v[232:235], v[132:135], v[0:15]
	v_add_u32_e32 v32, v184, v223
	v_or_b32_e32 v33, 0x400, v32
	v_or_b32_e32 v34, 0x800, v32
	v_or_b32_e32 v35, 0xc00, v32
	global_load_dwordx4 v[164:167], v32, s[14:15]
	global_load_dwordx4 v[160:163], v33, s[14:15]
	global_load_dwordx4 v[156:159], v34, s[14:15]
	global_load_dwordx4 v[140:143], v35, s[14:15]
	v_or_b32_e32 v132, 0x1000, v32
	s_waitcnt lgkmcnt(1)
	v_mfma_f32_32x32x16_bf16 v[16:31], v[236:239], v[128:131], v[16:31]
	v_or_b32_e32 v36, 0x1400, v32
	v_or_b32_e32 v37, 0x1800, v32
	v_or_b32_e32 v38, 0x1c00, v32
	s_waitcnt lgkmcnt(0)
	v_mfma_f32_32x32x16_bf16 v[0:15], v[240:243], v[128:131], v[0:15]
	ds_read_b128 v[32:35], v172
	global_load_dwordx4 v[144:147], v132, s[14:15]
	global_load_dwordx4 v[136:139], v36, s[14:15]
	s_nop 0
	global_load_dwordx4 v[132:135], v37, s[14:15]
	global_load_dwordx4 v[128:131], v38, s[14:15]
	ds_read_b128 v[36:39], v172 offset:16
	s_waitcnt lgkmcnt(1)
	v_mul_f32_e32 v32, v32, v46
	v_mul_f32_e32 v33, v33, v47
	v_mul_f32_e32 v34, v34, v48
	v_mul_f32_e32 v35, v35, v49
	s_waitcnt lgkmcnt(0)
	v_mul_f32_e32 v36, v36, v50
	v_mul_f32_e32 v37, v37, v51
	v_mul_f32_e32 v38, v38, v52
	v_mul_f32_e32 v39, v39, v53
	v_cvt_pk_bf16_f32 v32, v32, v33
	v_cvt_pk_bf16_f32 v33, v34, v35
	v_cvt_pk_bf16_f32 v34, v36, v37
	v_cvt_pk_bf16_f32 v35, v38, v39
	ds_write_b128 v62, v[32:35]
	global_load_dwordx4 v[152:155], v63, s[16:17]
	ds_read_b128 v[32:35], v173
	ds_read_b128 v[36:39], v173 offset:16
	s_waitcnt lgkmcnt(1)
	v_mul_f32_e32 v32, v32, v44
	v_mul_f32_e32 v33, v33, v45
	v_mul_f32_e32 v34, v34, v54
	v_mul_f32_e32 v35, v35, v55
	s_waitcnt lgkmcnt(0)
	v_mul_f32_e32 v36, v36, v56
	v_mul_f32_e32 v37, v37, v57
	v_mul_f32_e32 v38, v38, v58
	v_mul_f32_e32 v39, v39, v59
	v_cvt_pk_bf16_f32 v32, v32, v33
	v_cvt_pk_bf16_f32 v33, v34, v35
	v_cvt_pk_bf16_f32 v34, v36, v37
	v_cvt_pk_bf16_f32 v35, v38, v39
	global_load_dwordx4 v[148:151], v61, s[16:17]
	v_add_u32_e32 v37, s33, v60
	v_add_u32_e32 v36, s8, v199
	ds_write_b128 v37, v[32:35]
	v_mbcnt_lo_u32_b32 v251, -1, 0
	v_mbcnt_hi_u32_b32 v251, -1, v251
	v_and_b32_e32 v251, 1, v251
	v_sub_u32_e32 v250, 0, v251
	v_and_b32_e32 v248, 0x06060606, v250
	v_xor_b32_e32 v248, 0x05040100, v248
	v_and_b32_e32 v251, 0x107e, v250
	v_add_u32_e32 v249, v36, v251
	v_cvt_pk_bf16_f32 v232, v16, v20
	v_cvt_pk_bf16_f32 v233, v17, v21
	v_cvt_pk_bf16_f32 v234, v18, v22
	v_cvt_pk_bf16_f32 v235, v19, v23
	v_cvt_pk_bf16_f32 v236, v24, v28
	v_cvt_pk_bf16_f32 v237, v25, v29
	v_cvt_pk_bf16_f32 v238, v26, v30
	v_cvt_pk_bf16_f32 v239, v27, v31
	v_mov_b32_dpp v240, v232 quad_perm:[1,0,3,2] row_mask:0xf bank_mask:0xf
	v_mov_b32_dpp v241, v233 quad_perm:[1,0,3,2] row_mask:0xf bank_mask:0xf
	v_mov_b32_dpp v242, v234 quad_perm:[1,0,3,2] row_mask:0xf bank_mask:0xf
	v_mov_b32_dpp v243, v235 quad_perm:[1,0,3,2] row_mask:0xf bank_mask:0xf
	v_mov_b32_dpp v244, v236 quad_perm:[1,0,3,2] row_mask:0xf bank_mask:0xf
	v_mov_b32_dpp v245, v237 quad_perm:[1,0,3,2] row_mask:0xf bank_mask:0xf
	v_mov_b32_dpp v246, v238 quad_perm:[1,0,3,2] row_mask:0xf bank_mask:0xf
	v_mov_b32_dpp v247, v239 quad_perm:[1,0,3,2] row_mask:0xf bank_mask:0xf
	v_perm_b32 v240, v240, v232, v248
	v_perm_b32 v241, v241, v233, v248
	v_perm_b32 v242, v242, v234, v248
	v_perm_b32 v243, v243, v235, v248
	v_perm_b32 v244, v244, v236, v248
	v_perm_b32 v245, v245, v237, v248
	v_perm_b32 v246, v246, v238, v248
	v_perm_b32 v247, v247, v239, v248
	ds_write_b32 v249, v240 offset:0
	ds_write_b32 v249, v241 offset:528
	ds_write_b32 v249, v242 offset:1056
	ds_write_b32 v249, v243 offset:1584
	ds_write_b32 v249, v244 offset:8448
	ds_write_b32 v249, v245 offset:8976
	ds_write_b32 v249, v246 offset:9504
	ds_write_b32 v249, v247 offset:10032
	v_cvt_pk_bf16_f32 v232, v0, v4
	v_cvt_pk_bf16_f32 v233, v1, v5
	v_cvt_pk_bf16_f32 v234, v2, v6
	v_cvt_pk_bf16_f32 v235, v3, v7
	v_cvt_pk_bf16_f32 v236, v8, v12
	v_cvt_pk_bf16_f32 v237, v9, v13
	v_cvt_pk_bf16_f32 v238, v10, v14
	v_cvt_pk_bf16_f32 v239, v11, v15
	v_mov_b32_dpp v240, v232 quad_perm:[1,0,3,2] row_mask:0xf bank_mask:0xf
	v_mov_b32_dpp v241, v233 quad_perm:[1,0,3,2] row_mask:0xf bank_mask:0xf
	v_mov_b32_dpp v242, v234 quad_perm:[1,0,3,2] row_mask:0xf bank_mask:0xf
	v_mov_b32_dpp v243, v235 quad_perm:[1,0,3,2] row_mask:0xf bank_mask:0xf
	v_mov_b32_dpp v244, v236 quad_perm:[1,0,3,2] row_mask:0xf bank_mask:0xf
	v_mov_b32_dpp v245, v237 quad_perm:[1,0,3,2] row_mask:0xf bank_mask:0xf
	v_mov_b32_dpp v246, v238 quad_perm:[1,0,3,2] row_mask:0xf bank_mask:0xf
	v_mov_b32_dpp v247, v239 quad_perm:[1,0,3,2] row_mask:0xf bank_mask:0xf
	v_perm_b32 v240, v240, v232, v248
	v_perm_b32 v241, v241, v233, v248
	v_perm_b32 v242, v242, v234, v248
	v_perm_b32 v243, v243, v235, v248
	v_perm_b32 v244, v244, v236, v248
	v_perm_b32 v245, v245, v237, v248
	v_perm_b32 v246, v246, v238, v248
	v_perm_b32 v247, v247, v239, v248
	ds_write_b32 v249, v240 offset:16896
	ds_write_b32 v249, v241 offset:17424
	ds_write_b32 v249, v242 offset:17952
	ds_write_b32 v249, v243 offset:18480
	ds_write_b32 v249, v244 offset:25344
	ds_write_b32 v249, v245 offset:25872
	ds_write_b32 v249, v246 offset:26400
	ds_write_b32 v249, v247 offset:26928
	s_waitcnt lgkmcnt(0)
	s_barrier
	s_mov_b32 s8, s2
	s_cbranch_scc0 .LBB0_108
	s_setprio 0
	s_branch .LBB0_68
